# GEMM K-loops: back-edge branch taken before the loop-closing barrier (barrier copy in front of the loop head), exit path keeps its barrier
# speedup vs baseline: 1.0092x; 1.0013x over previous
; template <class Epi>
; __device__ __forceinline__ void gemm_phase(const int TID, const int BID, LAS unsigned char* lds, const Gemm g, const StaticOrder& S, const Epi& E) {
;     ...
;     for (;;) {
;         const bool has_next = S.next(ui + 1, nxt);
;         const char* nA = has_next ? (const char*)g.A + (size_t)nxt.pm * tstepA : cA; const char* nB = has_next ? (const char*)g.Bt + (size_t)nxt.pn * tstepB : cB;
;     ...
; #pragma unroll
;         for (int a = 0; a < 2; ++a)
; #pragma unroll
;             for (int b = 0; b < 2; ++b)
; #pragma unroll
;                 for (int m = 0; m < 4; ++m)
; #pragma unroll
;                     for (int n = 0; n < 2; ++n) acc[a][b][m][n] = (f32x4){0.f, 0.f, 0.f, 0.f};
;         cur = nxt; cA = nA; cB = nB; ++ui;
.LBB0_798:
	s_ashr_i32 s17, s16, 31
	v_cmp_lt_i64_e32 vcc, s[18:19], v[164:165]
	s_lshl_b64 s[18:19], s[16:17], 20
	s_add_u32 s18, s84, s18
	s_addc_u32 s19, s85, s19
	s_and_b64 s[20:21], vcc, exec
	s_cselect_b32 s17, s19, s25
	s_cselect_b32 s52, s18, s24
	s_ashr_i32 s15, s14, 31
	s_lshl_b64 s[20:21], s[14:15], 20
	s_add_u32 s20, s4, s20
	s_addc_u32 s21, s30, s21
	s_and_b64 s[28:29], vcc, exec
	s_cselect_b32 s15, s21, s27
	s_cselect_b32 s53, s20, s26
	s_add_u32 s24, s24, 0x80080
	s_addc_u32 s25, s25, 0
	s_add_u32 s54, s26, 0x100
	v_mov_b32_e32 v0, 0
	s_addc_u32 s55, s27, 0
	s_mov_b32 s56, -2
	v_mov_b32_e32 v1, v0
	v_mov_b32_e32 v2, v0
	v_mov_b32_e32 v3, v0
	v_mov_b32_e32 v4, v0
	v_mov_b32_e32 v5, v0
	v_mov_b32_e32 v6, v0
	v_mov_b32_e32 v7, v0
	v_mov_b32_e32 v16, v0
	v_mov_b32_e32 v17, v0
	v_mov_b32_e32 v18, v0
	v_mov_b32_e32 v19, v0
	v_mov_b32_e32 v20, v0
	v_mov_b32_e32 v21, v0
	v_mov_b32_e32 v22, v0
	v_mov_b32_e32 v23, v0
	s_waitcnt vmcnt(0)
	v_mov_b32_e32 v32, v0
	v_mov_b32_e32 v33, v0
	v_mov_b32_e32 v34, v0
	v_mov_b32_e32 v35, v0
	v_mov_b32_e32 v36, v0
	v_mov_b32_e32 v37, v0
	v_mov_b32_e32 v38, v0
	v_mov_b32_e32 v39, v0
	v_mov_b32_e32 v48, v0
	v_mov_b32_e32 v49, v0
	v_mov_b32_e32 v50, v0
	v_mov_b32_e32 v51, v0
	v_mov_b32_e32 v52, v0
	v_mov_b32_e32 v53, v0
	v_mov_b32_e32 v54, v0
	v_mov_b32_e32 v55, v0
	v_mov_b32_e32 v8, v0
	v_mov_b32_e32 v9, v0
	v_mov_b32_e32 v10, v0
	v_mov_b32_e32 v11, v0
	v_mov_b32_e32 v12, v0
	v_mov_b32_e32 v13, v0
	v_mov_b32_e32 v14, v0
	v_mov_b32_e32 v15, v0
	v_mov_b32_e32 v24, v0
	v_mov_b32_e32 v25, v0
	v_mov_b32_e32 v26, v0
	v_mov_b32_e32 v27, v0
	v_mov_b32_e32 v28, v0
	v_mov_b32_e32 v29, v0
	v_mov_b32_e32 v30, v0
	v_mov_b32_e32 v31, v0
	v_mov_b32_e32 v40, v0
	v_mov_b32_e32 v41, v0
	v_mov_b32_e32 v42, v0
	v_mov_b32_e32 v43, v0
	v_mov_b32_e32 v44, v0
	v_mov_b32_e32 v45, v0
	v_mov_b32_e32 v46, v0
	v_mov_b32_e32 v47, v0
	v_mov_b32_e32 v56, v0
	v_mov_b32_e32 v57, v0
	v_mov_b32_e32 v58, v0
	v_mov_b32_e32 v59, v0
	v_mov_b32_e32 v60, v0
	v_mov_b32_e32 v61, v0
	v_mov_b32_e32 v62, v0
	v_mov_b32_e32 v63, v0
	v_mov_b32_e32 v64, v0
	v_mov_b32_e32 v65, v0
	v_mov_b32_e32 v66, v0
	v_mov_b32_e32 v67, v0
	v_mov_b32_e32 v68, v0
	v_mov_b32_e32 v69, v0
	v_mov_b32_e32 v70, v0
	v_mov_b32_e32 v71, v0
	v_mov_b32_e32 v80, v0
	v_mov_b32_e32 v81, v0
	v_mov_b32_e32 v82, v0
	v_mov_b32_e32 v83, v0
	v_mov_b32_e32 v84, v0
	v_mov_b32_e32 v85, v0
	v_mov_b32_e32 v86, v0
	v_mov_b32_e32 v87, v0
	v_mov_b32_e32 v96, v0
	v_mov_b32_e32 v97, v0
	v_mov_b32_e32 v98, v0
	v_mov_b32_e32 v99, v0
	v_mov_b32_e32 v100, v0
	v_mov_b32_e32 v101, v0
	v_mov_b32_e32 v102, v0
	v_mov_b32_e32 v103, v0
	v_mov_b32_e32 v112, v0
	v_mov_b32_e32 v113, v0
	v_mov_b32_e32 v114, v0
	v_mov_b32_e32 v115, v0
	v_mov_b32_e32 v116, v0
	v_mov_b32_e32 v117, v0
	v_mov_b32_e32 v118, v0
	v_mov_b32_e32 v119, v0
	v_mov_b32_e32 v72, v0
	v_mov_b32_e32 v73, v0
	v_mov_b32_e32 v74, v0
	v_mov_b32_e32 v75, v0
	v_mov_b32_e32 v76, v0
	v_mov_b32_e32 v77, v0
	v_mov_b32_e32 v78, v0
	v_mov_b32_e32 v79, v0
	v_mov_b32_e32 v88, v0
	v_mov_b32_e32 v89, v0
	v_mov_b32_e32 v90, v0
	v_mov_b32_e32 v91, v0
	v_mov_b32_e32 v92, v0
	v_mov_b32_e32 v93, v0
	v_mov_b32_e32 v94, v0
	v_mov_b32_e32 v95, v0
	v_mov_b32_e32 v104, v0
	v_mov_b32_e32 v105, v0
	v_mov_b32_e32 v106, v0
	v_mov_b32_e32 v107, v0
	v_mov_b32_e32 v108, v0
	v_mov_b32_e32 v109, v0
	v_mov_b32_e32 v110, v0
	v_mov_b32_e32 v111, v0
	v_mov_b32_e32 v120, v0
	v_mov_b32_e32 v121, v0
	v_mov_b32_e32 v122, v0
	v_mov_b32_e32 v123, v0
	v_mov_b32_e32 v124, v0
	v_mov_b32_e32 v125, v0
	v_mov_b32_e32 v126, v0
	v_mov_b32_e32 v127, v0
	s_branch .LBB0_799

; #define PG8_STAGE(bufoff, gbase, voff) do { _Pragma("unroll") for (int _i = 0; _i < 2; ++_i) \
;         __builtin_amdgcn_global_load_lds((const unsigned*)((const char*)(gbase) + (voff)[_i]), (LAS unsigned*)(lds + (bufoff) + ldsw + _i * 8192), 16, 0, 0); } while (0)
; #define PG8_LDA(dst, b, h) do { _Pragma("unroll") for (int m = 0; m < 4; ++m) _Pragma("unroll") for (int k = 0; k < 2; ++k) dst[m][k] = *(const LAS bf16x8*)(lds + PG8_SA(b, h) + aoff + m * 2048 + k * 1024); } while (0)
; #define PG8_LDB(dst, b, h) do { _Pragma("unroll") for (int n = 0; n < 2; ++n) _Pragma("unroll") for (int k = 0; k < 2; ++k) dst[n][k] = *(const LAS bf16x8*)(lds + PG8_SB(b, h) + boff + n * 2048 + k * 1024); } while (0)
; #define PG8_MMA(ai, bj, At, Bt) do { __builtin_amdgcn_s_setprio(1); _Pragma("unroll") for (int m = 0; m < 4; ++m) _Pragma("unroll") for (int n = 0; n < 2; ++n) _Pragma("unroll") for (int k = 0; k < 2; ++k) \
;         acc[ai][bj][m][n] = __builtin_amdgcn_mfma_f32_16x16x32_bf16(Bt[n][k], At[m][k], acc[ai][bj][m][n], 0, 0, 0); __builtin_amdgcn_s_setprio(0); } while (0)
; #define PG8_WAIT_V(n) asm volatile("s_waitcnt vmcnt(" #n ")" ::: "memory")
; #define PG8_WAIT_L(n) asm volatile("s_waitcnt lgkmcnt(" #n ")" ::: "memory")
; #define PG8_BAR __builtin_amdgcn_s_barrier()
; #define PG8_SCHED __builtin_amdgcn_sched_barrier(0)
; template <class Epi>
; __device__ __forceinline__ void gemm_phase(const int TID, const int BID, LAS unsigned char* lds, const Gemm g, const StaticOrder& S, const Epi& E) {
;     ...
;             PG8_LDB(B0, 0, 0); PG8_SCHED; PG8_LDA(At, 0, 0); PG8_STAGE(PG8_SA(1, 1), a1 + hstepA, voffA);
;             PG8_WAIT_L(8); PG8_BAR; PG8_WAIT_L(0); PG8_MMA(0, 0, At, B0); PG8_BAR; PG8_SCHED;
;             PG8_LDB(B1, 0, 1); PG8_STAGE(PG8_SB(0, 0), b2, voffB);
;             PG8_BAR; PG8_WAIT_L(0); PG8_MMA(0, 1, At, B1); PG8_BAR;
;             PG8_LDA(At, 0, 1); PG8_STAGE(PG8_SA(0, 0), a2, voffA);
;             PG8_BAR; PG8_WAIT_L(0); PG8_MMA(1, 0, At, B0); PG8_BAR; PG8_SCHED;
;             PG8_STAGE(PG8_SB(0, 1), b2 + hstepB, voffB);
;             PG8_WAIT_V(6); PG8_BAR; PG8_MMA(1, 1, At, B1); PG8_BAR;
.LBB0_799:
	v_add_u32_e32 v173, s23, v170
	ds_read_b128 v[138:141], v173
	ds_read_b128 v[142:145], v173 offset:1024
	ds_read_b128 v[174:177], v173 offset:2048
	ds_read_b128 v[178:181], v173 offset:3072
	s_add_u32 s26, s24, 0xfff80080
	s_addc_u32 s27, s25, -1
	s_cmp_eq_u32 s56, 28
	s_cselect_b32 s29, s17, s27
	s_cselect_b32 s28, s52, s26
	s_cselect_b32 s27, s15, s55
	s_cselect_b32 s26, s53, s54
	v_lshl_add_u64 v[200:201], s[24:25], 0, v[134:135]
	s_add_i32 m0, s35, 0xc000
	ds_read_b128 v[182:185], v172
	ds_read_b128 v[196:199], v172 offset:1024
	ds_read_b128 v[208:211], v172 offset:2048
	ds_read_b128 v[212:215], v172 offset:3072
	ds_read_b128 v[216:219], v172 offset:4096
	ds_read_b128 v[220:223], v172 offset:5120
	ds_read_b128 v[224:227], v172 offset:6144
	ds_read_b128 v[228:231], v172 offset:7168
	global_load_lds_dwordx4 v[200:201], off
	s_add_i32 m0, s35, 0xe000
	v_lshl_add_u64 v[200:201], s[24:25], 0, v[136:137]
	global_load_lds_dwordx4 v[200:201], off
	s_waitcnt lgkmcnt(8)
	s_barrier
	s_waitcnt lgkmcnt(0)
	s_setprio 1
	v_mfma_f32_16x16x32_bf16 v[124:127], v[138:141], v[182:185], v[124:127]
	v_mfma_f32_16x16x32_bf16 v[120:123], v[174:177], v[182:185], v[120:123]
	v_mfma_f32_16x16x32_bf16 v[108:111], v[138:141], v[208:211], v[108:111]
	v_mfma_f32_16x16x32_bf16 v[104:107], v[174:177], v[208:211], v[104:107]
	v_mfma_f32_16x16x32_bf16 v[92:95], v[138:141], v[216:219], v[92:95]
	v_mfma_f32_16x16x32_bf16 v[88:91], v[174:177], v[216:219], v[88:91]
	v_mfma_f32_16x16x32_bf16 v[76:79], v[138:141], v[224:227], v[76:79]
	v_mfma_f32_16x16x32_bf16 v[72:75], v[174:177], v[224:227], v[72:75]
	v_mfma_f32_16x16x32_bf16 v[124:127], v[142:145], v[196:199], v[124:127]
	v_mfma_f32_16x16x32_bf16 v[120:123], v[178:181], v[196:199], v[120:123]
	v_mfma_f32_16x16x32_bf16 v[108:111], v[142:145], v[212:215], v[108:111]
	v_mfma_f32_16x16x32_bf16 v[104:107], v[178:181], v[212:215], v[104:107]
	v_mfma_f32_16x16x32_bf16 v[92:95], v[142:145], v[220:223], v[92:95]
	v_mfma_f32_16x16x32_bf16 v[88:91], v[178:181], v[220:223], v[88:91]
	v_mfma_f32_16x16x32_bf16 v[76:79], v[142:145], v[228:231], v[76:79]
	v_mfma_f32_16x16x32_bf16 v[72:75], v[178:181], v[228:231], v[72:75]
	s_setprio 0
	s_barrier
	s_mov_b32 m0, s31
	v_add_u32_e32 v173, s37, v170
	v_lshl_add_u64 v[200:201], s[26:27], 0, v[160:161]
	ds_read_b128 v[232:235], v173
	ds_read_b128 v[236:239], v173 offset:1024
	ds_read_b128 v[240:243], v173 offset:2048
	ds_read_b128 v[244:247], v173 offset:3072
	global_load_lds_dwordx4 v[200:201], off
	s_mov_b32 m0, s34
	v_lshl_add_u64 v[248:249], s[26:27], 0, v[132:133]
	global_load_lds_dwordx4 v[248:249], off
	s_barrier
	s_waitcnt lgkmcnt(0)
	s_setprio 1
	v_mfma_f32_16x16x32_bf16 v[116:119], v[232:235], v[182:185], v[116:119]
	v_mfma_f32_16x16x32_bf16 v[112:115], v[240:243], v[182:185], v[112:115]
	v_mfma_f32_16x16x32_bf16 v[100:103], v[232:235], v[208:211], v[100:103]
	v_mfma_f32_16x16x32_bf16 v[96:99], v[240:243], v[208:211], v[96:99]
	v_mfma_f32_16x16x32_bf16 v[84:87], v[232:235], v[216:219], v[84:87]
	v_mfma_f32_16x16x32_bf16 v[80:83], v[240:243], v[216:219], v[80:83]
	v_mfma_f32_16x16x32_bf16 v[68:71], v[232:235], v[224:227], v[68:71]
	v_mfma_f32_16x16x32_bf16 v[64:67], v[240:243], v[224:227], v[64:67]
	v_mfma_f32_16x16x32_bf16 v[116:119], v[236:239], v[196:199], v[116:119]
	v_mfma_f32_16x16x32_bf16 v[112:115], v[244:247], v[196:199], v[112:115]
	v_mfma_f32_16x16x32_bf16 v[100:103], v[236:239], v[212:215], v[100:103]
	v_mfma_f32_16x16x32_bf16 v[96:99], v[244:247], v[212:215], v[96:99]
	v_mfma_f32_16x16x32_bf16 v[84:87], v[236:239], v[220:223], v[84:87]
	v_mfma_f32_16x16x32_bf16 v[80:83], v[244:247], v[220:223], v[80:83]
	v_mfma_f32_16x16x32_bf16 v[68:71], v[236:239], v[228:231], v[68:71]
	v_mfma_f32_16x16x32_bf16 v[64:67], v[244:247], v[228:231], v[64:67]
	s_setprio 0
	s_mov_b32 m0, s35
	v_lshl_add_u64 v[250:251], s[28:29], 0, v[128:129]
	s_barrier
	ds_read_b128 v[182:185], v172 offset:16384
	ds_read_b128 v[196:199], v172 offset:17408
	ds_read_b128 v[208:211], v172 offset:18432
	ds_read_b128 v[212:215], v172 offset:19456
	ds_read_b128 v[216:219], v172 offset:20480
	ds_read_b128 v[220:223], v172 offset:21504
	ds_read_b128 v[224:227], v172 offset:22528
	ds_read_b128 v[228:231], v172 offset:23552
	global_load_lds_dwordx4 v[250:251], off
	s_mov_b32 m0, s36
	v_lshl_add_u64 v[252:253], s[28:29], 0, v[130:131]
	global_load_lds_dwordx4 v[252:253], off
	s_barrier
	s_waitcnt lgkmcnt(0)
	s_setprio 1
	v_mfma_f32_16x16x32_bf16 v[60:63], v[138:141], v[182:185], v[60:63]
	v_mfma_f32_16x16x32_bf16 v[56:59], v[174:177], v[182:185], v[56:59]
	v_mfma_f32_16x16x32_bf16 v[44:47], v[138:141], v[208:211], v[44:47]
	v_mfma_f32_16x16x32_bf16 v[40:43], v[174:177], v[208:211], v[40:43]
	v_mfma_f32_16x16x32_bf16 v[28:31], v[138:141], v[216:219], v[28:31]
	v_mfma_f32_16x16x32_bf16 v[24:27], v[174:177], v[216:219], v[24:27]
	v_mfma_f32_16x16x32_bf16 v[12:15], v[138:141], v[224:227], v[12:15]
	v_mfma_f32_16x16x32_bf16 v[8:11], v[174:177], v[224:227], v[8:11]
	v_mfma_f32_16x16x32_bf16 v[60:63], v[142:145], v[196:199], v[60:63]
	v_mfma_f32_16x16x32_bf16 v[56:59], v[178:181], v[196:199], v[56:59]
	v_mfma_f32_16x16x32_bf16 v[44:47], v[142:145], v[212:215], v[44:47]
	v_mfma_f32_16x16x32_bf16 v[40:43], v[178:181], v[212:215], v[40:43]
	v_mfma_f32_16x16x32_bf16 v[28:31], v[142:145], v[220:223], v[28:31]
	v_mfma_f32_16x16x32_bf16 v[24:27], v[178:181], v[220:223], v[24:27]
	v_mfma_f32_16x16x32_bf16 v[12:15], v[142:145], v[228:231], v[12:15]
	v_mfma_f32_16x16x32_bf16 v[8:11], v[178:181], v[228:231], v[8:11]
	s_setprio 0
	s_barrier
; #define PG8_STAGE(bufoff, gbase, voff) do { _Pragma("unroll") for (int _i = 0; _i < 2; ++_i) \
;         __builtin_amdgcn_global_load_lds((const unsigned*)((const char*)(gbase) + (voff)[_i]), (LAS unsigned*)(lds + (bufoff) + ldsw + _i * 8192), 16, 0, 0); } while (0)
; #define PG8_LDA(dst, b, h) do { _Pragma("unroll") for (int m = 0; m < 4; ++m) _Pragma("unroll") for (int k = 0; k < 2; ++k) dst[m][k] = *(const LAS bf16x8*)(lds + PG8_SA(b, h) + aoff + m * 2048 + k * 1024); } while (0)
; #define PG8_LDB(dst, b, h) do { _Pragma("unroll") for (int n = 0; n < 2; ++n) _Pragma("unroll") for (int k = 0; k < 2; ++k) dst[n][k] = *(const LAS bf16x8*)(lds + PG8_SB(b, h) + boff + n * 2048 + k * 1024); } while (0)
; #define PG8_MMA(ai, bj, At, Bt) do { __builtin_amdgcn_s_setprio(1); _Pragma("unroll") for (int m = 0; m < 4; ++m) _Pragma("unroll") for (int n = 0; n < 2; ++n) _Pragma("unroll") for (int k = 0; k < 2; ++k) \
;         acc[ai][bj][m][n] = __builtin_amdgcn_mfma_f32_16x16x32_bf16(Bt[n][k], At[m][k], acc[ai][bj][m][n], 0, 0, 0); __builtin_amdgcn_s_setprio(0); } while (0)
; #define PG8_WAIT_V(n) asm volatile("s_waitcnt vmcnt(" #n ")" ::: "memory")
; #define PG8_WAIT_L(n) asm volatile("s_waitcnt lgkmcnt(" #n ")" ::: "memory")
; #define PG8_BAR __builtin_amdgcn_s_barrier()
; #define PG8_SCHED __builtin_amdgcn_sched_barrier(0)
; template <class Epi>
; __device__ __forceinline__ void gemm_phase(const int TID, const int BID, LAS unsigned char* lds, const Gemm g, const StaticOrder& S, const Epi& E) {
;     ...
;             PG8_WAIT_V(6); PG8_BAR; PG8_MMA(1, 1, At, B1); PG8_BAR;
;             PG8_LDB(B0, 1, 0); PG8_SCHED; PG8_LDA(At, 1, 0); PG8_STAGE(PG8_SA(0, 1), a2 + hstepA, voffA);
;             PG8_WAIT_L(8); PG8_BAR; PG8_WAIT_L(0); PG8_MMA(0, 0, At, B0); PG8_BAR; PG8_SCHED;
;             PG8_LDB(B1, 1, 1); PG8_STAGE(PG8_SB(1, 0), b3, voffB);
;             PG8_BAR; PG8_WAIT_L(0); PG8_MMA(0, 1, At, B1); PG8_BAR;
;             PG8_LDA(At, 1, 1); PG8_STAGE(PG8_SA(1, 0), a3, voffA);
;             PG8_BAR; PG8_WAIT_L(0); PG8_MMA(1, 0, At, B0); PG8_BAR; PG8_SCHED;
	s_add_u32 s58, s26, 0x80000
	s_addc_u32 s59, s27, 0
	s_mov_b32 m0, s38
	v_lshl_add_u64 v[138:139], s[58:59], 0, v[160:161]
	global_load_lds_dwordx4 v[138:139], off
	s_mov_b32 m0, s39
	v_lshl_add_u64 v[138:139], s[58:59], 0, v[132:133]
	global_load_lds_dwordx4 v[138:139], off
	s_waitcnt vmcnt(6)
	s_barrier
	s_setprio 1
	v_mfma_f32_16x16x32_bf16 v[52:55], v[232:235], v[182:185], v[52:55]
	v_mfma_f32_16x16x32_bf16 v[48:51], v[240:243], v[182:185], v[48:51]
	v_mfma_f32_16x16x32_bf16 v[36:39], v[232:235], v[208:211], v[36:39]
	v_mfma_f32_16x16x32_bf16 v[32:35], v[240:243], v[208:211], v[32:35]
	v_mfma_f32_16x16x32_bf16 v[20:23], v[232:235], v[216:219], v[20:23]
	v_mfma_f32_16x16x32_bf16 v[16:19], v[240:243], v[216:219], v[16:19]
	v_mfma_f32_16x16x32_bf16 v[4:7], v[232:235], v[224:227], v[4:7]
	v_mfma_f32_16x16x32_bf16 v[0:3], v[240:243], v[224:227], v[0:3]
	v_mfma_f32_16x16x32_bf16 v[52:55], v[236:239], v[196:199], v[52:55]
	v_mfma_f32_16x16x32_bf16 v[48:51], v[244:247], v[196:199], v[48:51]
	v_mfma_f32_16x16x32_bf16 v[36:39], v[236:239], v[212:215], v[36:39]
	v_mfma_f32_16x16x32_bf16 v[32:35], v[244:247], v[212:215], v[32:35]
	v_mfma_f32_16x16x32_bf16 v[20:23], v[236:239], v[220:223], v[20:23]
	v_mfma_f32_16x16x32_bf16 v[16:19], v[244:247], v[220:223], v[16:19]
	v_mfma_f32_16x16x32_bf16 v[4:7], v[236:239], v[228:231], v[4:7]
	v_mfma_f32_16x16x32_bf16 v[0:3], v[244:247], v[228:231], v[0:3]
	s_setprio 0
	v_add_u32_e32 v173, s42, v170
	s_barrier
	ds_read_b128 v[138:141], v173
	ds_read_b128 v[142:145], v173 offset:1024
	ds_read_b128 v[174:177], v173 offset:2048
	ds_read_b128 v[178:181], v173 offset:3072
	s_add_u32 s28, s28, 0x80000
	s_addc_u32 s29, s29, 0
	s_mov_b32 m0, s40
	v_lshl_add_u64 v[232:233], s[28:29], 0, v[128:129]
	ds_read_b128 v[182:185], v172 offset:32768
	ds_read_b128 v[196:199], v172 offset:33792
	ds_read_b128 v[208:211], v172 offset:34816
	ds_read_b128 v[212:215], v172 offset:35840
	ds_read_b128 v[216:219], v172 offset:36864
	ds_read_b128 v[220:223], v172 offset:37888
	ds_read_b128 v[224:227], v172 offset:38912
	ds_read_b128 v[228:231], v172 offset:39936
	global_load_lds_dwordx4 v[232:233], off
	s_mov_b32 m0, s41
	v_lshl_add_u64 v[232:233], s[28:29], 0, v[130:131]
	global_load_lds_dwordx4 v[232:233], off
	s_waitcnt lgkmcnt(8)
	s_barrier
	s_waitcnt lgkmcnt(0)
	s_setprio 1
	v_mfma_f32_16x16x32_bf16 v[124:127], v[138:141], v[182:185], v[124:127]
	v_mfma_f32_16x16x32_bf16 v[120:123], v[174:177], v[182:185], v[120:123]
	v_mfma_f32_16x16x32_bf16 v[108:111], v[138:141], v[208:211], v[108:111]
	v_mfma_f32_16x16x32_bf16 v[104:107], v[174:177], v[208:211], v[104:107]
	v_mfma_f32_16x16x32_bf16 v[92:95], v[138:141], v[216:219], v[92:95]
	v_mfma_f32_16x16x32_bf16 v[88:91], v[174:177], v[216:219], v[88:91]
	v_mfma_f32_16x16x32_bf16 v[76:79], v[138:141], v[224:227], v[76:79]
	v_mfma_f32_16x16x32_bf16 v[72:75], v[174:177], v[224:227], v[72:75]
	v_mfma_f32_16x16x32_bf16 v[124:127], v[142:145], v[196:199], v[124:127]
	v_mfma_f32_16x16x32_bf16 v[120:123], v[178:181], v[196:199], v[120:123]
	v_mfma_f32_16x16x32_bf16 v[108:111], v[142:145], v[212:215], v[108:111]
	v_mfma_f32_16x16x32_bf16 v[104:107], v[178:181], v[212:215], v[104:107]
	v_mfma_f32_16x16x32_bf16 v[92:95], v[142:145], v[220:223], v[92:95]
	v_mfma_f32_16x16x32_bf16 v[88:91], v[178:181], v[220:223], v[88:91]
	v_mfma_f32_16x16x32_bf16 v[76:79], v[142:145], v[228:231], v[76:79]
	v_mfma_f32_16x16x32_bf16 v[72:75], v[178:181], v[228:231], v[72:75]
	s_setprio 0
	s_barrier
	s_mov_b32 m0, s43
	v_add_u32_e32 v173, s47, v170
	v_lshl_add_u64 v[200:201], v[200:201], 0, s[90:91]
	ds_read_b128 v[232:235], v173
	ds_read_b128 v[236:239], v173 offset:1024
	ds_read_b128 v[240:243], v173 offset:2048
	ds_read_b128 v[244:247], v173 offset:3072
	global_load_lds_dwordx4 v[200:201], off
	s_mov_b32 m0, s44
	v_lshl_add_u64 v[200:201], v[248:249], 0, s[90:91]
	global_load_lds_dwordx4 v[200:201], off
	s_barrier
	s_waitcnt lgkmcnt(0)
	s_setprio 1
	v_mfma_f32_16x16x32_bf16 v[116:119], v[232:235], v[182:185], v[116:119]
	v_mfma_f32_16x16x32_bf16 v[112:115], v[240:243], v[182:185], v[112:115]
	v_mfma_f32_16x16x32_bf16 v[100:103], v[232:235], v[208:211], v[100:103]
	v_mfma_f32_16x16x32_bf16 v[96:99], v[240:243], v[208:211], v[96:99]
	v_mfma_f32_16x16x32_bf16 v[84:87], v[232:235], v[216:219], v[84:87]
	v_mfma_f32_16x16x32_bf16 v[80:83], v[240:243], v[216:219], v[80:83]
	v_mfma_f32_16x16x32_bf16 v[68:71], v[232:235], v[224:227], v[68:71]
	v_mfma_f32_16x16x32_bf16 v[64:67], v[240:243], v[224:227], v[64:67]
	v_mfma_f32_16x16x32_bf16 v[116:119], v[236:239], v[196:199], v[116:119]
	v_mfma_f32_16x16x32_bf16 v[112:115], v[244:247], v[196:199], v[112:115]
	v_mfma_f32_16x16x32_bf16 v[100:103], v[236:239], v[212:215], v[100:103]
	v_mfma_f32_16x16x32_bf16 v[96:99], v[244:247], v[212:215], v[96:99]
	v_mfma_f32_16x16x32_bf16 v[84:87], v[236:239], v[220:223], v[84:87]
	v_mfma_f32_16x16x32_bf16 v[80:83], v[244:247], v[220:223], v[80:83]
	v_mfma_f32_16x16x32_bf16 v[68:71], v[236:239], v[228:231], v[68:71]
	v_mfma_f32_16x16x32_bf16 v[64:67], v[244:247], v[228:231], v[64:67]
	s_setprio 0
	s_mov_b32 m0, s45
	v_lshl_add_u64 v[200:201], v[250:251], 0, s[90:91]
	s_barrier
	ds_read_b128 v[182:185], v172 offset:49152
	ds_read_b128 v[196:199], v172 offset:50176
	ds_read_b128 v[208:211], v172 offset:51200
	ds_read_b128 v[212:215], v172 offset:52224
	ds_read_b128 v[216:219], v172 offset:53248
	ds_read_b128 v[220:223], v172 offset:54272
	ds_read_b128 v[224:227], v172 offset:55296
	ds_read_b128 v[228:231], v172 offset:56320
	global_load_lds_dwordx4 v[200:201], off
	s_mov_b32 m0, s46
	v_lshl_add_u64 v[200:201], v[252:253], 0, s[90:91]
	global_load_lds_dwordx4 v[200:201], off
	s_barrier
; __device__ __forceinline__ unsigned cvt_pk_bf16(float lo, float hi) { unsigned r; asm volatile("v_cvt_pk_bf16_f32 %0, %1, %2" : "=v"(r) : "v"(lo), "v"(hi)); return r; }
; __device__ __forceinline__ float rinv_st(stat_t s, float invn) { return rsqrtf((float)((double)s * (1.0 / 4294967296.0)) * invn + 1e-6f); }
; #define PG8_STAGE(bufoff, gbase, voff) do { _Pragma("unroll") for (int _i = 0; _i < 2; ++_i) \
;         __builtin_amdgcn_global_load_lds((const unsigned*)((const char*)(gbase) + (voff)[_i]), (LAS unsigned*)(lds + (bufoff) + ldsw + _i * 8192), 16, 0, 0); } while (0)
; #define PG8_MMA(ai, bj, At, Bt) do { __builtin_amdgcn_s_setprio(1); _Pragma("unroll") for (int m = 0; m < 4; ++m) _Pragma("unroll") for (int n = 0; n < 2; ++n) _Pragma("unroll") for (int k = 0; k < 2; ++k) \
;         acc[ai][bj][m][n] = __builtin_amdgcn_mfma_f32_16x16x32_bf16(Bt[n][k], At[m][k], acc[ai][bj][m][n], 0, 0, 0); __builtin_amdgcn_s_setprio(0); } while (0)
; #define PG8_WAIT_V(n) asm volatile("s_waitcnt vmcnt(" #n ")" ::: "memory")
; #define PG8_WAIT_L(n) asm volatile("s_waitcnt lgkmcnt(" #n ")" ::: "memory")
; #define PG8_BAR __builtin_amdgcn_s_barrier()
; #define PG8_SCHED __builtin_amdgcn_sched_barrier(0)
; template <class Epi>
; __device__ __forceinline__ void gemm_phase(const int TID, const int BID, LAS unsigned char* lds, const Gemm g, const StaticOrder& S, const Epi& E) {
;     ...
;             PG8_BAR; PG8_WAIT_L(0); PG8_MMA(1, 0, At, B0); PG8_BAR; PG8_SCHED;
;             PG8_STAGE(PG8_SB(1, 1), b3 + hstepB, voffB);
;             PG8_WAIT_V(6); PG8_BAR; PG8_MMA(1, 1, At, B1); PG8_BAR;
;         }
;     __device__ __forceinline__ void operator()(const f32x4 (&acc)[2][2][4][2], const Unit& u, int wr, int wc, int fr, int fq) const {
;     ...
;             for (int m = 0; m < 4; ++m) {
;                 const int row = row0 + ai * HALF + m * 16; const float r = rinv_st(stats[row], 1.0f / 2048.0f);
;                 bf16_t* rowp = raw + (size_t)row * NINP + col0;
; #pragma unroll
;                 for (int bj = 0; bj < 2; ++bj) {
;                     const f32x4 v0 = acc[ai][bj][m][0] * r, v1 = acc[ai][bj][m][1] * r;
;                     u32x4 w; w.x = cvt_pk_bf16(v0[0], v0[1]); w.y = cvt_pk_bf16(v0[2], v0[3]); w.z = cvt_pk_bf16(v1[0], v1[1]); w.w = cvt_pk_bf16(v1[2], v1[3]);
;                     *(u32x4*)(rowp + bj * HALF) = w;
	s_waitcnt lgkmcnt(0)
	s_setprio 1
	v_mfma_f32_16x16x32_bf16 v[60:63], v[138:141], v[182:185], v[60:63]
	v_mfma_f32_16x16x32_bf16 v[56:59], v[174:177], v[182:185], v[56:59]
	v_mfma_f32_16x16x32_bf16 v[44:47], v[138:141], v[208:211], v[44:47]
	v_mfma_f32_16x16x32_bf16 v[40:43], v[174:177], v[208:211], v[40:43]
	v_mfma_f32_16x16x32_bf16 v[28:31], v[138:141], v[216:219], v[28:31]
	v_mfma_f32_16x16x32_bf16 v[24:27], v[174:177], v[216:219], v[24:27]
	v_mfma_f32_16x16x32_bf16 v[12:15], v[138:141], v[224:227], v[12:15]
	v_mfma_f32_16x16x32_bf16 v[8:11], v[174:177], v[224:227], v[8:11]
	v_mfma_f32_16x16x32_bf16 v[60:63], v[142:145], v[196:199], v[60:63]
	v_mfma_f32_16x16x32_bf16 v[56:59], v[178:181], v[196:199], v[56:59]
	v_mfma_f32_16x16x32_bf16 v[44:47], v[142:145], v[212:215], v[44:47]
	v_mfma_f32_16x16x32_bf16 v[40:43], v[178:181], v[212:215], v[40:43]
	v_mfma_f32_16x16x32_bf16 v[28:31], v[142:145], v[220:223], v[28:31]
	v_mfma_f32_16x16x32_bf16 v[24:27], v[178:181], v[220:223], v[24:27]
	v_mfma_f32_16x16x32_bf16 v[12:15], v[142:145], v[228:231], v[12:15]
	v_mfma_f32_16x16x32_bf16 v[8:11], v[178:181], v[228:231], v[8:11]
	s_setprio 0
	s_barrier
	s_add_u32 s26, s26, 0x80080
	s_addc_u32 s27, s27, 0
	s_mov_b32 m0, s48
	v_lshl_add_u64 v[138:139], s[26:27], 0, v[160:161]
	global_load_lds_dwordx4 v[138:139], off
	s_mov_b32 m0, s49
	v_lshl_add_u64 v[138:139], s[26:27], 0, v[132:133]
	global_load_lds_dwordx4 v[138:139], off
	s_waitcnt vmcnt(6)
	s_barrier
	s_setprio 1
	v_mfma_f32_16x16x32_bf16 v[52:55], v[232:235], v[182:185], v[52:55]
	v_mfma_f32_16x16x32_bf16 v[48:51], v[240:243], v[182:185], v[48:51]
	v_mfma_f32_16x16x32_bf16 v[36:39], v[232:235], v[208:211], v[36:39]
	v_mfma_f32_16x16x32_bf16 v[32:35], v[240:243], v[208:211], v[32:35]
	v_mfma_f32_16x16x32_bf16 v[20:23], v[232:235], v[216:219], v[20:23]
	v_mfma_f32_16x16x32_bf16 v[16:19], v[240:243], v[216:219], v[16:19]
	v_mfma_f32_16x16x32_bf16 v[4:7], v[232:235], v[224:227], v[4:7]
	v_mfma_f32_16x16x32_bf16 v[0:3], v[240:243], v[224:227], v[0:3]
	v_mfma_f32_16x16x32_bf16 v[52:55], v[236:239], v[196:199], v[52:55]
	v_mfma_f32_16x16x32_bf16 v[48:51], v[244:247], v[196:199], v[48:51]
	v_mfma_f32_16x16x32_bf16 v[36:39], v[236:239], v[212:215], v[36:39]
	v_mfma_f32_16x16x32_bf16 v[32:35], v[244:247], v[212:215], v[32:35]
	v_mfma_f32_16x16x32_bf16 v[20:23], v[236:239], v[220:223], v[20:23]
	v_mfma_f32_16x16x32_bf16 v[16:19], v[244:247], v[220:223], v[16:19]
	v_mfma_f32_16x16x32_bf16 v[4:7], v[236:239], v[228:231], v[4:7]
	v_mfma_f32_16x16x32_bf16 v[0:3], v[244:247], v[228:231], v[0:3]
	s_setprio 0
	s_add_i32 s56, s56, 2
	s_add_u32 s24, s24, 0x100
	s_addc_u32 s25, s25, 0
	s_add_u32 s54, s54, 0x100
	s_addc_u32 s55, s55, 0
	s_cmp_gt_u32 s56, 29
	s_cbranch_scc0 .Lrot_799
	s_barrier
	v_lshl_add_u32 v138, s22, 8, v169
	v_ashrrev_i32_e32 v139, 31, v138
	v_lshl_add_u64 v[140:141], v[138:139], 3, s[10:11]
	global_load_dwordx2 v[142:143], v[140:141], off
	global_load_dwordx2 v[208:209], v[140:141], off offset:128
	global_load_dwordx2 v[210:211], v[140:141], off offset:256
	global_load_dwordx2 v[212:213], v[140:141], off offset:384
	global_load_dwordx2 v[214:215], v[140:141], off offset:1024
	global_load_dwordx2 v[216:217], v[140:141], off offset:1152
	global_load_dwordx2 v[218:219], v[140:141], off offset:1280
	global_load_dwordx2 v[220:221], v[140:141], off offset:1408
	v_lshl_or_b32 v144, s51, 8, v171
	v_ashrrev_i32_e32 v145, 31, v144
	s_movk_i32 s15, 0x2200
	v_lshlrev_b64 v[144:145], 1, v[144:145]
	s_mov_b32 s51, s14
	s_mov_b32 s22, s16
	s_mov_b64 s[26:27], s[20:21]
	s_waitcnt vmcnt(0)
	v_cvt_f64_u32_e32 v[174:175], v143
	v_ldexp_f64 v[174:175], v[174:175], 32
	v_cvt_f64_u32_e32 v[142:143], v142
	v_add_f64 v[142:143], v[174:175], v[142:143]
	v_ldexp_f64 v[142:143], v[142:143], s93
	v_cvt_f32_f64_e32 v139, v[142:143]
	v_fmamk_f32 v139, v139, 0x3a000000, v189
	v_cmp_gt_f32_e32 vcc, s78, v139
	v_mul_f32_e32 v142, 0x4b800000, v139
	s_nop 0
	v_cndmask_b32_e32 v139, v139, v142, vcc
	v_rsq_f32_e32 v139, v139
	s_nop 0
	v_mul_f32_e32 v142, 0x45800000, v139
	v_cndmask_b32_e32 v174, v139, v142, vcc
	v_mov_b64_e32 v[142:143], s[12:13]
	v_mad_i64_i32 v[176:177], s[24:25], v138, s15, v[142:143]
	v_lshl_add_u64 v[176:177], v[176:177], 0, v[144:145]
	v_pk_mul_f32 v[126:127], v[126:127], v[174:175] op_sel_hi:[1,0]
	v_pk_mul_f32 v[124:125], v[124:125], v[174:175] op_sel_hi:[1,0]
	v_pk_mul_f32 v[178:179], v[122:123], v[174:175] op_sel_hi:[1,0]
	v_pk_mul_f32 v[122:123], v[120:121], v[174:175] op_sel_hi:[1,0]
	v_cvt_pk_bf16_f32 v120, v124, v125
	v_cvt_pk_bf16_f32 v121, v126, v127
	v_pk_mul_f32 v[116:117], v[116:117], v[174:175] op_sel_hi:[1,0]
	v_cvt_pk_bf16_f32 v122, v122, v123
	v_cvt_pk_bf16_f32 v123, v178, v179
	global_store_dwordx4 v[176:177], v[120:123], off
	v_pk_mul_f32 v[118:119], v[118:119], v[174:175] op_sel_hi:[1,0]
	s_nop 0
	v_pk_mul_f32 v[120:121], v[114:115], v[174:175] op_sel_hi:[1,0]
	v_pk_mul_f32 v[114:115], v[112:113], v[174:175] op_sel_hi:[1,0]
	v_cvt_pk_bf16_f32 v112, v116, v117
	v_cvt_pk_bf16_f32 v113, v118, v119
	s_nop 0
	v_cvt_pk_bf16_f32 v114, v114, v115
	v_cvt_pk_bf16_f32 v115, v120, v121
	global_store_dwordx4 v[176:177], v[112:115], off offset:256
	s_nop 1
	v_or_b32_e32 v112, 16, v138
	v_ashrrev_i32_e32 v113, 31, v112
	v_lshl_add_u64 v[114:115], v[112:113], 3, s[10:11]
	s_nop 1
	v_mov_b64_e32 v[114:115], v[208:209]
	v_cvt_f64_u32_e32 v[116:117], v115
	v_ldexp_f64 v[116:117], v[116:117], 32
	v_cvt_f64_u32_e32 v[114:115], v114
	v_add_f64 v[114:115], v[116:117], v[114:115]
	v_ldexp_f64 v[114:115], v[114:115], s93
	v_cvt_f32_f64_e32 v113, v[114:115]
	v_fmamk_f32 v113, v113, 0x3a000000, v189
; __device__ __forceinline__ unsigned cvt_pk_bf16(float lo, float hi) { unsigned r; asm volatile("v_cvt_pk_bf16_f32 %0, %1, %2" : "=v"(r) : "v"(lo), "v"(hi)); return r; }
; __device__ __forceinline__ float rinv_st(stat_t s, float invn) { return rsqrtf((float)((double)s * (1.0 / 4294967296.0)) * invn + 1e-6f); }
;     __device__ __forceinline__ void operator()(const f32x4 (&acc)[2][2][4][2], const Unit& u, int wr, int wc, int fr, int fq) const {
;     ...
;             for (int m = 0; m < 4; ++m) {
;                 const int row = row0 + ai * HALF + m * 16; const float r = rinv_st(stats[row], 1.0f / 2048.0f);
;                 bf16_t* rowp = raw + (size_t)row * NINP + col0;
; #pragma unroll
;                 for (int bj = 0; bj < 2; ++bj) {
;                     const f32x4 v0 = acc[ai][bj][m][0] * r, v1 = acc[ai][bj][m][1] * r;
;                     u32x4 w; w.x = cvt_pk_bf16(v0[0], v0[1]); w.y = cvt_pk_bf16(v0[2], v0[3]); w.z = cvt_pk_bf16(v1[0], v1[1]); w.w = cvt_pk_bf16(v1[2], v1[3]);
;                     *(u32x4*)(rowp + bj * HALF) = w;
;                 }
;             }
	v_cmp_gt_f32_e32 vcc, s78, v113
	v_mul_f32_e32 v114, 0x4b800000, v113
	s_nop 0
	v_cndmask_b32_e32 v113, v113, v114, vcc
	v_rsq_f32_e32 v113, v113
	s_nop 0
	v_mul_f32_e32 v114, 0x45800000, v113
	v_cndmask_b32_e32 v114, v113, v114, vcc
	v_mad_i64_i32 v[112:113], s[24:25], v112, s15, v[142:143]
	v_lshl_add_u64 v[112:113], v[112:113], 0, v[144:145]
	v_pk_mul_f32 v[110:111], v[110:111], v[114:115] op_sel_hi:[1,0]
	v_pk_mul_f32 v[108:109], v[108:109], v[114:115] op_sel_hi:[1,0]
	v_pk_mul_f32 v[116:117], v[106:107], v[114:115] op_sel_hi:[1,0]
	v_pk_mul_f32 v[106:107], v[104:105], v[114:115] op_sel_hi:[1,0]
	v_cvt_pk_bf16_f32 v104, v108, v109
	v_cvt_pk_bf16_f32 v105, v110, v111
	v_pk_mul_f32 v[100:101], v[100:101], v[114:115] op_sel_hi:[1,0]
	v_cvt_pk_bf16_f32 v106, v106, v107
	v_cvt_pk_bf16_f32 v107, v116, v117
	global_store_dwordx4 v[112:113], v[104:107], off
	v_pk_mul_f32 v[102:103], v[102:103], v[114:115] op_sel_hi:[1,0]
	s_nop 0
	v_pk_mul_f32 v[104:105], v[98:99], v[114:115] op_sel_hi:[1,0]
	v_pk_mul_f32 v[98:99], v[96:97], v[114:115] op_sel_hi:[1,0]
	v_cvt_pk_bf16_f32 v96, v100, v101
	v_cvt_pk_bf16_f32 v97, v102, v103
	s_nop 0
	v_cvt_pk_bf16_f32 v98, v98, v99
	v_cvt_pk_bf16_f32 v99, v104, v105
	global_store_dwordx4 v[112:113], v[96:99], off offset:256
	s_nop 1
	v_or_b32_e32 v96, 32, v138
	v_ashrrev_i32_e32 v97, 31, v96
	v_lshl_add_u64 v[98:99], v[96:97], 3, s[10:11]
	s_nop 1
	v_mov_b64_e32 v[98:99], v[210:211]
	v_cvt_f64_u32_e32 v[100:101], v99
	v_ldexp_f64 v[100:101], v[100:101], 32
	v_cvt_f64_u32_e32 v[98:99], v98
	v_add_f64 v[98:99], v[100:101], v[98:99]
	v_ldexp_f64 v[98:99], v[98:99], s93
	v_cvt_f32_f64_e32 v97, v[98:99]
	v_fmamk_f32 v97, v97, 0x3a000000, v189
	v_cmp_gt_f32_e32 vcc, s78, v97
	v_mul_f32_e32 v98, 0x4b800000, v97
	s_nop 0
	v_cndmask_b32_e32 v97, v97, v98, vcc
	v_rsq_f32_e32 v97, v97
	s_nop 0
	v_mul_f32_e32 v98, 0x45800000, v97
	v_cndmask_b32_e32 v98, v97, v98, vcc
	v_mad_i64_i32 v[96:97], s[24:25], v96, s15, v[142:143]
	v_lshl_add_u64 v[96:97], v[96:97], 0, v[144:145]
	v_pk_mul_f32 v[94:95], v[94:95], v[98:99] op_sel_hi:[1,0]
	v_pk_mul_f32 v[92:93], v[92:93], v[98:99] op_sel_hi:[1,0]
	v_pk_mul_f32 v[100:101], v[90:91], v[98:99] op_sel_hi:[1,0]
	v_pk_mul_f32 v[90:91], v[88:89], v[98:99] op_sel_hi:[1,0]
	v_cvt_pk_bf16_f32 v88, v92, v93
	v_cvt_pk_bf16_f32 v89, v94, v95
	v_pk_mul_f32 v[84:85], v[84:85], v[98:99] op_sel_hi:[1,0]
	v_cvt_pk_bf16_f32 v90, v90, v91
	v_cvt_pk_bf16_f32 v91, v100, v101
	global_store_dwordx4 v[96:97], v[88:91], off
	v_pk_mul_f32 v[86:87], v[86:87], v[98:99] op_sel_hi:[1,0]
	s_nop 0
	v_pk_mul_f32 v[88:89], v[82:83], v[98:99] op_sel_hi:[1,0]
	v_pk_mul_f32 v[82:83], v[80:81], v[98:99] op_sel_hi:[1,0]
	v_cvt_pk_bf16_f32 v80, v84, v85
	v_cvt_pk_bf16_f32 v81, v86, v87
	s_nop 0
	v_cvt_pk_bf16_f32 v82, v82, v83
	v_cvt_pk_bf16_f32 v83, v88, v89
	global_store_dwordx4 v[96:97], v[80:83], off offset:256
	s_nop 1
	v_or_b32_e32 v80, 48, v138
	v_ashrrev_i32_e32 v81, 31, v80
	v_lshl_add_u64 v[82:83], v[80:81], 3, s[10:11]
	s_nop 1
	v_mov_b64_e32 v[82:83], v[212:213]
	v_cvt_f64_u32_e32 v[84:85], v83
	v_ldexp_f64 v[84:85], v[84:85], 32
	v_cvt_f64_u32_e32 v[82:83], v82
	v_add_f64 v[82:83], v[84:85], v[82:83]
	v_ldexp_f64 v[82:83], v[82:83], s93
	v_cvt_f32_f64_e32 v81, v[82:83]
	v_fmamk_f32 v81, v81, 0x3a000000, v189
	v_cmp_gt_f32_e32 vcc, s78, v81
	v_mul_f32_e32 v82, 0x4b800000, v81
	s_nop 0
	v_cndmask_b32_e32 v81, v81, v82, vcc
	v_rsq_f32_e32 v81, v81
	s_nop 0
	v_mul_f32_e32 v82, 0x45800000, v81
	v_cndmask_b32_e32 v82, v81, v82, vcc
	v_mad_i64_i32 v[80:81], s[24:25], v80, s15, v[142:143]
	v_lshl_add_u64 v[80:81], v[80:81], 0, v[144:145]
	v_pk_mul_f32 v[78:79], v[78:79], v[82:83] op_sel_hi:[1,0]
	v_pk_mul_f32 v[76:77], v[76:77], v[82:83] op_sel_hi:[1,0]
	v_pk_mul_f32 v[84:85], v[74:75], v[82:83] op_sel_hi:[1,0]
	v_pk_mul_f32 v[74:75], v[72:73], v[82:83] op_sel_hi:[1,0]
	v_cvt_pk_bf16_f32 v72, v76, v77
	v_cvt_pk_bf16_f32 v73, v78, v79
	v_pk_mul_f32 v[70:71], v[70:71], v[82:83] op_sel_hi:[1,0]
	v_cvt_pk_bf16_f32 v74, v74, v75
	v_cvt_pk_bf16_f32 v75, v84, v85
	global_store_dwordx4 v[80:81], v[72:75], off
	v_pk_mul_f32 v[68:69], v[68:69], v[82:83] op_sel_hi:[1,0]
	s_nop 0
	v_pk_mul_f32 v[72:73], v[66:67], v[82:83] op_sel_hi:[1,0]
	v_pk_mul_f32 v[66:67], v[64:65], v[82:83] op_sel_hi:[1,0]
	v_cvt_pk_bf16_f32 v64, v68, v69
	v_cvt_pk_bf16_f32 v65, v70, v71
	v_add_u32_e32 v68, 0x80, v138
	v_cvt_pk_bf16_f32 v66, v66, v67
	v_cvt_pk_bf16_f32 v67, v72, v73
	global_store_dwordx4 v[80:81], v[64:67], off offset:256
	s_nop 1
	v_mov_b64_e32 v[64:65], v[214:215]
	v_cvt_f64_u32_e32 v[66:67], v65
	v_ldexp_f64 v[66:67], v[66:67], 32
	v_cvt_f64_u32_e32 v[64:65], v64
	v_add_f64 v[64:65], v[66:67], v[64:65]
	v_ldexp_f64 v[64:65], v[64:65], s93
	v_cvt_f32_f64_e32 v64, v[64:65]
	v_fmamk_f32 v64, v64, 0x3a000000, v189
	v_cmp_gt_f32_e32 vcc, s78, v64
	v_mul_f32_e32 v65, 0x4b800000, v64
	v_mad_i64_i32 v[66:67], s[24:25], v68, s15, v[142:143]
	v_cndmask_b32_e32 v64, v64, v65, vcc
	v_rsq_f32_e32 v64, v64
	v_lshl_add_u64 v[66:67], v[66:67], 0, v[144:145]
	v_mul_f32_e32 v65, 0x45800000, v64
	v_cndmask_b32_e32 v64, v64, v65, vcc
	v_pk_mul_f32 v[62:63], v[62:63], v[64:65] op_sel_hi:[1,0]
	v_pk_mul_f32 v[60:61], v[60:61], v[64:65] op_sel_hi:[1,0]
	v_pk_mul_f32 v[68:69], v[58:59], v[64:65] op_sel_hi:[1,0]
; __device__ __forceinline__ unsigned cvt_pk_bf16(float lo, float hi) { unsigned r; asm volatile("v_cvt_pk_bf16_f32 %0, %1, %2" : "=v"(r) : "v"(lo), "v"(hi)); return r; }
; __device__ __forceinline__ float rinv_st(stat_t s, float invn) { return rsqrtf((float)((double)s * (1.0 / 4294967296.0)) * invn + 1e-6f); }
; #define PG8_WAIT_V(n) asm volatile("s_waitcnt vmcnt(" #n ")" ::: "memory")
; #define PG8_BAR __builtin_amdgcn_s_barrier()
; template <class Epi>
; __device__ __forceinline__ void gemm_phase(const int TID, const int BID, LAS unsigned char* lds, const Gemm g, const StaticOrder& S, const Epi& E) {
;     ...
;     PG8_WAIT_V(0);
;     if (wr == 0) PG8_BAR;
;     PG8_BAR;
;     __device__ __forceinline__ void operator()(const f32x4 (&acc)[2][2][4][2], const Unit& u, int wr, int wc, int fr, int fq) const {
;     ...
;             for (int m = 0; m < 4; ++m) {
;                 const int row = row0 + ai * HALF + m * 16; const float r = rinv_st(stats[row], 1.0f / 2048.0f);
;                 bf16_t* rowp = raw + (size_t)row * NINP + col0;
; #pragma unroll
;                 for (int bj = 0; bj < 2; ++bj) {
;                     const f32x4 v0 = acc[ai][bj][m][0] * r, v1 = acc[ai][bj][m][1] * r;
;                     u32x4 w; w.x = cvt_pk_bf16(v0[0], v0[1]); w.y = cvt_pk_bf16(v0[2], v0[3]); w.z = cvt_pk_bf16(v1[0], v1[1]); w.w = cvt_pk_bf16(v1[2], v1[3]);
;                     *(u32x4*)(rowp + bj * HALF) = w;
;                 }
;             }
	v_pk_mul_f32 v[58:59], v[56:57], v[64:65] op_sel_hi:[1,0]
	v_cvt_pk_bf16_f32 v56, v60, v61
	v_cvt_pk_bf16_f32 v57, v62, v63
	v_pk_mul_f32 v[54:55], v[54:55], v[64:65] op_sel_hi:[1,0]
	v_cvt_pk_bf16_f32 v58, v58, v59
	v_cvt_pk_bf16_f32 v59, v68, v69
	global_store_dwordx4 v[66:67], v[56:59], off
	v_pk_mul_f32 v[52:53], v[52:53], v[64:65] op_sel_hi:[1,0]
	s_nop 0
	v_pk_mul_f32 v[56:57], v[50:51], v[64:65] op_sel_hi:[1,0]
	v_pk_mul_f32 v[50:51], v[48:49], v[64:65] op_sel_hi:[1,0]
	v_cvt_pk_bf16_f32 v48, v52, v53
	v_cvt_pk_bf16_f32 v49, v54, v55
	v_add_u32_e32 v52, 0x90, v138
	v_cvt_pk_bf16_f32 v50, v50, v51
	v_cvt_pk_bf16_f32 v51, v56, v57
	global_store_dwordx4 v[66:67], v[48:51], off offset:256
	s_nop 1
	v_mov_b64_e32 v[48:49], v[216:217]
	v_cvt_f64_u32_e32 v[50:51], v49
	v_ldexp_f64 v[50:51], v[50:51], 32
	v_cvt_f64_u32_e32 v[48:49], v48
	v_add_f64 v[48:49], v[50:51], v[48:49]
	v_ldexp_f64 v[48:49], v[48:49], s93
	v_cvt_f32_f64_e32 v48, v[48:49]
	v_fmamk_f32 v48, v48, 0x3a000000, v189
	v_cmp_gt_f32_e32 vcc, s78, v48
	v_mul_f32_e32 v49, 0x4b800000, v48
	v_mad_i64_i32 v[50:51], s[24:25], v52, s15, v[142:143]
	v_cndmask_b32_e32 v48, v48, v49, vcc
	v_rsq_f32_e32 v48, v48
	v_lshl_add_u64 v[50:51], v[50:51], 0, v[144:145]
	v_mul_f32_e32 v49, 0x45800000, v48
	v_cndmask_b32_e32 v48, v48, v49, vcc
	v_pk_mul_f32 v[46:47], v[46:47], v[48:49] op_sel_hi:[1,0]
	v_pk_mul_f32 v[44:45], v[44:45], v[48:49] op_sel_hi:[1,0]
	v_pk_mul_f32 v[52:53], v[42:43], v[48:49] op_sel_hi:[1,0]
	v_pk_mul_f32 v[42:43], v[40:41], v[48:49] op_sel_hi:[1,0]
	v_cvt_pk_bf16_f32 v40, v44, v45
	v_cvt_pk_bf16_f32 v41, v46, v47
	v_pk_mul_f32 v[38:39], v[38:39], v[48:49] op_sel_hi:[1,0]
	v_cvt_pk_bf16_f32 v42, v42, v43
	v_cvt_pk_bf16_f32 v43, v52, v53
	global_store_dwordx4 v[50:51], v[40:43], off
	v_pk_mul_f32 v[36:37], v[36:37], v[48:49] op_sel_hi:[1,0]
	s_nop 0
	v_pk_mul_f32 v[40:41], v[34:35], v[48:49] op_sel_hi:[1,0]
	v_pk_mul_f32 v[34:35], v[32:33], v[48:49] op_sel_hi:[1,0]
	v_cvt_pk_bf16_f32 v32, v36, v37
	v_cvt_pk_bf16_f32 v33, v38, v39
	v_add_u32_e32 v36, 0xa0, v138
	v_cvt_pk_bf16_f32 v34, v34, v35
	v_cvt_pk_bf16_f32 v35, v40, v41
	global_store_dwordx4 v[50:51], v[32:35], off offset:256
	s_nop 1
	v_mov_b64_e32 v[32:33], v[218:219]
	v_cvt_f64_u32_e32 v[34:35], v33
	v_ldexp_f64 v[34:35], v[34:35], 32
	v_cvt_f64_u32_e32 v[32:33], v32
	v_add_f64 v[32:33], v[34:35], v[32:33]
	v_ldexp_f64 v[32:33], v[32:33], s93
	v_cvt_f32_f64_e32 v32, v[32:33]
	v_fmamk_f32 v32, v32, 0x3a000000, v189
	v_cmp_gt_f32_e32 vcc, s78, v32
	v_mul_f32_e32 v33, 0x4b800000, v32
	v_mad_i64_i32 v[34:35], s[24:25], v36, s15, v[142:143]
	v_cndmask_b32_e32 v32, v32, v33, vcc
	v_rsq_f32_e32 v32, v32
	v_lshl_add_u64 v[34:35], v[34:35], 0, v[144:145]
	v_mul_f32_e32 v33, 0x45800000, v32
	v_cndmask_b32_e32 v32, v32, v33, vcc
	v_pk_mul_f32 v[30:31], v[30:31], v[32:33] op_sel_hi:[1,0]
	v_pk_mul_f32 v[28:29], v[28:29], v[32:33] op_sel_hi:[1,0]
	v_pk_mul_f32 v[36:37], v[26:27], v[32:33] op_sel_hi:[1,0]
	v_pk_mul_f32 v[26:27], v[24:25], v[32:33] op_sel_hi:[1,0]
	v_cvt_pk_bf16_f32 v24, v28, v29
	v_cvt_pk_bf16_f32 v25, v30, v31
	v_pk_mul_f32 v[22:23], v[22:23], v[32:33] op_sel_hi:[1,0]
	v_cvt_pk_bf16_f32 v26, v26, v27
	v_cvt_pk_bf16_f32 v27, v36, v37
	global_store_dwordx4 v[34:35], v[24:27], off
	v_pk_mul_f32 v[20:21], v[20:21], v[32:33] op_sel_hi:[1,0]
	s_nop 0
	v_pk_mul_f32 v[24:25], v[18:19], v[32:33] op_sel_hi:[1,0]
	v_pk_mul_f32 v[18:19], v[16:17], v[32:33] op_sel_hi:[1,0]
	v_cvt_pk_bf16_f32 v16, v20, v21
	v_cvt_pk_bf16_f32 v17, v22, v23
	v_add_u32_e32 v20, 0xb0, v138
	v_cvt_pk_bf16_f32 v18, v18, v19
	v_cvt_pk_bf16_f32 v19, v24, v25
	global_store_dwordx4 v[34:35], v[16:19], off offset:256
	s_nop 1
	v_mov_b64_e32 v[16:17], v[220:221]
	v_cvt_f64_u32_e32 v[18:19], v17
	v_ldexp_f64 v[18:19], v[18:19], 32
	v_cvt_f64_u32_e32 v[16:17], v16
	v_add_f64 v[16:17], v[18:19], v[16:17]
	v_ldexp_f64 v[16:17], v[16:17], s93
	v_cvt_f32_f64_e32 v16, v[16:17]
	v_fmamk_f32 v16, v16, 0x3a000000, v189
	v_cmp_gt_f32_e32 vcc, s78, v16
	v_mul_f32_e32 v17, 0x4b800000, v16
	v_mad_i64_i32 v[18:19], s[24:25], v20, s15, v[142:143]
	v_cndmask_b32_e32 v16, v16, v17, vcc
	v_rsq_f32_e32 v16, v16
	v_lshl_add_u64 v[18:19], v[18:19], 0, v[144:145]
	s_mov_b64 s[24:25], s[18:19]
	v_mul_f32_e32 v17, 0x45800000, v16
	v_cndmask_b32_e32 v16, v16, v17, vcc
	v_pk_mul_f32 v[14:15], v[14:15], v[16:17] op_sel_hi:[1,0]
	v_pk_mul_f32 v[12:13], v[12:13], v[16:17] op_sel_hi:[1,0]
	v_pk_mul_f32 v[20:21], v[10:11], v[16:17] op_sel_hi:[1,0]
	v_pk_mul_f32 v[10:11], v[8:9], v[16:17] op_sel_hi:[1,0]
	v_cvt_pk_bf16_f32 v8, v12, v13
	v_cvt_pk_bf16_f32 v9, v14, v15
	s_and_b64 vcc, exec, s[8:9]
	v_cvt_pk_bf16_f32 v10, v10, v11
	v_cvt_pk_bf16_f32 v11, v20, v21
	global_store_dwordx4 v[18:19], v[8:11], off
	v_pk_mul_f32 v[6:7], v[6:7], v[16:17] op_sel_hi:[1,0]
	v_pk_mul_f32 v[4:5], v[4:5], v[16:17] op_sel_hi:[1,0]
	v_pk_mul_f32 v[8:9], v[2:3], v[16:17] op_sel_hi:[1,0]
	v_pk_mul_f32 v[2:3], v[0:1], v[16:17] op_sel_hi:[1,0]
	v_cvt_pk_bf16_f32 v0, v4, v5
	v_cvt_pk_bf16_f32 v1, v6, v7
	s_nop 0
	v_cvt_pk_bf16_f32 v2, v2, v3
	v_cvt_pk_bf16_f32 v3, v8, v9
	global_store_dwordx4 v[18:19], v[0:3], off offset:256
	s_cbranch_vccz .LBB0_792
	s_waitcnt vmcnt(0)
	s_cmpk_gt_u32 s0, 0xff
	s_cbranch_scc1 .LBB0_803
	s_barrier

; template <class Epi>
; __device__ __forceinline__ void gemm_phase(const int TID, const int BID, LAS unsigned char* lds, const Gemm g, const StaticOrder& S, const Epi& E) {
;     ...
;     for (;;) {
;         const bool has_next = S.next(ui + 1, nxt);
;         const char* nA = has_next ? (const char*)g.A + (size_t)nxt.pm * tstepA : cA; const char* nB = has_next ? (const char*)g.Bt + (size_t)nxt.pn * tstepB : cB;
;     ...
; #pragma unroll
;         for (int a = 0; a < 2; ++a)
; #pragma unroll
;             for (int b = 0; b < 2; ++b)
; #pragma unroll
;                 for (int m = 0; m < 4; ++m)
; #pragma unroll
;                     for (int n = 0; n < 2; ++n) acc[a][b][m][n] = (f32x4){0.f, 0.f, 0.f, 0.f};
;         cur = nxt; cA = nA; cB = nB; ++ui;
.LBB0_821:
	s_ashr_i32 s17, s16, 31
	v_cmp_lt_i64_e64 s[30:31], s[20:21], 32
	s_lshl_b64 s[20:21], s[16:17], 20
	s_add_u32 s20, s44, s20
	s_addc_u32 s21, s45, s21
	s_and_b64 s[22:23], s[30:31], exec
	s_cselect_b32 s17, s21, s27
	s_cselect_b32 s61, s20, s26
	s_ashr_i32 s15, s14, 31
	s_lshl_b64 s[22:23], s[14:15], 20
	s_add_u32 s22, s8, s22
	s_addc_u32 s23, s9, s23
	s_and_b64 s[30:31], s[30:31], exec
	s_cselect_b32 s15, s23, s29
	s_cselect_b32 s62, s22, s28
	s_add_u32 s26, s26, 0x80080
	s_addc_u32 s27, s27, 0
	s_add_u32 s63, s28, 0x100
	v_mov_b32_e32 v0, 0
	s_addc_u32 s64, s29, 0
	s_mov_b32 s66, -2
	v_mov_b32_e32 v1, v0
	v_mov_b32_e32 v2, v0
	v_mov_b32_e32 v3, v0
	v_mov_b32_e32 v4, v0
	v_mov_b32_e32 v5, v0
	v_mov_b32_e32 v6, v0
	v_mov_b32_e32 v7, v0
	v_mov_b32_e32 v16, v0
	v_mov_b32_e32 v17, v0
	v_mov_b32_e32 v18, v0
	v_mov_b32_e32 v19, v0
	v_mov_b32_e32 v20, v0
	v_mov_b32_e32 v21, v0
	v_mov_b32_e32 v22, v0
	v_mov_b32_e32 v23, v0
	s_waitcnt vmcnt(0)
	v_mov_b32_e32 v32, v0
	v_mov_b32_e32 v33, v0
	v_mov_b32_e32 v34, v0
	v_mov_b32_e32 v35, v0
	v_mov_b32_e32 v36, v0
	v_mov_b32_e32 v37, v0
	v_mov_b32_e32 v38, v0
	v_mov_b32_e32 v39, v0
	v_mov_b32_e32 v48, v0
	v_mov_b32_e32 v49, v0
	v_mov_b32_e32 v50, v0
	v_mov_b32_e32 v51, v0
	v_mov_b32_e32 v52, v0
	v_mov_b32_e32 v53, v0
	v_mov_b32_e32 v54, v0
	v_mov_b32_e32 v55, v0
	v_mov_b32_e32 v8, v0
	v_mov_b32_e32 v9, v0
	v_mov_b32_e32 v10, v0
	v_mov_b32_e32 v11, v0
	v_mov_b32_e32 v12, v0
	v_mov_b32_e32 v13, v0
	v_mov_b32_e32 v14, v0
	v_mov_b32_e32 v15, v0
	v_mov_b32_e32 v24, v0
	v_mov_b32_e32 v25, v0
	v_mov_b32_e32 v26, v0
	v_mov_b32_e32 v27, v0
	v_mov_b32_e32 v28, v0
	v_mov_b32_e32 v29, v0
	v_mov_b32_e32 v30, v0
	v_mov_b32_e32 v31, v0
	v_mov_b32_e32 v40, v0
	v_mov_b32_e32 v41, v0
	v_mov_b32_e32 v42, v0
	v_mov_b32_e32 v43, v0
	v_mov_b32_e32 v44, v0
	v_mov_b32_e32 v45, v0
	v_mov_b32_e32 v46, v0
	v_mov_b32_e32 v47, v0
	v_mov_b32_e32 v56, v0
	v_mov_b32_e32 v57, v0
	v_mov_b32_e32 v58, v0
	v_mov_b32_e32 v59, v0
	v_mov_b32_e32 v60, v0
	v_mov_b32_e32 v61, v0
	v_mov_b32_e32 v62, v0
	v_mov_b32_e32 v63, v0
	v_mov_b32_e32 v64, v0
	v_mov_b32_e32 v65, v0
	v_mov_b32_e32 v66, v0
	v_mov_b32_e32 v67, v0
	v_mov_b32_e32 v68, v0
	v_mov_b32_e32 v69, v0
	v_mov_b32_e32 v70, v0
	v_mov_b32_e32 v71, v0
	v_mov_b32_e32 v80, v0
	v_mov_b32_e32 v81, v0
	v_mov_b32_e32 v82, v0
	v_mov_b32_e32 v83, v0
	v_mov_b32_e32 v84, v0
	v_mov_b32_e32 v85, v0
	v_mov_b32_e32 v86, v0
	v_mov_b32_e32 v87, v0
	v_mov_b32_e32 v96, v0
	v_mov_b32_e32 v97, v0
	v_mov_b32_e32 v98, v0
	v_mov_b32_e32 v99, v0
	v_mov_b32_e32 v100, v0
	v_mov_b32_e32 v101, v0
	v_mov_b32_e32 v102, v0
	v_mov_b32_e32 v103, v0
	v_mov_b32_e32 v112, v0
	v_mov_b32_e32 v113, v0
	v_mov_b32_e32 v114, v0
	v_mov_b32_e32 v115, v0
	v_mov_b32_e32 v116, v0
	v_mov_b32_e32 v117, v0
	v_mov_b32_e32 v118, v0
	v_mov_b32_e32 v119, v0
	v_mov_b32_e32 v72, v0
	v_mov_b32_e32 v73, v0
	v_mov_b32_e32 v74, v0
	v_mov_b32_e32 v75, v0
	v_mov_b32_e32 v76, v0
	v_mov_b32_e32 v77, v0
	v_mov_b32_e32 v78, v0
	v_mov_b32_e32 v79, v0
	v_mov_b32_e32 v88, v0
	v_mov_b32_e32 v89, v0
	v_mov_b32_e32 v90, v0
	v_mov_b32_e32 v91, v0
	v_mov_b32_e32 v92, v0
	v_mov_b32_e32 v93, v0
	v_mov_b32_e32 v94, v0
	v_mov_b32_e32 v95, v0
	v_mov_b32_e32 v104, v0
	v_mov_b32_e32 v105, v0
	v_mov_b32_e32 v106, v0
	v_mov_b32_e32 v107, v0
	v_mov_b32_e32 v108, v0
	v_mov_b32_e32 v109, v0
	v_mov_b32_e32 v110, v0
	v_mov_b32_e32 v111, v0
	v_mov_b32_e32 v120, v0
	v_mov_b32_e32 v121, v0
	v_mov_b32_e32 v122, v0
	v_mov_b32_e32 v123, v0
	v_mov_b32_e32 v124, v0
	v_mov_b32_e32 v125, v0
	v_mov_b32_e32 v126, v0
	v_mov_b32_e32 v127, v0
	s_branch .LBB0_822

; #define PG8_STAGE(bufoff, gbase, voff) do { _Pragma("unroll") for (int _i = 0; _i < 2; ++_i) \
;         __builtin_amdgcn_global_load_lds((const unsigned*)((const char*)(gbase) + (voff)[_i]), (LAS unsigned*)(lds + (bufoff) + ldsw + _i * 8192), 16, 0, 0); } while (0)
; #define PG8_LDA(dst, b, h) do { _Pragma("unroll") for (int m = 0; m < 4; ++m) _Pragma("unroll") for (int k = 0; k < 2; ++k) dst[m][k] = *(const LAS bf16x8*)(lds + PG8_SA(b, h) + aoff + m * 2048 + k * 1024); } while (0)
; #define PG8_LDB(dst, b, h) do { _Pragma("unroll") for (int n = 0; n < 2; ++n) _Pragma("unroll") for (int k = 0; k < 2; ++k) dst[n][k] = *(const LAS bf16x8*)(lds + PG8_SB(b, h) + boff + n * 2048 + k * 1024); } while (0)
; #define PG8_MMA(ai, bj, At, Bt) do { __builtin_amdgcn_s_setprio(1); _Pragma("unroll") for (int m = 0; m < 4; ++m) _Pragma("unroll") for (int n = 0; n < 2; ++n) _Pragma("unroll") for (int k = 0; k < 2; ++k) \
;         acc[ai][bj][m][n] = __builtin_amdgcn_mfma_f32_16x16x32_bf16(Bt[n][k], At[m][k], acc[ai][bj][m][n], 0, 0, 0); __builtin_amdgcn_s_setprio(0); } while (0)
; #define PG8_WAIT_V(n) asm volatile("s_waitcnt vmcnt(" #n ")" ::: "memory")
; #define PG8_WAIT_L(n) asm volatile("s_waitcnt lgkmcnt(" #n ")" ::: "memory")
; #define PG8_BAR __builtin_amdgcn_s_barrier()
; #define PG8_SCHED __builtin_amdgcn_sched_barrier(0)
; template <class Epi>
; __device__ __forceinline__ void gemm_phase(const int TID, const int BID, LAS unsigned char* lds, const Gemm g, const StaticOrder& S, const Epi& E) {
;     ...
;             PG8_LDB(B0, 0, 0); PG8_SCHED; PG8_LDA(At, 0, 0); PG8_STAGE(PG8_SA(1, 1), a1 + hstepA, voffA);
;             PG8_WAIT_L(8); PG8_BAR; PG8_WAIT_L(0); PG8_MMA(0, 0, At, B0); PG8_BAR; PG8_SCHED;
;             PG8_LDB(B1, 0, 1); PG8_STAGE(PG8_SB(0, 0), b2, voffB);
;             PG8_BAR; PG8_WAIT_L(0); PG8_MMA(0, 1, At, B1); PG8_BAR;
;             PG8_LDA(At, 0, 1); PG8_STAGE(PG8_SA(0, 0), a2, voffA);
;             PG8_BAR; PG8_WAIT_L(0); PG8_MMA(1, 0, At, B0); PG8_BAR; PG8_SCHED;
;             PG8_STAGE(PG8_SB(0, 1), b2 + hstepB, voffB);
;             PG8_WAIT_V(6); PG8_BAR; PG8_MMA(1, 1, At, B1); PG8_BAR;
.LBB0_822:
	v_add_u32_e32 v154, s36, v147
	ds_read_b128 v[134:137], v154
	ds_read_b128 v[138:141], v154 offset:1024
	ds_read_b128 v[150:153], v154 offset:2048
	ds_read_b128 v[154:157], v154 offset:3072
	s_add_u32 s28, s26, 0xfff80080
	s_addc_u32 s29, s27, -1
	s_cmp_eq_u32 s66, 4
	s_cselect_b32 s31, s17, s29
	s_cselect_b32 s30, s61, s28
	s_cselect_b32 s29, s15, s64
	s_cselect_b32 s28, s62, s63
	v_lshl_add_u64 v[158:159], s[26:27], 0, v[130:131]
	s_add_i32 m0, s47, 0xc000
	ds_read_b128 v[166:169], v149
	ds_read_b128 v[170:173], v149 offset:1024
	ds_read_b128 v[174:177], v149 offset:2048
	ds_read_b128 v[178:181], v149 offset:3072
	ds_read_b128 v[182:185], v149 offset:4096
	ds_read_b128 v[196:199], v149 offset:5120
	ds_read_b128 v[208:211], v149 offset:6144
	ds_read_b128 v[212:215], v149 offset:7168
	global_load_lds_dwordx4 v[158:159], off
	s_add_i32 m0, s47, 0xe000
	v_lshl_add_u64 v[158:159], s[26:27], 0, v[132:133]
	global_load_lds_dwordx4 v[158:159], off
	s_waitcnt lgkmcnt(8)
	s_barrier
	s_waitcnt lgkmcnt(0)
	s_setprio 1
	v_mfma_f32_16x16x32_bf16 v[124:127], v[134:137], v[166:169], v[124:127]
	v_mfma_f32_16x16x32_bf16 v[120:123], v[150:153], v[166:169], v[120:123]
	v_mfma_f32_16x16x32_bf16 v[108:111], v[134:137], v[174:177], v[108:111]
	v_mfma_f32_16x16x32_bf16 v[104:107], v[150:153], v[174:177], v[104:107]
	v_mfma_f32_16x16x32_bf16 v[92:95], v[134:137], v[182:185], v[92:95]
	v_mfma_f32_16x16x32_bf16 v[88:91], v[150:153], v[182:185], v[88:91]
	v_mfma_f32_16x16x32_bf16 v[76:79], v[134:137], v[208:211], v[76:79]
	v_mfma_f32_16x16x32_bf16 v[72:75], v[150:153], v[208:211], v[72:75]
	v_mfma_f32_16x16x32_bf16 v[124:127], v[138:141], v[170:173], v[124:127]
	v_mfma_f32_16x16x32_bf16 v[120:123], v[154:157], v[170:173], v[120:123]
	v_mfma_f32_16x16x32_bf16 v[108:111], v[138:141], v[178:181], v[108:111]
	v_mfma_f32_16x16x32_bf16 v[104:107], v[154:157], v[178:181], v[104:107]
	v_mfma_f32_16x16x32_bf16 v[92:95], v[138:141], v[196:199], v[92:95]
	v_mfma_f32_16x16x32_bf16 v[88:91], v[154:157], v[196:199], v[88:91]
	v_mfma_f32_16x16x32_bf16 v[76:79], v[138:141], v[212:215], v[76:79]
	v_mfma_f32_16x16x32_bf16 v[72:75], v[154:157], v[212:215], v[72:75]
	s_setprio 0
	s_barrier
	v_add_u32_e32 v158, s37, v147
	s_mov_b32 m0, s25
	ds_read_b128 v[216:219], v158
	ds_read_b128 v[220:223], v158 offset:1024
	ds_read_b128 v[224:227], v158 offset:2048
	ds_read_b128 v[228:231], v158 offset:3072
	v_lshl_add_u64 v[158:159], s[28:29], 0, v[160:161]
	global_load_lds_dwordx4 v[158:159], off
	s_mov_b32 m0, s46
	v_lshl_add_u64 v[200:201], s[28:29], 0, v[128:129]
	global_load_lds_dwordx4 v[200:201], off
	s_barrier
	s_waitcnt lgkmcnt(0)
	s_setprio 1
	v_mfma_f32_16x16x32_bf16 v[116:119], v[216:219], v[166:169], v[116:119]
	v_mfma_f32_16x16x32_bf16 v[112:115], v[224:227], v[166:169], v[112:115]
	v_mfma_f32_16x16x32_bf16 v[100:103], v[216:219], v[174:177], v[100:103]
	v_mfma_f32_16x16x32_bf16 v[96:99], v[224:227], v[174:177], v[96:99]
	v_mfma_f32_16x16x32_bf16 v[84:87], v[216:219], v[182:185], v[84:87]
	v_mfma_f32_16x16x32_bf16 v[80:83], v[224:227], v[182:185], v[80:83]
	v_mfma_f32_16x16x32_bf16 v[68:71], v[216:219], v[208:211], v[68:71]
	v_mfma_f32_16x16x32_bf16 v[64:67], v[224:227], v[208:211], v[64:67]
	v_mfma_f32_16x16x32_bf16 v[116:119], v[220:223], v[170:173], v[116:119]
	v_mfma_f32_16x16x32_bf16 v[112:115], v[228:231], v[170:173], v[112:115]
	v_mfma_f32_16x16x32_bf16 v[100:103], v[220:223], v[178:181], v[100:103]
	v_mfma_f32_16x16x32_bf16 v[96:99], v[228:231], v[178:181], v[96:99]
	v_mfma_f32_16x16x32_bf16 v[84:87], v[220:223], v[196:199], v[84:87]
	v_mfma_f32_16x16x32_bf16 v[80:83], v[228:231], v[196:199], v[80:83]
	v_mfma_f32_16x16x32_bf16 v[68:71], v[220:223], v[212:215], v[68:71]
	v_mfma_f32_16x16x32_bf16 v[64:67], v[228:231], v[212:215], v[64:67]
	s_setprio 0
	s_mov_b32 m0, s47
	v_lshl_add_u64 v[232:233], s[30:31], 0, v[160:161]
	s_barrier
	ds_read_b128 v[166:169], v149 offset:16384
	ds_read_b128 v[170:173], v149 offset:17408
	ds_read_b128 v[174:177], v149 offset:18432
	ds_read_b128 v[178:181], v149 offset:19456
	ds_read_b128 v[182:185], v149 offset:20480
	ds_read_b128 v[196:199], v149 offset:21504
	ds_read_b128 v[208:211], v149 offset:22528
	ds_read_b128 v[212:215], v149 offset:23552
	global_load_lds_dwordx4 v[232:233], off
	s_mov_b32 m0, s48
	v_lshl_add_u64 v[234:235], s[30:31], 0, v[128:129]
	global_load_lds_dwordx4 v[234:235], off
	s_barrier
	s_waitcnt lgkmcnt(0)
	s_setprio 1
	v_mfma_f32_16x16x32_bf16 v[60:63], v[134:137], v[166:169], v[60:63]
	v_mfma_f32_16x16x32_bf16 v[56:59], v[150:153], v[166:169], v[56:59]
	v_mfma_f32_16x16x32_bf16 v[44:47], v[134:137], v[174:177], v[44:47]
	v_mfma_f32_16x16x32_bf16 v[40:43], v[150:153], v[174:177], v[40:43]
	v_mfma_f32_16x16x32_bf16 v[28:31], v[134:137], v[182:185], v[28:31]
	v_mfma_f32_16x16x32_bf16 v[24:27], v[150:153], v[182:185], v[24:27]
	v_mfma_f32_16x16x32_bf16 v[12:15], v[134:137], v[208:211], v[12:15]
	v_mfma_f32_16x16x32_bf16 v[8:11], v[150:153], v[208:211], v[8:11]
	v_mfma_f32_16x16x32_bf16 v[60:63], v[138:141], v[170:173], v[60:63]
	v_mfma_f32_16x16x32_bf16 v[56:59], v[154:157], v[170:173], v[56:59]
	v_mfma_f32_16x16x32_bf16 v[44:47], v[138:141], v[178:181], v[44:47]
	v_mfma_f32_16x16x32_bf16 v[40:43], v[154:157], v[178:181], v[40:43]
	v_mfma_f32_16x16x32_bf16 v[28:31], v[138:141], v[196:199], v[28:31]
	v_mfma_f32_16x16x32_bf16 v[24:27], v[154:157], v[196:199], v[24:27]
	v_mfma_f32_16x16x32_bf16 v[12:15], v[138:141], v[212:215], v[12:15]
	v_mfma_f32_16x16x32_bf16 v[8:11], v[154:157], v[212:215], v[8:11]
	s_setprio 0
	s_barrier
; #define PG8_STAGE(bufoff, gbase, voff) do { _Pragma("unroll") for (int _i = 0; _i < 2; ++_i) \
;         __builtin_amdgcn_global_load_lds((const unsigned*)((const char*)(gbase) + (voff)[_i]), (LAS unsigned*)(lds + (bufoff) + ldsw + _i * 8192), 16, 0, 0); } while (0)
; #define PG8_LDA(dst, b, h) do { _Pragma("unroll") for (int m = 0; m < 4; ++m) _Pragma("unroll") for (int k = 0; k < 2; ++k) dst[m][k] = *(const LAS bf16x8*)(lds + PG8_SA(b, h) + aoff + m * 2048 + k * 1024); } while (0)
; #define PG8_LDB(dst, b, h) do { _Pragma("unroll") for (int n = 0; n < 2; ++n) _Pragma("unroll") for (int k = 0; k < 2; ++k) dst[n][k] = *(const LAS bf16x8*)(lds + PG8_SB(b, h) + boff + n * 2048 + k * 1024); } while (0)
; #define PG8_MMA(ai, bj, At, Bt) do { __builtin_amdgcn_s_setprio(1); _Pragma("unroll") for (int m = 0; m < 4; ++m) _Pragma("unroll") for (int n = 0; n < 2; ++n) _Pragma("unroll") for (int k = 0; k < 2; ++k) \
;         acc[ai][bj][m][n] = __builtin_amdgcn_mfma_f32_16x16x32_bf16(Bt[n][k], At[m][k], acc[ai][bj][m][n], 0, 0, 0); __builtin_amdgcn_s_setprio(0); } while (0)
; #define PG8_WAIT_V(n) asm volatile("s_waitcnt vmcnt(" #n ")" ::: "memory")
; #define PG8_WAIT_L(n) asm volatile("s_waitcnt lgkmcnt(" #n ")" ::: "memory")
; #define PG8_BAR __builtin_amdgcn_s_barrier()
; #define PG8_SCHED __builtin_amdgcn_sched_barrier(0)
; template <class Epi>
; __device__ __forceinline__ void gemm_phase(const int TID, const int BID, LAS unsigned char* lds, const Gemm g, const StaticOrder& S, const Epi& E) {
;     ...
;             PG8_WAIT_V(6); PG8_BAR; PG8_MMA(1, 1, At, B1); PG8_BAR;
;             PG8_LDB(B0, 1, 0); PG8_SCHED; PG8_LDA(At, 1, 0); PG8_STAGE(PG8_SA(0, 1), a2 + hstepA, voffA);
;             PG8_WAIT_L(8); PG8_BAR; PG8_WAIT_L(0); PG8_MMA(0, 0, At, B0); PG8_BAR; PG8_SCHED;
;             PG8_LDB(B1, 1, 1); PG8_STAGE(PG8_SB(1, 0), b3, voffB);
;             PG8_BAR; PG8_WAIT_L(0); PG8_MMA(0, 1, At, B1); PG8_BAR;
;             PG8_LDA(At, 1, 1); PG8_STAGE(PG8_SA(1, 0), a3, voffA);
;             PG8_BAR; PG8_WAIT_L(0); PG8_MMA(1, 0, At, B0); PG8_BAR; PG8_SCHED;
	s_add_u32 s74, s28, 0x80000
	s_addc_u32 s75, s29, 0
	s_mov_b32 m0, s49
	v_lshl_add_u64 v[134:135], s[74:75], 0, v[160:161]
	global_load_lds_dwordx4 v[134:135], off
	s_mov_b32 m0, s50
	v_lshl_add_u64 v[134:135], s[74:75], 0, v[128:129]
	global_load_lds_dwordx4 v[134:135], off
	s_waitcnt vmcnt(6)
	s_barrier
	s_setprio 1
	v_mfma_f32_16x16x32_bf16 v[52:55], v[216:219], v[166:169], v[52:55]
	v_mfma_f32_16x16x32_bf16 v[48:51], v[224:227], v[166:169], v[48:51]
	v_mfma_f32_16x16x32_bf16 v[36:39], v[216:219], v[174:177], v[36:39]
	v_mfma_f32_16x16x32_bf16 v[32:35], v[224:227], v[174:177], v[32:35]
	v_mfma_f32_16x16x32_bf16 v[20:23], v[216:219], v[182:185], v[20:23]
	v_mfma_f32_16x16x32_bf16 v[16:19], v[224:227], v[182:185], v[16:19]
	v_mfma_f32_16x16x32_bf16 v[4:7], v[216:219], v[208:211], v[4:7]
	v_mfma_f32_16x16x32_bf16 v[0:3], v[224:227], v[208:211], v[0:3]
	v_mfma_f32_16x16x32_bf16 v[52:55], v[220:223], v[170:173], v[52:55]
	v_mfma_f32_16x16x32_bf16 v[48:51], v[228:231], v[170:173], v[48:51]
	v_mfma_f32_16x16x32_bf16 v[36:39], v[220:223], v[178:181], v[36:39]
	v_mfma_f32_16x16x32_bf16 v[32:35], v[228:231], v[178:181], v[32:35]
	v_mfma_f32_16x16x32_bf16 v[20:23], v[220:223], v[196:199], v[20:23]
	v_mfma_f32_16x16x32_bf16 v[16:19], v[228:231], v[196:199], v[16:19]
	v_mfma_f32_16x16x32_bf16 v[4:7], v[220:223], v[212:215], v[4:7]
	v_mfma_f32_16x16x32_bf16 v[0:3], v[228:231], v[212:215], v[0:3]
	s_setprio 0
	v_add_u32_e32 v154, s38, v147
	s_barrier
	ds_read_b128 v[134:137], v154
	ds_read_b128 v[138:141], v154 offset:1024
	ds_read_b128 v[150:153], v154 offset:2048
	ds_read_b128 v[154:157], v154 offset:3072
	s_add_u32 s30, s30, 0x80000
	s_addc_u32 s31, s31, 0
	s_mov_b32 m0, s51
	v_lshl_add_u64 v[216:217], s[30:31], 0, v[160:161]
	ds_read_b128 v[166:169], v149 offset:32768
	ds_read_b128 v[170:173], v149 offset:33792
	ds_read_b128 v[174:177], v149 offset:34816
	ds_read_b128 v[178:181], v149 offset:35840
	ds_read_b128 v[182:185], v149 offset:36864
	ds_read_b128 v[196:199], v149 offset:37888
	ds_read_b128 v[208:211], v149 offset:38912
	ds_read_b128 v[212:215], v149 offset:39936
	global_load_lds_dwordx4 v[216:217], off
	s_mov_b32 m0, s52
	v_lshl_add_u64 v[216:217], s[30:31], 0, v[128:129]
	global_load_lds_dwordx4 v[216:217], off
	s_waitcnt lgkmcnt(8)
	s_barrier
	s_waitcnt lgkmcnt(0)
	s_setprio 1
	v_mfma_f32_16x16x32_bf16 v[124:127], v[134:137], v[166:169], v[124:127]
	v_mfma_f32_16x16x32_bf16 v[120:123], v[150:153], v[166:169], v[120:123]
	v_mfma_f32_16x16x32_bf16 v[108:111], v[134:137], v[174:177], v[108:111]
	v_mfma_f32_16x16x32_bf16 v[104:107], v[150:153], v[174:177], v[104:107]
	v_mfma_f32_16x16x32_bf16 v[92:95], v[134:137], v[182:185], v[92:95]
	v_mfma_f32_16x16x32_bf16 v[88:91], v[150:153], v[182:185], v[88:91]
	v_mfma_f32_16x16x32_bf16 v[76:79], v[134:137], v[208:211], v[76:79]
	v_mfma_f32_16x16x32_bf16 v[72:75], v[150:153], v[208:211], v[72:75]
	v_mfma_f32_16x16x32_bf16 v[124:127], v[138:141], v[170:173], v[124:127]
	v_mfma_f32_16x16x32_bf16 v[120:123], v[154:157], v[170:173], v[120:123]
	v_mfma_f32_16x16x32_bf16 v[108:111], v[138:141], v[178:181], v[108:111]
	v_mfma_f32_16x16x32_bf16 v[104:107], v[154:157], v[178:181], v[104:107]
	v_mfma_f32_16x16x32_bf16 v[92:95], v[138:141], v[196:199], v[92:95]
	v_mfma_f32_16x16x32_bf16 v[88:91], v[154:157], v[196:199], v[88:91]
	v_mfma_f32_16x16x32_bf16 v[76:79], v[138:141], v[212:215], v[76:79]
	v_mfma_f32_16x16x32_bf16 v[72:75], v[154:157], v[212:215], v[72:75]
	s_setprio 0
	s_barrier
	s_mov_b32 m0, s53
	v_add_u32_e32 v228, s39, v147
	v_lshl_add_u64 v[158:159], v[158:159], 0, s[90:91]
	ds_read_b128 v[216:219], v228
	ds_read_b128 v[220:223], v228 offset:1024
	ds_read_b128 v[224:227], v228 offset:2048
	ds_read_b128 v[228:231], v228 offset:3072
	global_load_lds_dwordx4 v[158:159], off
	s_mov_b32 m0, s54
	v_lshl_add_u64 v[158:159], v[200:201], 0, s[90:91]
	global_load_lds_dwordx4 v[158:159], off
	s_barrier
	s_waitcnt lgkmcnt(0)
	s_setprio 1
	v_mfma_f32_16x16x32_bf16 v[116:119], v[216:219], v[166:169], v[116:119]
	v_mfma_f32_16x16x32_bf16 v[112:115], v[224:227], v[166:169], v[112:115]
	v_mfma_f32_16x16x32_bf16 v[100:103], v[216:219], v[174:177], v[100:103]
	v_mfma_f32_16x16x32_bf16 v[96:99], v[224:227], v[174:177], v[96:99]
	v_mfma_f32_16x16x32_bf16 v[84:87], v[216:219], v[182:185], v[84:87]
	v_mfma_f32_16x16x32_bf16 v[80:83], v[224:227], v[182:185], v[80:83]
	v_mfma_f32_16x16x32_bf16 v[68:71], v[216:219], v[208:211], v[68:71]
	v_mfma_f32_16x16x32_bf16 v[64:67], v[224:227], v[208:211], v[64:67]
	v_mfma_f32_16x16x32_bf16 v[116:119], v[220:223], v[170:173], v[116:119]
	v_mfma_f32_16x16x32_bf16 v[112:115], v[228:231], v[170:173], v[112:115]
	v_mfma_f32_16x16x32_bf16 v[100:103], v[220:223], v[178:181], v[100:103]
	v_mfma_f32_16x16x32_bf16 v[96:99], v[228:231], v[178:181], v[96:99]
	v_mfma_f32_16x16x32_bf16 v[84:87], v[220:223], v[196:199], v[84:87]
	v_mfma_f32_16x16x32_bf16 v[80:83], v[228:231], v[196:199], v[80:83]
	v_mfma_f32_16x16x32_bf16 v[68:71], v[220:223], v[212:215], v[68:71]
	v_mfma_f32_16x16x32_bf16 v[64:67], v[228:231], v[212:215], v[64:67]
	s_setprio 0
	s_mov_b32 m0, s55
	v_lshl_add_u64 v[158:159], v[232:233], 0, s[90:91]
	s_barrier
	ds_read_b128 v[166:169], v149 offset:49152
	ds_read_b128 v[170:173], v149 offset:50176
	ds_read_b128 v[174:177], v149 offset:51200
	ds_read_b128 v[178:181], v149 offset:52224
	ds_read_b128 v[182:185], v149 offset:53248
	ds_read_b128 v[196:199], v149 offset:54272
	ds_read_b128 v[208:211], v149 offset:55296
	ds_read_b128 v[212:215], v149 offset:56320
	global_load_lds_dwordx4 v[158:159], off
	s_mov_b32 m0, s56
	v_lshl_add_u64 v[158:159], v[234:235], 0, s[90:91]
	global_load_lds_dwordx4 v[158:159], off
	s_barrier
; __device__ __forceinline__ float rinv_st(stat_t s, float invn) { return rsqrtf((float)((double)s * (1.0 / 4294967296.0)) * invn + 1e-6f); }
; #define PG8_STAGE(bufoff, gbase, voff) do { _Pragma("unroll") for (int _i = 0; _i < 2; ++_i) \
;         __builtin_amdgcn_global_load_lds((const unsigned*)((const char*)(gbase) + (voff)[_i]), (LAS unsigned*)(lds + (bufoff) + ldsw + _i * 8192), 16, 0, 0); } while (0)
; #define PG8_MMA(ai, bj, At, Bt) do { __builtin_amdgcn_s_setprio(1); _Pragma("unroll") for (int m = 0; m < 4; ++m) _Pragma("unroll") for (int n = 0; n < 2; ++n) _Pragma("unroll") for (int k = 0; k < 2; ++k) \
;         acc[ai][bj][m][n] = __builtin_amdgcn_mfma_f32_16x16x32_bf16(Bt[n][k], At[m][k], acc[ai][bj][m][n], 0, 0, 0); __builtin_amdgcn_s_setprio(0); } while (0)
; #define PG8_WAIT_V(n) asm volatile("s_waitcnt vmcnt(" #n ")" ::: "memory")
; #define PG8_WAIT_L(n) asm volatile("s_waitcnt lgkmcnt(" #n ")" ::: "memory")
; #define PG8_BAR __builtin_amdgcn_s_barrier()
; #define PG8_SCHED __builtin_amdgcn_sched_barrier(0)
; template <class Epi>
; __device__ __forceinline__ void gemm_phase(const int TID, const int BID, LAS unsigned char* lds, const Gemm g, const StaticOrder& S, const Epi& E) {
;     ...
;             PG8_BAR; PG8_WAIT_L(0); PG8_MMA(1, 0, At, B0); PG8_BAR; PG8_SCHED;
;             PG8_STAGE(PG8_SB(1, 1), b3 + hstepB, voffB);
;             PG8_WAIT_V(6); PG8_BAR; PG8_MMA(1, 1, At, B1); PG8_BAR;
;         }
;     __device__ __forceinline__ void operator()(const f32x4 (&acc)[2][2][4][2], const Unit& u, int wr, int wc, int fr, int fq) const {
;     ...
;         for (int ai = 0; ai < 2; ++ai)
; #pragma unroll
;             for (int m = 0; m < 4; ++m) {
;                 const int row = row0 + ai * HALF + m * 16; const float r = rinv_st(stats[row], 1.0f / 2048.0f);
;                 float* rowp = raw + (size_t)row * 256 + col0;
; #pragma unroll
;                 for (int bj = 0; bj < 2; ++bj)
; #pragma unroll
;                     for (int n = 0; n < 2; ++n) *(f32x4*)(rowp + bj * HALF + n * 16) = acc[ai][bj][m][n] * r;
	s_waitcnt lgkmcnt(0)
	s_setprio 1
	v_mfma_f32_16x16x32_bf16 v[60:63], v[134:137], v[166:169], v[60:63]
	v_mfma_f32_16x16x32_bf16 v[56:59], v[150:153], v[166:169], v[56:59]
	v_mfma_f32_16x16x32_bf16 v[44:47], v[134:137], v[174:177], v[44:47]
	v_mfma_f32_16x16x32_bf16 v[40:43], v[150:153], v[174:177], v[40:43]
	v_mfma_f32_16x16x32_bf16 v[28:31], v[134:137], v[182:185], v[28:31]
	v_mfma_f32_16x16x32_bf16 v[24:27], v[150:153], v[182:185], v[24:27]
	v_mfma_f32_16x16x32_bf16 v[12:15], v[134:137], v[208:211], v[12:15]
	v_mfma_f32_16x16x32_bf16 v[8:11], v[150:153], v[208:211], v[8:11]
	v_mfma_f32_16x16x32_bf16 v[60:63], v[138:141], v[170:173], v[60:63]
	v_mfma_f32_16x16x32_bf16 v[56:59], v[154:157], v[170:173], v[56:59]
	v_mfma_f32_16x16x32_bf16 v[44:47], v[138:141], v[178:181], v[44:47]
	v_mfma_f32_16x16x32_bf16 v[40:43], v[154:157], v[178:181], v[40:43]
	v_mfma_f32_16x16x32_bf16 v[28:31], v[138:141], v[196:199], v[28:31]
	v_mfma_f32_16x16x32_bf16 v[24:27], v[154:157], v[196:199], v[24:27]
	v_mfma_f32_16x16x32_bf16 v[12:15], v[138:141], v[212:215], v[12:15]
	v_mfma_f32_16x16x32_bf16 v[8:11], v[154:157], v[212:215], v[8:11]
	s_setprio 0
	s_barrier
	s_add_u32 s28, s28, 0x80080
	s_addc_u32 s29, s29, 0
	s_mov_b32 m0, s57
	v_lshl_add_u64 v[134:135], s[28:29], 0, v[160:161]
	global_load_lds_dwordx4 v[134:135], off
	s_mov_b32 m0, s58
	v_lshl_add_u64 v[134:135], s[28:29], 0, v[128:129]
	global_load_lds_dwordx4 v[134:135], off
	s_waitcnt vmcnt(6)
	s_barrier
	s_setprio 1
	v_mfma_f32_16x16x32_bf16 v[52:55], v[216:219], v[166:169], v[52:55]
	v_mfma_f32_16x16x32_bf16 v[48:51], v[224:227], v[166:169], v[48:51]
	v_mfma_f32_16x16x32_bf16 v[36:39], v[216:219], v[174:177], v[36:39]
	v_mfma_f32_16x16x32_bf16 v[32:35], v[224:227], v[174:177], v[32:35]
	v_mfma_f32_16x16x32_bf16 v[20:23], v[216:219], v[182:185], v[20:23]
	v_mfma_f32_16x16x32_bf16 v[16:19], v[224:227], v[182:185], v[16:19]
	v_mfma_f32_16x16x32_bf16 v[4:7], v[216:219], v[208:211], v[4:7]
	v_mfma_f32_16x16x32_bf16 v[0:3], v[224:227], v[208:211], v[0:3]
	v_mfma_f32_16x16x32_bf16 v[52:55], v[220:223], v[170:173], v[52:55]
	v_mfma_f32_16x16x32_bf16 v[48:51], v[228:231], v[170:173], v[48:51]
	v_mfma_f32_16x16x32_bf16 v[36:39], v[220:223], v[178:181], v[36:39]
	v_mfma_f32_16x16x32_bf16 v[32:35], v[228:231], v[178:181], v[32:35]
	v_mfma_f32_16x16x32_bf16 v[20:23], v[220:223], v[196:199], v[20:23]
	v_mfma_f32_16x16x32_bf16 v[16:19], v[228:231], v[196:199], v[16:19]
	v_mfma_f32_16x16x32_bf16 v[4:7], v[220:223], v[212:215], v[4:7]
	v_mfma_f32_16x16x32_bf16 v[0:3], v[228:231], v[212:215], v[0:3]
	s_setprio 0
	s_add_i32 s66, s66, 2
	s_add_u32 s26, s26, 0x100
	s_addc_u32 s27, s27, 0
	s_add_u32 s63, s63, 0x100
	s_addc_u32 s64, s64, 0
	s_cmp_gt_u32 s66, 5
	s_cbranch_scc0 .Lrot_822
	s_barrier
	v_lshl_add_u32 v140, s24, 8, v145
	v_ashrrev_i32_e32 v141, 31, v140
	v_lshl_add_u64 v[136:137], v[140:141], 3, s[10:11]
	global_load_dwordx2 v[138:139], v[136:137], off
	global_load_dwordx2 v[208:209], v[136:137], off offset:128
	global_load_dwordx2 v[210:211], v[136:137], off offset:256
	global_load_dwordx2 v[212:213], v[136:137], off offset:384
	global_load_dwordx2 v[214:215], v[136:137], off offset:1024
	global_load_dwordx2 v[216:217], v[136:137], off offset:1152
	global_load_dwordx2 v[218:219], v[136:137], off offset:1280
	global_load_dwordx2 v[220:221], v[136:137], off offset:1408
	v_lshl_or_b32 v134, s60, 8, v148
	v_ashrrev_i32_e32 v135, 31, v134
	s_mov_b32 s15, 0x20000
	s_mov_b64 s[26:27], 0x20000
	s_mov_b32 s60, s14
	s_mov_b32 s24, s16
	s_mov_b64 s[28:29], s[22:23]
	s_waitcnt vmcnt(0)
	v_cvt_f64_u32_e32 v[150:151], v139
	v_ldexp_f64 v[150:151], v[150:151], 32
	v_cvt_f64_u32_e32 v[138:139], v138
	v_add_f64 v[138:139], v[150:151], v[138:139]
	v_ldexp_f64 v[138:139], v[138:139], s93
	v_cvt_f32_f64_e32 v138, v[138:139]
	v_fmamk_f32 v138, v138, 0x3a000000, v189
	v_cmp_gt_f32_e32 vcc, s78, v138
	v_mul_f32_e32 v139, 0x4b800000, v138
	s_nop 0
	v_cndmask_b32_e32 v138, v138, v139, vcc
	v_rsq_f32_e32 v138, v138
	s_nop 0
	v_mul_f32_e32 v139, 0x45800000, v138
	v_cndmask_b32_e32 v150, v138, v139, vcc
	v_lshlrev_b64 v[138:139], 10, v[140:141]
	v_lshl_add_u64 v[152:153], s[12:13], 0, v[138:139]
	v_lshlrev_b64 v[138:139], 2, v[134:135]
	v_lshl_add_u64 v[134:135], v[152:153], 0, v[138:139]
	v_pk_mul_f32 v[114:115], v[114:115], v[150:151] op_sel_hi:[1,0]
	v_pk_mul_f32 v[112:113], v[112:113], v[150:151] op_sel_hi:[1,0]
	global_store_dwordx4 v[134:135], v[112:115], off offset:576
	v_pk_mul_f32 v[126:127], v[126:127], v[150:151] op_sel_hi:[1,0]
	v_pk_mul_f32 v[124:125], v[124:125], v[150:151] op_sel_hi:[1,0]
	v_or_b32_e32 v112, 16, v140
	v_pk_mul_f32 v[122:123], v[122:123], v[150:151] op_sel_hi:[1,0]
	v_pk_mul_f32 v[120:121], v[120:121], v[150:151] op_sel_hi:[1,0]
	v_pk_mul_f32 v[118:119], v[118:119], v[150:151] op_sel_hi:[1,0]
	v_pk_mul_f32 v[116:117], v[116:117], v[150:151] op_sel_hi:[1,0]
	v_ashrrev_i32_e32 v113, 31, v112
	global_store_dwordx4 v[134:135], v[124:127], off
	global_store_dwordx4 v[134:135], v[120:123], off offset:64
	global_store_dwordx4 v[134:135], v[116:119], off offset:512
	v_lshl_add_u64 v[114:115], v[112:113], 3, s[10:11]
	s_nop 1
	v_mov_b64_e32 v[114:115], v[208:209]
	v_lshlrev_b64 v[112:113], 10, v[112:113]
	v_lshl_add_u64 v[112:113], s[12:13], 0, v[112:113]
	v_lshl_add_u64 v[112:113], v[112:113], 0, v[138:139]
	v_cvt_f64_u32_e32 v[116:117], v115
	v_ldexp_f64 v[116:117], v[116:117], 32
	v_cvt_f64_u32_e32 v[114:115], v114
	v_add_f64 v[114:115], v[116:117], v[114:115]
	v_ldexp_f64 v[114:115], v[114:115], s93
	v_cvt_f32_f64_e32 v114, v[114:115]
	v_fmamk_f32 v114, v114, 0x3a000000, v189
	v_cmp_gt_f32_e32 vcc, s78, v114
; __device__ __forceinline__ float rinv_st(stat_t s, float invn) { return rsqrtf((float)((double)s * (1.0 / 4294967296.0)) * invn + 1e-6f); }
;     __device__ __forceinline__ void operator()(const f32x4 (&acc)[2][2][4][2], const Unit& u, int wr, int wc, int fr, int fq) const {
;     ...
;         for (int ai = 0; ai < 2; ++ai)
; #pragma unroll
;             for (int m = 0; m < 4; ++m) {
;                 const int row = row0 + ai * HALF + m * 16; const float r = rinv_st(stats[row], 1.0f / 2048.0f);
;                 float* rowp = raw + (size_t)row * 256 + col0;
; #pragma unroll
;                 for (int bj = 0; bj < 2; ++bj)
; #pragma unroll
;                     for (int n = 0; n < 2; ++n) *(f32x4*)(rowp + bj * HALF + n * 16) = acc[ai][bj][m][n] * r;
	v_mul_f32_e32 v115, 0x4b800000, v114
	s_nop 0
	v_cndmask_b32_e32 v114, v114, v115, vcc
	v_rsq_f32_e32 v114, v114
	s_nop 0
	v_mul_f32_e32 v115, 0x45800000, v114
	v_cndmask_b32_e32 v114, v114, v115, vcc
	v_pk_mul_f32 v[98:99], v[98:99], v[114:115] op_sel_hi:[1,0]
	v_pk_mul_f32 v[96:97], v[96:97], v[114:115] op_sel_hi:[1,0]
	global_store_dwordx4 v[112:113], v[96:99], off offset:576
	v_pk_mul_f32 v[110:111], v[110:111], v[114:115] op_sel_hi:[1,0]
	v_pk_mul_f32 v[108:109], v[108:109], v[114:115] op_sel_hi:[1,0]
	v_or_b32_e32 v96, 32, v140
	v_pk_mul_f32 v[106:107], v[106:107], v[114:115] op_sel_hi:[1,0]
	v_pk_mul_f32 v[104:105], v[104:105], v[114:115] op_sel_hi:[1,0]
	v_pk_mul_f32 v[102:103], v[102:103], v[114:115] op_sel_hi:[1,0]
	v_pk_mul_f32 v[100:101], v[100:101], v[114:115] op_sel_hi:[1,0]
	v_ashrrev_i32_e32 v97, 31, v96
	global_store_dwordx4 v[112:113], v[108:111], off
	global_store_dwordx4 v[112:113], v[104:107], off offset:64
	global_store_dwordx4 v[112:113], v[100:103], off offset:512
	v_lshl_add_u64 v[98:99], v[96:97], 3, s[10:11]
	s_nop 1
	v_mov_b64_e32 v[98:99], v[210:211]
	v_lshlrev_b64 v[96:97], 10, v[96:97]
	v_lshl_add_u64 v[96:97], s[12:13], 0, v[96:97]
	v_lshl_add_u64 v[96:97], v[96:97], 0, v[138:139]
	v_cvt_f64_u32_e32 v[100:101], v99
	v_ldexp_f64 v[100:101], v[100:101], 32
	v_cvt_f64_u32_e32 v[98:99], v98
	v_add_f64 v[98:99], v[100:101], v[98:99]
	v_ldexp_f64 v[98:99], v[98:99], s93
	v_cvt_f32_f64_e32 v98, v[98:99]
	v_fmamk_f32 v98, v98, 0x3a000000, v189
	v_cmp_gt_f32_e32 vcc, s78, v98
	v_mul_f32_e32 v99, 0x4b800000, v98
	s_nop 0
	v_cndmask_b32_e32 v98, v98, v99, vcc
	v_rsq_f32_e32 v98, v98
	s_nop 0
	v_mul_f32_e32 v99, 0x45800000, v98
	v_cndmask_b32_e32 v98, v98, v99, vcc
	v_pk_mul_f32 v[82:83], v[82:83], v[98:99] op_sel_hi:[1,0]
	v_pk_mul_f32 v[80:81], v[80:81], v[98:99] op_sel_hi:[1,0]
	global_store_dwordx4 v[96:97], v[80:83], off offset:576
	v_pk_mul_f32 v[94:95], v[94:95], v[98:99] op_sel_hi:[1,0]
	v_pk_mul_f32 v[92:93], v[92:93], v[98:99] op_sel_hi:[1,0]
	v_or_b32_e32 v80, 48, v140
	v_pk_mul_f32 v[90:91], v[90:91], v[98:99] op_sel_hi:[1,0]
	v_pk_mul_f32 v[88:89], v[88:89], v[98:99] op_sel_hi:[1,0]
	v_pk_mul_f32 v[86:87], v[86:87], v[98:99] op_sel_hi:[1,0]
	v_pk_mul_f32 v[84:85], v[84:85], v[98:99] op_sel_hi:[1,0]
	v_ashrrev_i32_e32 v81, 31, v80
	global_store_dwordx4 v[96:97], v[92:95], off
	global_store_dwordx4 v[96:97], v[88:91], off offset:64
	global_store_dwordx4 v[96:97], v[84:87], off offset:512
	v_lshl_add_u64 v[82:83], v[80:81], 3, s[10:11]
	s_nop 1
	v_mov_b64_e32 v[82:83], v[212:213]
	v_lshlrev_b64 v[80:81], 10, v[80:81]
	v_lshl_add_u64 v[80:81], s[12:13], 0, v[80:81]
	v_lshl_add_u64 v[80:81], v[80:81], 0, v[138:139]
	v_cvt_f64_u32_e32 v[84:85], v83
	v_ldexp_f64 v[84:85], v[84:85], 32
	v_cvt_f64_u32_e32 v[82:83], v82
	v_add_f64 v[82:83], v[84:85], v[82:83]
	v_ldexp_f64 v[82:83], v[82:83], s93
	v_cvt_f32_f64_e32 v82, v[82:83]
	v_fmamk_f32 v82, v82, 0x3a000000, v189
	v_cmp_gt_f32_e32 vcc, s78, v82
	v_mul_f32_e32 v83, 0x4b800000, v82
	s_nop 0
	v_cndmask_b32_e32 v82, v82, v83, vcc
	v_rsq_f32_e32 v82, v82
	s_nop 0
	v_mul_f32_e32 v83, 0x45800000, v82
	v_cndmask_b32_e32 v82, v82, v83, vcc
	v_pk_mul_f32 v[78:79], v[78:79], v[82:83] op_sel_hi:[1,0]
	v_pk_mul_f32 v[76:77], v[76:77], v[82:83] op_sel_hi:[1,0]
	v_pk_mul_f32 v[74:75], v[74:75], v[82:83] op_sel_hi:[1,0]
	v_pk_mul_f32 v[72:73], v[72:73], v[82:83] op_sel_hi:[1,0]
	v_pk_mul_f32 v[70:71], v[70:71], v[82:83] op_sel_hi:[1,0]
	v_pk_mul_f32 v[68:69], v[68:69], v[82:83] op_sel_hi:[1,0]
	v_pk_mul_f32 v[66:67], v[66:67], v[82:83] op_sel_hi:[1,0]
	v_pk_mul_f32 v[64:65], v[64:65], v[82:83] op_sel_hi:[1,0]
	global_store_dwordx4 v[80:81], v[76:79], off
	global_store_dwordx4 v[80:81], v[72:75], off offset:64
	global_store_dwordx4 v[80:81], v[68:71], off offset:512
	global_store_dwordx4 v[80:81], v[64:67], off offset:576
	s_nop 1
	v_mov_b64_e32 v[64:65], v[214:215]
	v_cvt_f64_u32_e32 v[66:67], v65
	v_ldexp_f64 v[66:67], v[66:67], 32
	v_cvt_f64_u32_e32 v[64:65], v64
	v_add_f64 v[64:65], v[66:67], v[64:65]
	v_ldexp_f64 v[64:65], v[64:65], s93
	v_cvt_f32_f64_e32 v64, v[64:65]
	v_fmamk_f32 v64, v64, 0x3a000000, v189
	v_cmp_gt_f32_e32 vcc, s78, v64
	v_mul_f32_e32 v65, 0x4b800000, v64
	v_lshl_add_u64 v[66:67], v[134:135], 0, s[26:27]
	v_cndmask_b32_e32 v64, v64, v65, vcc
	v_rsq_f32_e32 v64, v64
	s_mov_b64 s[26:27], 0x24000
	v_mul_f32_e32 v65, 0x45800000, v64
	v_cndmask_b32_e32 v64, v64, v65, vcc
	v_add_co_u32_e32 v68, vcc, s15, v134
	v_pk_mul_f32 v[62:63], v[62:63], v[64:65] op_sel_hi:[1,0]
	v_pk_mul_f32 v[60:61], v[60:61], v[64:65] op_sel_hi:[1,0]
	v_addc_co_u32_e32 v69, vcc, 0, v135, vcc
	v_pk_mul_f32 v[58:59], v[58:59], v[64:65] op_sel_hi:[1,0]
	v_pk_mul_f32 v[56:57], v[56:57], v[64:65] op_sel_hi:[1,0]
; __device__ __forceinline__ float rinv_st(stat_t s, float invn) { return rsqrtf((float)((double)s * (1.0 / 4294967296.0)) * invn + 1e-6f); }
; #define PG8_WAIT_V(n) asm volatile("s_waitcnt vmcnt(" #n ")" ::: "memory")
; #define PG8_BAR __builtin_amdgcn_s_barrier()
; template <class Epi>
; __device__ __forceinline__ void gemm_phase(const int TID, const int BID, LAS unsigned char* lds, const Gemm g, const StaticOrder& S, const Epi& E) {
;     ...
;     PG8_WAIT_V(0);
;     if (wr == 0) PG8_BAR;
;     PG8_BAR;
;     __device__ __forceinline__ void operator()(const f32x4 (&acc)[2][2][4][2], const Unit& u, int wr, int wc, int fr, int fq) const {
;     ...
;         for (int ai = 0; ai < 2; ++ai)
; #pragma unroll
;             for (int m = 0; m < 4; ++m) {
;                 const int row = row0 + ai * HALF + m * 16; const float r = rinv_st(stats[row], 1.0f / 2048.0f);
;                 float* rowp = raw + (size_t)row * 256 + col0;
; #pragma unroll
;                 for (int bj = 0; bj < 2; ++bj)
; #pragma unroll
;                     for (int n = 0; n < 2; ++n) *(f32x4*)(rowp + bj * HALF + n * 16) = acc[ai][bj][m][n] * r;
	v_pk_mul_f32 v[54:55], v[54:55], v[64:65] op_sel_hi:[1,0]
	v_pk_mul_f32 v[52:53], v[52:53], v[64:65] op_sel_hi:[1,0]
	v_pk_mul_f32 v[50:51], v[50:51], v[64:65] op_sel_hi:[1,0]
	v_pk_mul_f32 v[48:49], v[48:49], v[64:65] op_sel_hi:[1,0]
	global_store_dwordx4 v[68:69], v[60:63], off
	global_store_dwordx4 v[66:67], v[56:59], off offset:64
	global_store_dwordx4 v[66:67], v[52:55], off offset:512
	global_store_dwordx4 v[66:67], v[48:51], off offset:576
	s_nop 1
	v_mov_b64_e32 v[48:49], v[216:217]
	s_mov_b32 s15, 0x24000
	v_cvt_f64_u32_e32 v[50:51], v49
	v_ldexp_f64 v[50:51], v[50:51], 32
	v_cvt_f64_u32_e32 v[48:49], v48
	v_add_f64 v[48:49], v[50:51], v[48:49]
	v_ldexp_f64 v[48:49], v[48:49], s93
	v_cvt_f32_f64_e32 v48, v[48:49]
	v_fmamk_f32 v48, v48, 0x3a000000, v189
	v_cmp_gt_f32_e32 vcc, s78, v48
	v_mul_f32_e32 v49, 0x4b800000, v48
	v_lshl_add_u64 v[50:51], v[134:135], 0, s[26:27]
	v_cndmask_b32_e32 v48, v48, v49, vcc
	v_rsq_f32_e32 v48, v48
	s_mov_b64 s[26:27], 0x28000
	v_mul_f32_e32 v49, 0x45800000, v48
	v_cndmask_b32_e32 v48, v48, v49, vcc
	v_add_co_u32_e32 v52, vcc, s15, v134
	v_pk_mul_f32 v[46:47], v[46:47], v[48:49] op_sel_hi:[1,0]
	v_pk_mul_f32 v[44:45], v[44:45], v[48:49] op_sel_hi:[1,0]
	v_addc_co_u32_e32 v53, vcc, 0, v135, vcc
	v_pk_mul_f32 v[42:43], v[42:43], v[48:49] op_sel_hi:[1,0]
	v_pk_mul_f32 v[40:41], v[40:41], v[48:49] op_sel_hi:[1,0]
	v_pk_mul_f32 v[38:39], v[38:39], v[48:49] op_sel_hi:[1,0]
	v_pk_mul_f32 v[36:37], v[36:37], v[48:49] op_sel_hi:[1,0]
	v_pk_mul_f32 v[34:35], v[34:35], v[48:49] op_sel_hi:[1,0]
	v_pk_mul_f32 v[32:33], v[32:33], v[48:49] op_sel_hi:[1,0]
	global_store_dwordx4 v[52:53], v[44:47], off
	global_store_dwordx4 v[50:51], v[40:43], off offset:64
	global_store_dwordx4 v[50:51], v[36:39], off offset:512
	global_store_dwordx4 v[50:51], v[32:35], off offset:576
	s_nop 1
	v_mov_b64_e32 v[32:33], v[218:219]
	s_mov_b32 s15, 0x28000
	v_cvt_f64_u32_e32 v[34:35], v33
	v_ldexp_f64 v[34:35], v[34:35], 32
	v_cvt_f64_u32_e32 v[32:33], v32
	v_add_f64 v[32:33], v[34:35], v[32:33]
	v_ldexp_f64 v[32:33], v[32:33], s93
	v_cvt_f32_f64_e32 v32, v[32:33]
	v_fmamk_f32 v32, v32, 0x3a000000, v189
	v_cmp_gt_f32_e32 vcc, s78, v32
	v_mul_f32_e32 v33, 0x4b800000, v32
	v_lshl_add_u64 v[34:35], v[134:135], 0, s[26:27]
	v_cndmask_b32_e32 v32, v32, v33, vcc
	v_rsq_f32_e32 v32, v32
	s_mov_b64 s[26:27], 0x2c000
	v_mul_f32_e32 v33, 0x45800000, v32
	v_cndmask_b32_e32 v32, v32, v33, vcc
	v_add_co_u32_e32 v36, vcc, s15, v134
	v_pk_mul_f32 v[30:31], v[30:31], v[32:33] op_sel_hi:[1,0]
	v_pk_mul_f32 v[28:29], v[28:29], v[32:33] op_sel_hi:[1,0]
	v_addc_co_u32_e32 v37, vcc, 0, v135, vcc
	v_pk_mul_f32 v[26:27], v[26:27], v[32:33] op_sel_hi:[1,0]
	v_pk_mul_f32 v[24:25], v[24:25], v[32:33] op_sel_hi:[1,0]
	v_pk_mul_f32 v[22:23], v[22:23], v[32:33] op_sel_hi:[1,0]
	v_pk_mul_f32 v[20:21], v[20:21], v[32:33] op_sel_hi:[1,0]
	v_pk_mul_f32 v[18:19], v[18:19], v[32:33] op_sel_hi:[1,0]
	v_pk_mul_f32 v[16:17], v[16:17], v[32:33] op_sel_hi:[1,0]
	global_store_dwordx4 v[36:37], v[28:31], off
	global_store_dwordx4 v[34:35], v[24:27], off offset:64
	global_store_dwordx4 v[34:35], v[20:23], off offset:512
	global_store_dwordx4 v[34:35], v[16:19], off offset:576
	s_nop 1
	v_mov_b64_e32 v[16:17], v[220:221]
	s_mov_b32 s15, 0x2c000
	v_cvt_f64_u32_e32 v[18:19], v17
	v_ldexp_f64 v[18:19], v[18:19], 32
	v_cvt_f64_u32_e32 v[16:17], v16
	v_add_f64 v[16:17], v[18:19], v[16:17]
	v_ldexp_f64 v[16:17], v[16:17], s93
	v_cvt_f32_f64_e32 v16, v[16:17]
	v_fmamk_f32 v16, v16, 0x3a000000, v189
	v_cmp_gt_f32_e32 vcc, s78, v16
	v_mul_f32_e32 v17, 0x4b800000, v16
	v_lshl_add_u64 v[18:19], v[134:135], 0, s[26:27]
	v_cndmask_b32_e32 v16, v16, v17, vcc
	v_rsq_f32_e32 v16, v16
	s_mov_b64 s[26:27], s[20:21]
	v_mul_f32_e32 v17, 0x45800000, v16
	v_cndmask_b32_e32 v16, v16, v17, vcc
	v_add_co_u32_e32 v20, vcc, s15, v134
	v_pk_mul_f32 v[14:15], v[14:15], v[16:17] op_sel_hi:[1,0]
	s_nop 0
	v_addc_co_u32_e32 v21, vcc, 0, v135, vcc
	v_pk_mul_f32 v[12:13], v[12:13], v[16:17] op_sel_hi:[1,0]
	v_pk_mul_f32 v[10:11], v[10:11], v[16:17] op_sel_hi:[1,0]
	v_pk_mul_f32 v[8:9], v[8:9], v[16:17] op_sel_hi:[1,0]
	v_pk_mul_f32 v[6:7], v[6:7], v[16:17] op_sel_hi:[1,0]
	v_pk_mul_f32 v[4:5], v[4:5], v[16:17] op_sel_hi:[1,0]
	v_pk_mul_f32 v[2:3], v[2:3], v[16:17] op_sel_hi:[1,0]
	v_pk_mul_f32 v[0:1], v[0:1], v[16:17] op_sel_hi:[1,0]
	s_and_b64 vcc, exec, s[18:19]
	global_store_dwordx4 v[20:21], v[12:15], off
	global_store_dwordx4 v[18:19], v[8:11], off offset:64
	global_store_dwordx4 v[18:19], v[4:7], off offset:512
	global_store_dwordx4 v[18:19], v[0:3], off offset:576
	s_cbranch_vccz .LBB0_815
	s_waitcnt vmcnt(0)
	s_cmpk_gt_u32 s42, 0xff
	s_cbranch_scc1 .LBB0_805
	s_barrier
	s_branch .LBB0_805

; template <class Epi>
; __device__ __forceinline__ void gemm_phase(const int TID, const int BID, LAS unsigned char* lds, const Gemm g, const StaticOrder& S, const Epi& E) {
;     ...
;     for (;;) {
;         const bool has_next = S.next(ui + 1, nxt);
;         const char* nA = has_next ? (const char*)g.A + (size_t)nxt.pm * tstepA : cA; const char* nB = has_next ? (const char*)g.Bt + (size_t)nxt.pn * tstepB : cB;
;     ...
; #pragma unroll
;         for (int a = 0; a < 2; ++a)
; #pragma unroll
;             for (int b = 0; b < 2; ++b)
; #pragma unroll
;                 for (int m = 0; m < 4; ++m)
; #pragma unroll
;                     for (int n = 0; n < 2; ++n) acc[a][b][m][n] = (f32x4){0.f, 0.f, 0.f, 0.f};
;         cur = nxt; cA = nA; cB = nB; ++ui;
.LBB0_863:
	s_ashr_i32 s23, s22, 31
	s_lshl_b64 s[0:1], s[22:23], 20
	v_cmp_lt_i64_e32 vcc, s[24:25], v[164:165]
	s_add_u32 s24, s84, s0
	s_addc_u32 s25, s85, s1
	s_and_b64 s[0:1], vcc, exec
	s_cselect_b32 s0, s25, s35
	s_cselect_b32 s1, s24, s34
	s_ashr_i32 s21, s20, 31
	s_lshl_b64 s[26:27], s[20:21], 20
	s_add_u32 s26, s41, s26
	s_addc_u32 s27, s42, s27
	s_and_b64 s[38:39], vcc, exec
	s_cselect_b32 s4, s27, s37
	s_cselect_b32 s21, s26, s36
	s_add_u32 s34, s34, 0x80080
	s_addc_u32 s35, s35, 0
	s_add_u32 s23, s36, 0x100
	v_mov_b32_e32 v0, 0
	s_addc_u32 s29, s37, 0
	s_mov_b32 s31, -2
	s_waitcnt lgkmcnt(0)
	v_mov_b32_e32 v1, v0
	v_mov_b32_e32 v2, v0
	v_mov_b32_e32 v3, v0
	v_mov_b32_e32 v4, v0
	v_mov_b32_e32 v5, v0
	v_mov_b32_e32 v6, v0
	v_mov_b32_e32 v7, v0
	v_mov_b32_e32 v24, v0
	v_mov_b32_e32 v25, v0
	v_mov_b32_e32 v26, v0
	v_mov_b32_e32 v27, v0
	v_mov_b32_e32 v28, v0
	v_mov_b32_e32 v29, v0
	v_mov_b32_e32 v30, v0
	v_mov_b32_e32 v31, v0
	v_mov_b32_e32 v48, v0
	v_mov_b32_e32 v49, v0
	v_mov_b32_e32 v50, v0
	v_mov_b32_e32 v51, v0
	v_mov_b32_e32 v52, v0
	v_mov_b32_e32 v53, v0
	v_mov_b32_e32 v54, v0
	v_mov_b32_e32 v55, v0
	v_mov_b32_e32 v64, v0
	v_mov_b32_e32 v65, v0
	v_mov_b32_e32 v66, v0
	v_mov_b32_e32 v67, v0
	v_mov_b32_e32 v68, v0
	v_mov_b32_e32 v69, v0
	v_mov_b32_e32 v70, v0
	v_mov_b32_e32 v71, v0
	v_mov_b32_e32 v16, v0
	v_mov_b32_e32 v17, v0
	v_mov_b32_e32 v18, v0
	v_mov_b32_e32 v19, v0
	v_mov_b32_e32 v20, v0
	v_mov_b32_e32 v21, v0
	v_mov_b32_e32 v22, v0
	v_mov_b32_e32 v23, v0
	v_mov_b32_e32 v40, v0
	v_mov_b32_e32 v41, v0
	v_mov_b32_e32 v42, v0
	v_mov_b32_e32 v43, v0
	v_mov_b32_e32 v44, v0
	v_mov_b32_e32 v45, v0
	v_mov_b32_e32 v46, v0
	v_mov_b32_e32 v47, v0
	v_mov_b32_e32 v56, v0
	v_mov_b32_e32 v57, v0
	v_mov_b32_e32 v58, v0
	v_mov_b32_e32 v59, v0
	v_mov_b32_e32 v60, v0
	v_mov_b32_e32 v61, v0
	v_mov_b32_e32 v62, v0
	v_mov_b32_e32 v63, v0
	v_mov_b32_e32 v72, v0
	v_mov_b32_e32 v73, v0
	v_mov_b32_e32 v74, v0
	v_mov_b32_e32 v75, v0
	v_mov_b32_e32 v76, v0
	v_mov_b32_e32 v77, v0
	v_mov_b32_e32 v78, v0
	v_mov_b32_e32 v79, v0
	v_mov_b32_e32 v80, v0
	v_mov_b32_e32 v81, v0
	v_mov_b32_e32 v82, v0
	v_mov_b32_e32 v83, v0
	v_mov_b32_e32 v84, v0
	v_mov_b32_e32 v85, v0
	v_mov_b32_e32 v86, v0
	v_mov_b32_e32 v87, v0
	v_mov_b32_e32 v96, v0
	v_mov_b32_e32 v97, v0
	v_mov_b32_e32 v98, v0
	v_mov_b32_e32 v99, v0
	v_mov_b32_e32 v100, v0
	v_mov_b32_e32 v101, v0
	v_mov_b32_e32 v102, v0
	v_mov_b32_e32 v103, v0
	v_mov_b32_e32 v112, v0
	v_mov_b32_e32 v113, v0
	v_mov_b32_e32 v114, v0
	v_mov_b32_e32 v115, v0
	v_mov_b32_e32 v116, v0
	v_mov_b32_e32 v117, v0
	v_mov_b32_e32 v118, v0
	v_mov_b32_e32 v119, v0
	v_mov_b32_e32 v128, v0
	v_mov_b32_e32 v129, v0
	v_mov_b32_e32 v130, v0
	v_mov_b32_e32 v131, v0
	v_mov_b32_e32 v132, v0
	v_mov_b32_e32 v133, v0
	v_mov_b32_e32 v134, v0
	v_mov_b32_e32 v135, v0
	v_mov_b32_e32 v88, v0
	v_mov_b32_e32 v89, v0
	v_mov_b32_e32 v90, v0
	v_mov_b32_e32 v91, v0
	v_mov_b32_e32 v92, v0
	v_mov_b32_e32 v93, v0
	v_mov_b32_e32 v94, v0
	v_mov_b32_e32 v95, v0
	v_mov_b32_e32 v104, v0
	v_mov_b32_e32 v105, v0
	v_mov_b32_e32 v106, v0
	v_mov_b32_e32 v107, v0
	v_mov_b32_e32 v108, v0
	v_mov_b32_e32 v109, v0
	v_mov_b32_e32 v110, v0
	v_mov_b32_e32 v111, v0
	v_mov_b32_e32 v120, v0
	v_mov_b32_e32 v121, v0
	v_mov_b32_e32 v122, v0
	v_mov_b32_e32 v123, v0
	v_mov_b32_e32 v124, v0
	v_mov_b32_e32 v125, v0
	v_mov_b32_e32 v126, v0
	v_mov_b32_e32 v127, v0
	v_mov_b32_e32 v136, v0
	v_mov_b32_e32 v137, v0
	v_mov_b32_e32 v138, v0
	v_mov_b32_e32 v139, v0
	v_mov_b32_e32 v140, v0
	v_mov_b32_e32 v141, v0
	v_mov_b32_e32 v142, v0
	v_mov_b32_e32 v143, v0
	s_branch .LBB0_864

; #define PG8_STAGE(bufoff, gbase, voff) do { _Pragma("unroll") for (int _i = 0; _i < 2; ++_i) \
;         __builtin_amdgcn_global_load_lds((const unsigned*)((const char*)(gbase) + (voff)[_i]), (LAS unsigned*)(lds + (bufoff) + ldsw + _i * 8192), 16, 0, 0); } while (0)
; #define PG8_LDA(dst, b, h) do { _Pragma("unroll") for (int m = 0; m < 4; ++m) _Pragma("unroll") for (int k = 0; k < 2; ++k) dst[m][k] = *(const LAS bf16x8*)(lds + PG8_SA(b, h) + aoff + m * 2048 + k * 1024); } while (0)
; #define PG8_LDB(dst, b, h) do { _Pragma("unroll") for (int n = 0; n < 2; ++n) _Pragma("unroll") for (int k = 0; k < 2; ++k) dst[n][k] = *(const LAS bf16x8*)(lds + PG8_SB(b, h) + boff + n * 2048 + k * 1024); } while (0)
; #define PG8_MMA(ai, bj, At, Bt) do { __builtin_amdgcn_s_setprio(1); _Pragma("unroll") for (int m = 0; m < 4; ++m) _Pragma("unroll") for (int n = 0; n < 2; ++n) _Pragma("unroll") for (int k = 0; k < 2; ++k) \
;         acc[ai][bj][m][n] = __builtin_amdgcn_mfma_f32_16x16x32_bf16(Bt[n][k], At[m][k], acc[ai][bj][m][n], 0, 0, 0); __builtin_amdgcn_s_setprio(0); } while (0)
; #define PG8_WAIT_V(n) asm volatile("s_waitcnt vmcnt(" #n ")" ::: "memory")
; #define PG8_WAIT_L(n) asm volatile("s_waitcnt lgkmcnt(" #n ")" ::: "memory")
; #define PG8_BAR __builtin_amdgcn_s_barrier()
; #define PG8_SCHED __builtin_amdgcn_sched_barrier(0)
; template <class Epi>
; __device__ __forceinline__ void gemm_phase(const int TID, const int BID, LAS unsigned char* lds, const Gemm g, const StaticOrder& S, const Epi& E) {
;     ...
;             PG8_LDB(B0, 0, 0); PG8_SCHED; PG8_LDA(At, 0, 0); PG8_STAGE(PG8_SA(1, 1), a1 + hstepA, voffA);
;             PG8_WAIT_L(8); PG8_BAR; PG8_WAIT_L(0); PG8_MMA(0, 0, At, B0); PG8_BAR; PG8_SCHED;
;             PG8_LDB(B1, 0, 1); PG8_STAGE(PG8_SB(0, 0), b2, voffB);
;             PG8_BAR; PG8_WAIT_L(0); PG8_MMA(0, 1, At, B1); PG8_BAR;
;             PG8_LDA(At, 0, 1); PG8_STAGE(PG8_SA(0, 0), a2, voffA);
;             PG8_BAR; PG8_WAIT_L(0); PG8_MMA(1, 0, At, B0); PG8_BAR; PG8_SCHED;
;             PG8_STAGE(PG8_SB(0, 1), b2 + hstepB, voffB);
;             PG8_WAIT_V(6); PG8_BAR; PG8_MMA(1, 1, At, B1); PG8_BAR;
.LBB0_864:
	v_add_u32_e32 v36, s43, v172
	ds_read_b128 v[8:11], v36
	ds_read_b128 v[12:15], v36 offset:1024
	ds_read_b128 v[32:35], v36 offset:2048
	ds_read_b128 v[36:39], v36 offset:3072
	s_add_u32 s36, s34, 0xfff80080
	s_addc_u32 s37, s35, -1
	s_cmp_eq_u32 s31, 28
	s_cselect_b32 s39, s0, s37
	s_cselect_b32 s38, s1, s36
	s_cselect_b32 s37, s4, s29
	s_cselect_b32 s36, s21, s23
	v_lshl_add_u64 v[158:159], s[34:35], 0, v[150:151]
	s_add_i32 m0, s46, 0xc000
	ds_read_b128 v[154:157], v174
	ds_read_b128 v[176:179], v174 offset:1024
	ds_read_b128 v[180:183], v174 offset:2048
	ds_read_b128 v[196:199], v174 offset:3072
	ds_read_b128 v[208:211], v174 offset:4096
	ds_read_b128 v[212:215], v174 offset:5120
	ds_read_b128 v[216:219], v174 offset:6144
	ds_read_b128 v[220:223], v174 offset:7168
	global_load_lds_dwordx4 v[158:159], off
	s_add_i32 m0, s46, 0xe000
	v_lshl_add_u64 v[158:159], s[34:35], 0, v[152:153]
	global_load_lds_dwordx4 v[158:159], off
	s_waitcnt lgkmcnt(8)
	s_barrier
	s_waitcnt lgkmcnt(0)
	s_setprio 1
	v_mfma_f32_16x16x32_bf16 v[140:143], v[8:11], v[154:157], v[140:143]
	v_mfma_f32_16x16x32_bf16 v[136:139], v[32:35], v[154:157], v[136:139]
	v_mfma_f32_16x16x32_bf16 v[124:127], v[8:11], v[180:183], v[124:127]
	v_mfma_f32_16x16x32_bf16 v[120:123], v[32:35], v[180:183], v[120:123]
	v_mfma_f32_16x16x32_bf16 v[108:111], v[8:11], v[208:211], v[108:111]
	v_mfma_f32_16x16x32_bf16 v[104:107], v[32:35], v[208:211], v[104:107]
	v_mfma_f32_16x16x32_bf16 v[92:95], v[8:11], v[216:219], v[92:95]
	v_mfma_f32_16x16x32_bf16 v[88:91], v[32:35], v[216:219], v[88:91]
	v_mfma_f32_16x16x32_bf16 v[140:143], v[12:15], v[176:179], v[140:143]
	v_mfma_f32_16x16x32_bf16 v[136:139], v[36:39], v[176:179], v[136:139]
	v_mfma_f32_16x16x32_bf16 v[124:127], v[12:15], v[196:199], v[124:127]
	v_mfma_f32_16x16x32_bf16 v[120:123], v[36:39], v[196:199], v[120:123]
	v_mfma_f32_16x16x32_bf16 v[108:111], v[12:15], v[212:215], v[108:111]
	v_mfma_f32_16x16x32_bf16 v[104:107], v[36:39], v[212:215], v[104:107]
	v_mfma_f32_16x16x32_bf16 v[92:95], v[12:15], v[220:223], v[92:95]
	v_mfma_f32_16x16x32_bf16 v[88:91], v[36:39], v[220:223], v[88:91]
	s_setprio 0
	s_barrier
	v_add_u32_e32 v158, s48, v172
	s_mov_b32 m0, s44
	ds_read_b128 v[224:227], v158
	ds_read_b128 v[228:231], v158 offset:1024
	ds_read_b128 v[232:235], v158 offset:2048
	ds_read_b128 v[236:239], v158 offset:3072
	v_lshl_add_u64 v[158:159], s[36:37], 0, v[160:161]
	global_load_lds_dwordx4 v[158:159], off
	s_mov_b32 m0, s45
	v_lshl_add_u64 v[166:167], s[36:37], 0, v[148:149]
	global_load_lds_dwordx4 v[166:167], off
	s_barrier
	s_waitcnt lgkmcnt(0)
	s_setprio 1
	v_mfma_f32_16x16x32_bf16 v[132:135], v[224:227], v[154:157], v[132:135]
	v_mfma_f32_16x16x32_bf16 v[128:131], v[232:235], v[154:157], v[128:131]
	v_mfma_f32_16x16x32_bf16 v[116:119], v[224:227], v[180:183], v[116:119]
	v_mfma_f32_16x16x32_bf16 v[112:115], v[232:235], v[180:183], v[112:115]
	v_mfma_f32_16x16x32_bf16 v[100:103], v[224:227], v[208:211], v[100:103]
	v_mfma_f32_16x16x32_bf16 v[96:99], v[232:235], v[208:211], v[96:99]
	v_mfma_f32_16x16x32_bf16 v[84:87], v[224:227], v[216:219], v[84:87]
	v_mfma_f32_16x16x32_bf16 v[80:83], v[232:235], v[216:219], v[80:83]
	v_mfma_f32_16x16x32_bf16 v[132:135], v[228:231], v[176:179], v[132:135]
	v_mfma_f32_16x16x32_bf16 v[128:131], v[236:239], v[176:179], v[128:131]
	v_mfma_f32_16x16x32_bf16 v[116:119], v[228:231], v[196:199], v[116:119]
	v_mfma_f32_16x16x32_bf16 v[112:115], v[236:239], v[196:199], v[112:115]
	v_mfma_f32_16x16x32_bf16 v[100:103], v[228:231], v[212:215], v[100:103]
	v_mfma_f32_16x16x32_bf16 v[96:99], v[236:239], v[212:215], v[96:99]
	v_mfma_f32_16x16x32_bf16 v[84:87], v[228:231], v[220:223], v[84:87]
	v_mfma_f32_16x16x32_bf16 v[80:83], v[236:239], v[220:223], v[80:83]
	s_setprio 0
	s_mov_b32 m0, s46
	v_lshl_add_u64 v[170:171], s[38:39], 0, v[144:145]
	s_barrier
	ds_read_b128 v[154:157], v174 offset:16384
	ds_read_b128 v[176:179], v174 offset:17408
	ds_read_b128 v[180:183], v174 offset:18432
	ds_read_b128 v[196:199], v174 offset:19456
	ds_read_b128 v[208:211], v174 offset:20480
	ds_read_b128 v[212:215], v174 offset:21504
	ds_read_b128 v[216:219], v174 offset:22528
	ds_read_b128 v[220:223], v174 offset:23552
	global_load_lds_dwordx4 v[170:171], off
	s_mov_b32 m0, s47
	v_lshl_add_u64 v[184:185], s[38:39], 0, v[146:147]
	global_load_lds_dwordx4 v[184:185], off
	s_barrier
	s_waitcnt lgkmcnt(0)
	s_setprio 1
	v_mfma_f32_16x16x32_bf16 v[76:79], v[8:11], v[154:157], v[76:79]
	v_mfma_f32_16x16x32_bf16 v[72:75], v[32:35], v[154:157], v[72:75]
	v_mfma_f32_16x16x32_bf16 v[60:63], v[8:11], v[180:183], v[60:63]
	v_mfma_f32_16x16x32_bf16 v[56:59], v[32:35], v[180:183], v[56:59]
	v_mfma_f32_16x16x32_bf16 v[44:47], v[8:11], v[208:211], v[44:47]
	v_mfma_f32_16x16x32_bf16 v[40:43], v[32:35], v[208:211], v[40:43]
	v_mfma_f32_16x16x32_bf16 v[8:11], v[8:11], v[216:219], v[20:23]
	v_mfma_f32_16x16x32_bf16 v[76:79], v[12:15], v[176:179], v[76:79]
	v_mfma_f32_16x16x32_bf16 v[72:75], v[36:39], v[176:179], v[72:75]
	v_mfma_f32_16x16x32_bf16 v[60:63], v[12:15], v[196:199], v[60:63]
	v_mfma_f32_16x16x32_bf16 v[56:59], v[36:39], v[196:199], v[56:59]
	v_mfma_f32_16x16x32_bf16 v[44:47], v[12:15], v[212:215], v[44:47]
	v_mfma_f32_16x16x32_bf16 v[40:43], v[36:39], v[212:215], v[40:43]
	v_mfma_f32_16x16x32_bf16 v[8:11], v[12:15], v[220:223], v[8:11]
	v_mfma_f32_16x16x32_bf16 v[12:15], v[32:35], v[216:219], v[16:19]
	v_mfma_f32_16x16x32_bf16 v[12:15], v[36:39], v[220:223], v[12:15]
	s_setprio 0
	s_barrier
; #define PG8_STAGE(bufoff, gbase, voff) do { _Pragma("unroll") for (int _i = 0; _i < 2; ++_i) \
;         __builtin_amdgcn_global_load_lds((const unsigned*)((const char*)(gbase) + (voff)[_i]), (LAS unsigned*)(lds + (bufoff) + ldsw + _i * 8192), 16, 0, 0); } while (0)
; #define PG8_LDA(dst, b, h) do { _Pragma("unroll") for (int m = 0; m < 4; ++m) _Pragma("unroll") for (int k = 0; k < 2; ++k) dst[m][k] = *(const LAS bf16x8*)(lds + PG8_SA(b, h) + aoff + m * 2048 + k * 1024); } while (0)
; #define PG8_LDB(dst, b, h) do { _Pragma("unroll") for (int n = 0; n < 2; ++n) _Pragma("unroll") for (int k = 0; k < 2; ++k) dst[n][k] = *(const LAS bf16x8*)(lds + PG8_SB(b, h) + boff + n * 2048 + k * 1024); } while (0)
; #define PG8_MMA(ai, bj, At, Bt) do { __builtin_amdgcn_s_setprio(1); _Pragma("unroll") for (int m = 0; m < 4; ++m) _Pragma("unroll") for (int n = 0; n < 2; ++n) _Pragma("unroll") for (int k = 0; k < 2; ++k) \
;         acc[ai][bj][m][n] = __builtin_amdgcn_mfma_f32_16x16x32_bf16(Bt[n][k], At[m][k], acc[ai][bj][m][n], 0, 0, 0); __builtin_amdgcn_s_setprio(0); } while (0)
; #define PG8_WAIT_V(n) asm volatile("s_waitcnt vmcnt(" #n ")" ::: "memory")
; #define PG8_WAIT_L(n) asm volatile("s_waitcnt lgkmcnt(" #n ")" ::: "memory")
; #define PG8_BAR __builtin_amdgcn_s_barrier()
; #define PG8_SCHED __builtin_amdgcn_sched_barrier(0)
; template <class Epi>
; __device__ __forceinline__ void gemm_phase(const int TID, const int BID, LAS unsigned char* lds, const Gemm g, const StaticOrder& S, const Epi& E) {
;     ...
;             PG8_WAIT_V(6); PG8_BAR; PG8_MMA(1, 1, At, B1); PG8_BAR;
;             PG8_LDB(B0, 1, 0); PG8_SCHED; PG8_LDA(At, 1, 0); PG8_STAGE(PG8_SA(0, 1), a2 + hstepA, voffA);
;             PG8_WAIT_L(8); PG8_BAR; PG8_WAIT_L(0); PG8_MMA(0, 0, At, B0); PG8_BAR; PG8_SCHED;
;             PG8_LDB(B1, 1, 1); PG8_STAGE(PG8_SB(1, 0), b3, voffB);
;             PG8_BAR; PG8_WAIT_L(0); PG8_MMA(0, 1, At, B1); PG8_BAR;
;             PG8_LDA(At, 1, 1); PG8_STAGE(PG8_SA(1, 0), a3, voffA);
;             PG8_BAR; PG8_WAIT_L(0); PG8_MMA(1, 0, At, B0); PG8_BAR; PG8_SCHED;
	s_add_u32 s66, s36, 0x80000
	s_addc_u32 s67, s37, 0
	s_mov_b32 m0, s49
	v_lshl_add_u64 v[16:17], s[66:67], 0, v[160:161]
	global_load_lds_dwordx4 v[16:17], off
	s_mov_b32 m0, s50
	v_lshl_add_u64 v[16:17], s[66:67], 0, v[148:149]
	global_load_lds_dwordx4 v[16:17], off
	s_waitcnt vmcnt(6)
	s_barrier
	s_setprio 1
	v_mfma_f32_16x16x32_bf16 v[16:19], v[224:227], v[154:157], v[68:71]
	v_mfma_f32_16x16x32_bf16 v[32:35], v[228:231], v[176:179], v[16:19]
	v_mfma_f32_16x16x32_bf16 v[16:19], v[232:235], v[154:157], v[64:67]
	v_mfma_f32_16x16x32_bf16 v[36:39], v[236:239], v[176:179], v[16:19]
	v_mfma_f32_16x16x32_bf16 v[16:19], v[224:227], v[180:183], v[52:55]
	v_mfma_f32_16x16x32_bf16 v[52:55], v[228:231], v[196:199], v[16:19]
	v_mfma_f32_16x16x32_bf16 v[16:19], v[232:235], v[180:183], v[48:51]
	v_mfma_f32_16x16x32_bf16 v[48:51], v[236:239], v[196:199], v[16:19]
	v_mfma_f32_16x16x32_bf16 v[16:19], v[224:227], v[208:211], v[28:31]
	v_mfma_f32_16x16x32_bf16 v[28:31], v[228:231], v[212:215], v[16:19]
	v_mfma_f32_16x16x32_bf16 v[16:19], v[232:235], v[208:211], v[24:27]
	v_mfma_f32_16x16x32_bf16 v[4:7], v[224:227], v[216:219], v[4:7]
	v_mfma_f32_16x16x32_bf16 v[0:3], v[232:235], v[216:219], v[0:3]
	v_mfma_f32_16x16x32_bf16 v[24:27], v[236:239], v[212:215], v[16:19]
	v_mfma_f32_16x16x32_bf16 v[4:7], v[228:231], v[220:223], v[4:7]
	v_mfma_f32_16x16x32_bf16 v[0:3], v[236:239], v[220:223], v[0:3]
	s_setprio 0
	v_add_u32_e32 v68, s53, v172
	s_barrier
	ds_read_b128 v[16:19], v68
	ds_read_b128 v[20:23], v68 offset:1024
	ds_read_b128 v[64:67], v68 offset:2048
	ds_read_b128 v[68:71], v68 offset:3072
	s_add_u32 s38, s38, 0x80000
	s_addc_u32 s39, s39, 0
	s_mov_b32 m0, s51
	v_lshl_add_u64 v[200:201], s[38:39], 0, v[144:145]
	ds_read_b128 v[154:157], v174 offset:32768
	ds_read_b128 v[176:179], v174 offset:33792
	ds_read_b128 v[180:183], v174 offset:34816
	ds_read_b128 v[196:199], v174 offset:35840
	ds_read_b128 v[208:211], v174 offset:36864
	ds_read_b128 v[212:215], v174 offset:37888
	ds_read_b128 v[216:219], v174 offset:38912
	ds_read_b128 v[220:223], v174 offset:39936
	global_load_lds_dwordx4 v[200:201], off
	s_mov_b32 m0, s52
	v_lshl_add_u64 v[200:201], s[38:39], 0, v[146:147]
	global_load_lds_dwordx4 v[200:201], off
	s_waitcnt lgkmcnt(8)
	s_barrier
	s_waitcnt lgkmcnt(0)
	s_setprio 1
	v_mfma_f32_16x16x32_bf16 v[140:143], v[16:19], v[154:157], v[140:143]
	v_mfma_f32_16x16x32_bf16 v[136:139], v[64:67], v[154:157], v[136:139]
	v_mfma_f32_16x16x32_bf16 v[124:127], v[16:19], v[180:183], v[124:127]
	v_mfma_f32_16x16x32_bf16 v[120:123], v[64:67], v[180:183], v[120:123]
	v_mfma_f32_16x16x32_bf16 v[108:111], v[16:19], v[208:211], v[108:111]
	v_mfma_f32_16x16x32_bf16 v[104:107], v[64:67], v[208:211], v[104:107]
	v_mfma_f32_16x16x32_bf16 v[92:95], v[16:19], v[216:219], v[92:95]
	v_mfma_f32_16x16x32_bf16 v[88:91], v[64:67], v[216:219], v[88:91]
	v_mfma_f32_16x16x32_bf16 v[140:143], v[20:23], v[176:179], v[140:143]
	v_mfma_f32_16x16x32_bf16 v[136:139], v[68:71], v[176:179], v[136:139]
	v_mfma_f32_16x16x32_bf16 v[124:127], v[20:23], v[196:199], v[124:127]
	v_mfma_f32_16x16x32_bf16 v[120:123], v[68:71], v[196:199], v[120:123]
	v_mfma_f32_16x16x32_bf16 v[108:111], v[20:23], v[212:215], v[108:111]
	v_mfma_f32_16x16x32_bf16 v[104:107], v[68:71], v[212:215], v[104:107]
	v_mfma_f32_16x16x32_bf16 v[92:95], v[20:23], v[220:223], v[92:95]
	v_mfma_f32_16x16x32_bf16 v[88:91], v[68:71], v[220:223], v[88:91]
	s_setprio 0
	s_barrier
	s_mov_b32 m0, s54
	v_add_u32_e32 v168, s58, v172
	v_lshl_add_u64 v[158:159], v[158:159], 0, s[90:91]
	ds_read_b128 v[224:227], v168
	ds_read_b128 v[228:231], v168 offset:1024
	ds_read_b128 v[232:235], v168 offset:2048
	ds_read_b128 v[236:239], v168 offset:3072
	global_load_lds_dwordx4 v[158:159], off
	s_mov_b32 m0, s55
	v_lshl_add_u64 v[158:159], v[166:167], 0, s[90:91]
	global_load_lds_dwordx4 v[158:159], off
	s_barrier
	s_waitcnt lgkmcnt(0)
	s_setprio 1
	v_mfma_f32_16x16x32_bf16 v[132:135], v[224:227], v[154:157], v[132:135]
	v_mfma_f32_16x16x32_bf16 v[128:131], v[232:235], v[154:157], v[128:131]
	v_mfma_f32_16x16x32_bf16 v[116:119], v[224:227], v[180:183], v[116:119]
	v_mfma_f32_16x16x32_bf16 v[112:115], v[232:235], v[180:183], v[112:115]
	v_mfma_f32_16x16x32_bf16 v[100:103], v[224:227], v[208:211], v[100:103]
	v_mfma_f32_16x16x32_bf16 v[96:99], v[232:235], v[208:211], v[96:99]
	v_mfma_f32_16x16x32_bf16 v[84:87], v[224:227], v[216:219], v[84:87]
	v_mfma_f32_16x16x32_bf16 v[80:83], v[232:235], v[216:219], v[80:83]
	v_mfma_f32_16x16x32_bf16 v[132:135], v[228:231], v[176:179], v[132:135]
	v_mfma_f32_16x16x32_bf16 v[128:131], v[236:239], v[176:179], v[128:131]
	v_mfma_f32_16x16x32_bf16 v[116:119], v[228:231], v[196:199], v[116:119]
	v_mfma_f32_16x16x32_bf16 v[112:115], v[236:239], v[196:199], v[112:115]
	v_mfma_f32_16x16x32_bf16 v[100:103], v[228:231], v[212:215], v[100:103]
	v_mfma_f32_16x16x32_bf16 v[96:99], v[236:239], v[212:215], v[96:99]
	v_mfma_f32_16x16x32_bf16 v[84:87], v[228:231], v[220:223], v[84:87]
	v_mfma_f32_16x16x32_bf16 v[80:83], v[236:239], v[220:223], v[80:83]
	s_setprio 0
	s_mov_b32 m0, s56
	v_lshl_add_u64 v[158:159], v[170:171], 0, s[90:91]
	s_barrier
	ds_read_b128 v[154:157], v174 offset:49152
	ds_read_b128 v[176:179], v174 offset:50176
	ds_read_b128 v[180:183], v174 offset:51200
	ds_read_b128 v[196:199], v174 offset:52224
	ds_read_b128 v[208:211], v174 offset:53248
	ds_read_b128 v[212:215], v174 offset:54272
	ds_read_b128 v[216:219], v174 offset:55296
	ds_read_b128 v[220:223], v174 offset:56320
	global_load_lds_dwordx4 v[158:159], off
	s_mov_b32 m0, s57
	v_lshl_add_u64 v[158:159], v[184:185], 0, s[90:91]
	global_load_lds_dwordx4 v[158:159], off
	s_barrier
; __device__ __forceinline__ float rinv_st(stat_t s, float invn) { return rsqrtf((float)((double)s * (1.0 / 4294967296.0)) * invn + 1e-6f); }
; #define PG8_STAGE(bufoff, gbase, voff) do { _Pragma("unroll") for (int _i = 0; _i < 2; ++_i) \
;         __builtin_amdgcn_global_load_lds((const unsigned*)((const char*)(gbase) + (voff)[_i]), (LAS unsigned*)(lds + (bufoff) + ldsw + _i * 8192), 16, 0, 0); } while (0)
; #define PG8_MMA(ai, bj, At, Bt) do { __builtin_amdgcn_s_setprio(1); _Pragma("unroll") for (int m = 0; m < 4; ++m) _Pragma("unroll") for (int n = 0; n < 2; ++n) _Pragma("unroll") for (int k = 0; k < 2; ++k) \
;         acc[ai][bj][m][n] = __builtin_amdgcn_mfma_f32_16x16x32_bf16(Bt[n][k], At[m][k], acc[ai][bj][m][n], 0, 0, 0); __builtin_amdgcn_s_setprio(0); } while (0)
; #define PG8_WAIT_V(n) asm volatile("s_waitcnt vmcnt(" #n ")" ::: "memory")
; template <class Epi>
; __device__ __forceinline__ void gemm_phase(const int TID, const int BID, LAS unsigned char* lds, const Gemm g, const StaticOrder& S, const Epi& E) {
;     ...
;             PG8_BAR; PG8_WAIT_L(0); PG8_MMA(1, 0, At, B0); PG8_BAR; PG8_SCHED;
;             PG8_STAGE(PG8_SB(1, 1), b3 + hstepB, voffB);
;             PG8_WAIT_V(6); PG8_BAR; PG8_MMA(1, 1, At, B1); PG8_BAR;
;         }
;     __device__ __forceinline__ void operator()(const f32x4 (&acc)[2][2][4][2], const Unit& u, int wr, int wc, int fr, int fq) const {
;         const int row0 = u.pm * BM + wr * 64 + fr, col0 = u.pn * BM + wc * 32 + 8 * fq;
;         f32x4 bv[2][2];
; #pragma unroll
;         for (int bj = 0; bj < 2; ++bj)
; #pragma unroll
;             for (int n = 0; n < 2; ++n) bv[bj][n] = *(const f32x4*)(bias + col0 + bj * HALF + 4 * n);
;         const bool isv = u.pn >= 8;
; #pragma unroll
;         for (int ai = 0; ai < 2; ++ai)
; #pragma unroll
;             for (int m = 0; m < 4; ++m) {
;                 const int row = row0 + ai * HALF + m * 16; const float r = rinv_st(stats[row], 1.0f / 2048.0f);
;                 bf16_t* rowp = uv + (size_t)row * 4096 + col0; float ss = 0.f;
; #pragma unroll
;                 for (int bj = 0; bj < 2; ++bj) {
;                     const f32x4 v0 = acc[ai][bj][m][0] * r + bv[bj][0], v1 = acc[ai][bj][m][1] * r + bv[bj][1];
;                     const f32x2 a = gelu_pk((f32x2){v0[0], v0[1]}), b = gelu_pk((f32x2){v0[2], v0[3]}), c = gelu_pk((f32x2){v1[0], v1[1]}), d = gelu_pk((f32x2){v1[2], v1[3]});
	s_waitcnt lgkmcnt(0)
	s_setprio 1
	v_mfma_f32_16x16x32_bf16 v[76:79], v[16:19], v[154:157], v[76:79]
	v_mfma_f32_16x16x32_bf16 v[60:63], v[16:19], v[180:183], v[60:63]
	v_mfma_f32_16x16x32_bf16 v[44:47], v[16:19], v[208:211], v[44:47]
	v_mfma_f32_16x16x32_bf16 v[8:11], v[16:19], v[216:219], v[8:11]
	v_mfma_f32_16x16x32_bf16 v[76:79], v[20:23], v[176:179], v[76:79]
	v_mfma_f32_16x16x32_bf16 v[72:75], v[64:67], v[154:157], v[72:75]
	v_mfma_f32_16x16x32_bf16 v[60:63], v[20:23], v[196:199], v[60:63]
	v_mfma_f32_16x16x32_bf16 v[56:59], v[64:67], v[180:183], v[56:59]
	v_mfma_f32_16x16x32_bf16 v[44:47], v[20:23], v[212:215], v[44:47]
	v_mfma_f32_16x16x32_bf16 v[40:43], v[64:67], v[208:211], v[40:43]
	v_mfma_f32_16x16x32_bf16 v[20:23], v[20:23], v[220:223], v[8:11]
	v_mfma_f32_16x16x32_bf16 v[8:11], v[64:67], v[216:219], v[12:15]
	v_mfma_f32_16x16x32_bf16 v[72:75], v[68:71], v[176:179], v[72:75]
	v_mfma_f32_16x16x32_bf16 v[56:59], v[68:71], v[196:199], v[56:59]
	v_mfma_f32_16x16x32_bf16 v[40:43], v[68:71], v[212:215], v[40:43]
	v_mfma_f32_16x16x32_bf16 v[16:19], v[68:71], v[220:223], v[8:11]
	s_setprio 0
	s_barrier
	s_add_u32 s36, s36, 0x80080
	s_addc_u32 s37, s37, 0
	s_mov_b32 m0, s59
	v_lshl_add_u64 v[8:9], s[36:37], 0, v[160:161]
	global_load_lds_dwordx4 v[8:9], off
	s_mov_b32 m0, s60
	v_lshl_add_u64 v[8:9], s[36:37], 0, v[148:149]
	global_load_lds_dwordx4 v[8:9], off
	s_waitcnt vmcnt(6)
	s_barrier
	s_setprio 1
	v_mfma_f32_16x16x32_bf16 v[8:11], v[224:227], v[154:157], v[32:35]
	v_mfma_f32_16x16x32_bf16 v[68:71], v[228:231], v[176:179], v[8:11]
	v_mfma_f32_16x16x32_bf16 v[8:11], v[232:235], v[154:157], v[36:39]
	v_mfma_f32_16x16x32_bf16 v[64:67], v[236:239], v[176:179], v[8:11]
	v_mfma_f32_16x16x32_bf16 v[8:11], v[224:227], v[180:183], v[52:55]
	v_mfma_f32_16x16x32_bf16 v[52:55], v[228:231], v[196:199], v[8:11]
	v_mfma_f32_16x16x32_bf16 v[8:11], v[232:235], v[180:183], v[48:51]
	v_mfma_f32_16x16x32_bf16 v[48:51], v[236:239], v[196:199], v[8:11]
	v_mfma_f32_16x16x32_bf16 v[8:11], v[224:227], v[208:211], v[28:31]
	v_mfma_f32_16x16x32_bf16 v[28:31], v[228:231], v[212:215], v[8:11]
	v_mfma_f32_16x16x32_bf16 v[8:11], v[232:235], v[208:211], v[24:27]
	v_mfma_f32_16x16x32_bf16 v[4:7], v[224:227], v[216:219], v[4:7]
	v_mfma_f32_16x16x32_bf16 v[0:3], v[232:235], v[216:219], v[0:3]
	v_mfma_f32_16x16x32_bf16 v[24:27], v[236:239], v[212:215], v[8:11]
	v_mfma_f32_16x16x32_bf16 v[4:7], v[228:231], v[220:223], v[4:7]
	v_mfma_f32_16x16x32_bf16 v[0:3], v[236:239], v[220:223], v[0:3]
	s_setprio 0
	s_add_i32 s31, s31, 2
	s_add_u32 s34, s34, 0x100
	s_addc_u32 s35, s35, 0
	s_add_u32 s23, s23, 0x100
	s_addc_u32 s29, s29, 0
	s_cmp_gt_u32 s31, 29
	s_cbranch_scc0 .Lrot_864
	s_barrier
	v_readlane_b32 s0, v254, 32
	v_readlane_b32 s1, v254, 33
	s_load_dwordx2 s[0:1], s[0:1], 0x50
	v_lshl_or_b32 v154, s30, 8, v173
	v_lshl_add_u32 v156, s28, 8, v169
	v_ashrrev_i32_e32 v155, 31, v154
	v_ashrrev_i32_e32 v157, 31, v156
	s_waitcnt lgkmcnt(0)
	v_lshl_add_u64 v[12:13], v[154:155], 2, s[0:1]
	v_lshl_add_u64 v[158:159], v[156:157], 3, s[16:17]
	global_load_dwordx4 v[32:35], v[12:13], off offset:16
	global_load_dwordx4 v[36:39], v[12:13], off
	global_load_dwordx4 v[8:11], v[12:13], off offset:528
	s_nop 0
	global_load_dwordx4 v[12:15], v[12:13], off offset:512
	s_cmp_gt_i32 s30, 7
	global_load_dwordx2 v[166:167], v[158:159], off
	global_load_dwordx2 v[208:209], v[158:159], off offset:128
	global_load_dwordx2 v[210:211], v[158:159], off offset:256
	global_load_dwordx2 v[212:213], v[158:159], off offset:384
	global_load_dwordx2 v[214:215], v[158:159], off offset:1024
	global_load_dwordx2 v[216:217], v[158:159], off offset:1152
	global_load_dwordx2 v[218:219], v[158:159], off offset:1280
	global_load_dwordx2 v[220:221], v[158:159], off offset:1408
	s_mov_b32 s30, 0xbf38aa3b
	s_cselect_b64 s[0:1], -1, 0
	s_and_b64 s[28:29], s[8:9], s[0:1]
	s_mov_b32 s0, 0xbe11a98e
	s_mov_b32 s4, 0x3e027906
	s_waitcnt vmcnt(0)
	v_cvt_f64_u32_e32 v[170:171], v167
	v_ldexp_f64 v[170:171], v[170:171], 32
	v_cvt_f64_u32_e32 v[166:167], v166
	v_add_f64 v[166:167], v[170:171], v[166:167]
	v_ldexp_f64 v[166:167], v[166:167], s93
	v_cvt_f32_f64_e32 v166, v[166:167]
	v_fmamk_f32 v166, v166, 0x3a000000, v189
	v_cmp_gt_f32_e32 vcc, s78, v166
	v_mul_f32_e32 v167, 0x4b800000, v166
	s_nop 0
	v_cndmask_b32_e32 v166, v166, v167, vcc
	v_rsq_f32_e32 v166, v166
	s_nop 0
	v_mul_f32_e32 v167, 0x45800000, v166
	v_cndmask_b32_e32 v168, v166, v167, vcc
	v_pk_fma_f32 v[170:171], v[140:141], v[168:169], v[36:37] op_sel_hi:[1,0,1]
	v_pk_fma_f32 v[140:141], v[136:137], v[168:169], v[32:33] op_sel_hi:[1,0,1]
	v_and_b32_e32 v137, 0x7fffffff, v171
	v_and_b32_e32 v136, 0x7fffffff, v170
	v_pk_fma_f32 v[136:137], v[136:137], s[64:65], 1.0 op_sel_hi:[1,0,0]
	v_pk_mul_f32 v[180:181], v[170:171], v[170:171]
	v_rcp_f32_e32 v176, v136
	v_rcp_f32_e32 v177, v137
	v_mov_b64_e32 v[136:137], s[80:81]
	v_pk_mul_f32 v[180:181], v[180:181], s[30:31] op_sel_hi:[1,0]
	v_cmp_gt_f32_e32 vcc, 0, v170
	v_pk_fma_f32 v[178:179], v[176:177], s[74:75], v[136:137] op_sel_hi:[1,0,0]
	v_exp_f32_e32 v180, v180
	v_pk_fma_f32 v[178:179], v[176:177], v[178:179], s[86:87] op_sel_hi:[1,1,0]
	v_exp_f32_e32 v181, v181
	v_pk_fma_f32 v[178:179], v[176:177], v[178:179], s[0:1] op_sel_hi:[1,1,0]
	v_pk_fma_f32 v[142:143], v[142:143], v[168:169], v[38:39] op_sel_hi:[1,0,1]
	v_pk_fma_f32 v[178:179], v[176:177], v[178:179], s[4:5] op_sel_hi:[1,1,0]
	v_pk_fma_f32 v[138:139], v[138:139], v[168:169], v[34:35] op_sel_hi:[1,0,1]
	v_pk_mul_f32 v[176:177], v[176:177], v[178:179]
	v_pk_mul_f32 v[178:179], v[142:143], v[142:143]
	v_pk_mul_f32 v[176:177], v[180:181], v[176:177]
; __device__ __forceinline__ unsigned cvt_pk_bf16(float lo, float hi) { unsigned r; asm volatile("v_cvt_pk_bf16_f32 %0, %1, %2" : "=v"(r) : "v"(lo), "v"(hi)); return r; }
; __device__ __forceinline__ f32x2 gelu_pk(f32x2 v) {
;     const f32x2 av = __builtin_elementwise_abs(v), d = av * 0.2316418882f + 1.0f;
;     f32x2 t; t.x = __builtin_amdgcn_rcpf(d.x); t.y = __builtin_amdgcn_rcpf(d.y);
;     f32x2 q = t * 0.5307027145f + (-0.7265760135f); q = q * t + 0.7107068705f; q = q * t + (-0.142248368f); q = q * t + 0.127414796f; q = q * t;
;     const f32x2 s = (v * v) * (-0.72134752044f);
;     f32x2 e; e.x = __builtin_amdgcn_exp2f(s.x); e.y = __builtin_amdgcn_exp2f(s.y);
;     const f32x2 m = v * (q * e), r = v - m;
;     f32x2 o; o.x = v.x < 0.f ? m.x : r.x; o.y = v.y < 0.f ? m.y : r.y; return o;
; }
;     __device__ __forceinline__ void operator()(const f32x4 (&acc)[2][2][4][2], const Unit& u, int wr, int wc, int fr, int fq) const {
;     ...
;                     const f32x4 v0 = acc[ai][bj][m][0] * r + bv[bj][0], v1 = acc[ai][bj][m][1] * r + bv[bj][1];
;                     const f32x2 a = gelu_pk((f32x2){v0[0], v0[1]}), b = gelu_pk((f32x2){v0[2], v0[3]}), c = gelu_pk((f32x2){v1[0], v1[1]}), d = gelu_pk((f32x2){v1[2], v1[3]});
;                     ss += a.x * a.x + a.y * a.y + b.x * b.x + b.y * b.y + c.x * c.x + c.y * c.y + d.x * d.x + d.y * d.y;
;                     u32x4 w; w.x = cvt_pk_bf16(a.x, a.y); w.y = cvt_pk_bf16(b.x, b.y); w.z = cvt_pk_bf16(c.x, c.y); w.w = cvt_pk_bf16(d.x, d.y);
;                     *(u32x4*)(rowp + bj * HALF) = w;
	v_pk_mul_f32 v[178:179], v[178:179], s[30:31] op_sel_hi:[1,0]
	v_pk_mul_f32 v[180:181], v[170:171], v[176:177]
	v_pk_fma_f32 v[176:177], v[170:171], v[176:177], v[170:171] neg_lo:[1,0,0] neg_hi:[1,0,0]
	v_exp_f32_e32 v178, v178
	v_cndmask_b32_e32 v170, v176, v180, vcc
	v_cmp_gt_f32_e32 vcc, 0, v171
	v_and_b32_e32 v176, 0x7fffffff, v142
	v_exp_f32_e32 v179, v179
	v_cndmask_b32_e32 v171, v177, v181, vcc
	v_and_b32_e32 v177, 0x7fffffff, v143
	v_pk_fma_f32 v[176:177], v[176:177], s[64:65], 1.0 op_sel_hi:[1,0,0]
	v_cmp_gt_f32_e32 vcc, 0, v142
	v_rcp_f32_e32 v176, v176
	v_rcp_f32_e32 v177, v177
	v_lshlrev_b64 v[166:167], 13, v[156:157]
	v_lshl_add_u64 v[166:167], s[14:15], 0, v[166:167]
	v_lshl_add_u64 v[166:167], v[154:155], 1, v[166:167]
	v_pk_fma_f32 v[180:181], v[176:177], s[74:75], v[136:137] op_sel_hi:[1,0,0]
	v_pk_fma_f32 v[132:133], v[132:133], v[168:169], v[12:13] op_sel_hi:[1,0,1]
	v_pk_fma_f32 v[180:181], v[176:177], v[180:181], s[86:87] op_sel_hi:[1,1,0]
	v_pk_fma_f32 v[134:135], v[134:135], v[168:169], v[14:15] op_sel_hi:[1,0,1]
	v_pk_fma_f32 v[180:181], v[176:177], v[180:181], s[0:1] op_sel_hi:[1,1,0]
	v_pk_fma_f32 v[128:129], v[128:129], v[168:169], v[8:9] op_sel_hi:[1,0,1]
	v_pk_fma_f32 v[180:181], v[176:177], v[180:181], s[4:5] op_sel_hi:[1,1,0]
	v_pk_fma_f32 v[130:131], v[130:131], v[168:169], v[10:11] op_sel_hi:[1,0,1]
	v_pk_mul_f32 v[176:177], v[176:177], v[180:181]
	s_nop 0
	v_pk_mul_f32 v[176:177], v[178:179], v[176:177]
	s_nop 0
	v_pk_mul_f32 v[178:179], v[142:143], v[176:177]
	v_pk_fma_f32 v[176:177], v[142:143], v[176:177], v[142:143] neg_lo:[1,0,0] neg_hi:[1,0,0]
	v_and_b32_e32 v142, 0x7fffffff, v140
	v_cndmask_b32_e32 v175, v176, v178, vcc
	v_cmp_gt_f32_e32 vcc, 0, v143
	v_and_b32_e32 v143, 0x7fffffff, v141
	v_pk_fma_f32 v[142:143], v[142:143], s[64:65], 1.0 op_sel_hi:[1,0,0]
	v_cndmask_b32_e32 v180, v177, v179, vcc
	v_rcp_f32_e32 v142, v142
	v_rcp_f32_e32 v143, v143
	v_pk_mul_f32 v[178:179], v[140:141], v[140:141]
	v_cmp_gt_f32_e32 vcc, 0, v140
	v_pk_mul_f32 v[178:179], v[178:179], s[30:31] op_sel_hi:[1,0]
	v_pk_fma_f32 v[176:177], v[142:143], s[74:75], v[136:137] op_sel_hi:[1,0,0]
	v_exp_f32_e32 v178, v178
	v_pk_fma_f32 v[176:177], v[142:143], v[176:177], s[86:87] op_sel_hi:[1,1,0]
	v_exp_f32_e32 v179, v179
	v_pk_fma_f32 v[176:177], v[142:143], v[176:177], s[0:1] op_sel_hi:[1,1,0]
	s_nop 0
	v_pk_fma_f32 v[176:177], v[142:143], v[176:177], s[4:5] op_sel_hi:[1,1,0]
	s_nop 0
	v_pk_mul_f32 v[142:143], v[142:143], v[176:177]
	v_pk_mul_f32 v[176:177], v[138:139], v[138:139]
	v_pk_mul_f32 v[142:143], v[178:179], v[142:143]
	s_nop 0
	v_pk_mul_f32 v[178:179], v[140:141], v[142:143]
	v_pk_fma_f32 v[142:143], v[140:141], v[142:143], v[140:141] neg_lo:[1,0,0] neg_hi:[1,0,0]
	v_and_b32_e32 v140, 0x7fffffff, v138
	v_cndmask_b32_e32 v178, v142, v178, vcc
	v_cmp_gt_f32_e32 vcc, 0, v141
	v_and_b32_e32 v141, 0x7fffffff, v139
	v_pk_fma_f32 v[140:141], v[140:141], s[64:65], 1.0 op_sel_hi:[1,0,0]
	v_cndmask_b32_e32 v179, v143, v179, vcc
	v_rcp_f32_e32 v140, v140
	v_rcp_f32_e32 v141, v141
	v_cmp_gt_f32_e32 vcc, 0, v138
	v_pk_fma_f32 v[142:143], v[140:141], s[74:75], v[136:137] op_sel_hi:[1,0,0]
	s_nop 0
	v_pk_fma_f32 v[142:143], v[140:141], v[142:143], s[86:87] op_sel_hi:[1,1,0]
	s_nop 0
	v_pk_fma_f32 v[142:143], v[140:141], v[142:143], s[0:1] op_sel_hi:[1,1,0]
	s_nop 0
	v_pk_fma_f32 v[142:143], v[140:141], v[142:143], s[4:5] op_sel_hi:[1,1,0]
	s_nop 0
	v_pk_mul_f32 v[140:141], v[140:141], v[142:143]
	v_pk_mul_f32 v[142:143], v[176:177], s[30:31] op_sel_hi:[1,0]
	v_mul_f32_e32 v176, v171, v171
	v_exp_f32_e32 v142, v142
	v_exp_f32_e32 v143, v143
	v_fmac_f32_e32 v176, v170, v170
	v_fmac_f32_e32 v176, v175, v175
	v_fmac_f32_e32 v176, v180, v180
	v_pk_mul_f32 v[140:141], v[142:143], v[140:141]
	v_fmac_f32_e32 v176, v178, v178
	v_pk_mul_f32 v[142:143], v[138:139], v[140:141]
	v_pk_fma_f32 v[140:141], v[138:139], v[140:141], v[138:139] neg_lo:[1,0,0] neg_hi:[1,0,0]
	v_fmac_f32_e32 v176, v179, v179
	v_cndmask_b32_e32 v142, v140, v142, vcc
	v_cmp_gt_f32_e32 vcc, 0, v139
	v_fmac_f32_e32 v176, v142, v142
	v_cvt_pk_bf16_f32 v138, v170, v171
	v_cvt_pk_bf16_f32 v139, v175, v180
	v_cvt_pk_bf16_f32 v140, v178, v179
	s_nop 0
	v_cndmask_b32_e32 v141, v141, v143, vcc
	v_fmac_f32_e32 v176, v141, v141
	v_cvt_pk_bf16_f32 v141, v142, v141
	global_store_dwordx4 v[166:167], v[138:141], off
	v_pk_mul_f32 v[142:143], v[132:133], v[132:133]
	v_cmp_gt_f32_e32 vcc, 0, v132
	v_and_b32_e32 v139, 0x7fffffff, v133
	v_and_b32_e32 v138, 0x7fffffff, v132
	v_pk_fma_f32 v[138:139], v[138:139], s[64:65], 1.0 op_sel_hi:[1,0,0]
	v_pk_mul_f32 v[142:143], v[142:143], s[30:31] op_sel_hi:[1,0]
	v_rcp_f32_e32 v138, v138
	v_rcp_f32_e32 v139, v139
	v_exp_f32_e32 v142, v142
	v_exp_f32_e32 v143, v143
	v_pk_fma_f32 v[140:141], v[138:139], s[74:75], v[136:137] op_sel_hi:[1,0,0]
	s_nop 0
	v_pk_fma_f32 v[140:141], v[138:139], v[140:141], s[86:87] op_sel_hi:[1,1,0]
	s_nop 0
	v_pk_fma_f32 v[140:141], v[138:139], v[140:141], s[0:1] op_sel_hi:[1,1,0]
	s_nop 0
	v_pk_fma_f32 v[140:141], v[138:139], v[140:141], s[4:5] op_sel_hi:[1,1,0]
	s_nop 0
	v_pk_mul_f32 v[138:139], v[138:139], v[140:141]
; __device__ __forceinline__ unsigned cvt_pk_bf16(float lo, float hi) { unsigned r; asm volatile("v_cvt_pk_bf16_f32 %0, %1, %2" : "=v"(r) : "v"(lo), "v"(hi)); return r; }
; __device__ __forceinline__ void stat_add(stat_t* p, float ss) { __hip_atomic_fetch_add(p, (stat_t)((double)ss * 4294967296.0), __ATOMIC_RELAXED, __HIP_MEMORY_SCOPE_AGENT); }
; __device__ __forceinline__ f32x2 gelu_pk(f32x2 v) {
;     const f32x2 av = __builtin_elementwise_abs(v), d = av * 0.2316418882f + 1.0f;
;     f32x2 t; t.x = __builtin_amdgcn_rcpf(d.x); t.y = __builtin_amdgcn_rcpf(d.y);
;     f32x2 q = t * 0.5307027145f + (-0.7265760135f); q = q * t + 0.7107068705f; q = q * t + (-0.142248368f); q = q * t + 0.127414796f; q = q * t;
;     const f32x2 s = (v * v) * (-0.72134752044f);
;     f32x2 e; e.x = __builtin_amdgcn_exp2f(s.x); e.y = __builtin_amdgcn_exp2f(s.y);
;     const f32x2 m = v * (q * e), r = v - m;
;     f32x2 o; o.x = v.x < 0.f ? m.x : r.x; o.y = v.y < 0.f ? m.y : r.y; return o;
; }
;     __device__ __forceinline__ void operator()(const f32x4 (&acc)[2][2][4][2], const Unit& u, int wr, int wc, int fr, int fq) const {
;     ...
;                     const f32x4 v0 = acc[ai][bj][m][0] * r + bv[bj][0], v1 = acc[ai][bj][m][1] * r + bv[bj][1];
;                     const f32x2 a = gelu_pk((f32x2){v0[0], v0[1]}), b = gelu_pk((f32x2){v0[2], v0[3]}), c = gelu_pk((f32x2){v1[0], v1[1]}), d = gelu_pk((f32x2){v1[2], v1[3]});
;                     ss += a.x * a.x + a.y * a.y + b.x * b.x + b.y * b.y + c.x * c.x + c.y * c.y + d.x * d.x + d.y * d.y;
;                     u32x4 w; w.x = cvt_pk_bf16(a.x, a.y); w.y = cvt_pk_bf16(b.x, b.y); w.z = cvt_pk_bf16(c.x, c.y); w.w = cvt_pk_bf16(d.x, d.y);
;                     *(u32x4*)(rowp + bj * HALF) = w;
;                 }
;                 ss += __shfl_xor(ss, 16); ss += __shfl_xor(ss, 32);
;                 if (isv && fq == 0) stat_add(stats_v + row, ss);
	v_pk_mul_f32 v[140:141], v[134:135], v[134:135]
	v_pk_mul_f32 v[138:139], v[142:143], v[138:139]
	s_nop 0
	v_pk_mul_f32 v[142:143], v[132:133], v[138:139]
	v_pk_fma_f32 v[138:139], v[132:133], v[138:139], v[132:133] neg_lo:[1,0,0] neg_hi:[1,0,0]
	v_and_b32_e32 v132, 0x7fffffff, v134
	v_cndmask_b32_e32 v142, v138, v142, vcc
	v_cmp_gt_f32_e32 vcc, 0, v133
	v_and_b32_e32 v133, 0x7fffffff, v135
	v_pk_fma_f32 v[132:133], v[132:133], s[64:65], 1.0 op_sel_hi:[1,0,0]
	v_cndmask_b32_e32 v143, v139, v143, vcc
	v_rcp_f32_e32 v132, v132
	v_rcp_f32_e32 v133, v133
	v_cmp_gt_f32_e32 vcc, 0, v134
	v_pk_fma_f32 v[138:139], v[132:133], s[74:75], v[136:137] op_sel_hi:[1,0,0]
	s_nop 0
	v_pk_fma_f32 v[138:139], v[132:133], v[138:139], s[86:87] op_sel_hi:[1,1,0]
	s_nop 0
	v_pk_fma_f32 v[138:139], v[132:133], v[138:139], s[0:1] op_sel_hi:[1,1,0]
	s_nop 0
	v_pk_fma_f32 v[138:139], v[132:133], v[138:139], s[4:5] op_sel_hi:[1,1,0]
	s_nop 0
	v_pk_mul_f32 v[132:133], v[132:133], v[138:139]
	v_pk_mul_f32 v[138:139], v[140:141], s[30:31] op_sel_hi:[1,0]
	s_nop 0
	v_exp_f32_e32 v138, v138
	v_exp_f32_e32 v139, v139
	s_nop 0
	v_pk_mul_f32 v[132:133], v[138:139], v[132:133]
	s_nop 0
	v_pk_mul_f32 v[138:139], v[134:135], v[132:133]
	v_pk_fma_f32 v[132:133], v[134:135], v[132:133], v[134:135] neg_lo:[1,0,0] neg_hi:[1,0,0]
	s_nop 0
	v_cndmask_b32_e32 v140, v132, v138, vcc
	v_cmp_gt_f32_e32 vcc, 0, v135
	v_and_b32_e32 v132, 0x7fffffff, v128
	s_nop 0
	v_cndmask_b32_e32 v141, v133, v139, vcc
	v_and_b32_e32 v133, 0x7fffffff, v129
	v_pk_fma_f32 v[132:133], v[132:133], s[64:65], 1.0 op_sel_hi:[1,0,0]
	v_pk_mul_f32 v[138:139], v[128:129], v[128:129]
	v_rcp_f32_e32 v132, v132
	v_rcp_f32_e32 v133, v133
	v_pk_mul_f32 v[138:139], v[138:139], s[30:31] op_sel_hi:[1,0]
	v_cmp_gt_f32_e32 vcc, 0, v128
	v_exp_f32_e32 v138, v138
	v_pk_fma_f32 v[134:135], v[132:133], s[74:75], v[136:137] op_sel_hi:[1,0,0]
	v_exp_f32_e32 v139, v139
	v_pk_fma_f32 v[134:135], v[132:133], v[134:135], s[86:87] op_sel_hi:[1,1,0]
	s_nop 0
	v_pk_fma_f32 v[134:135], v[132:133], v[134:135], s[0:1] op_sel_hi:[1,1,0]
	s_nop 0
	v_pk_fma_f32 v[134:135], v[132:133], v[134:135], s[4:5] op_sel_hi:[1,1,0]
	s_nop 0
	v_pk_mul_f32 v[132:133], v[132:133], v[134:135]
	v_pk_mul_f32 v[134:135], v[130:131], v[130:131]
	v_pk_mul_f32 v[132:133], v[138:139], v[132:133]
	s_nop 0
	v_pk_mul_f32 v[138:139], v[128:129], v[132:133]
	v_pk_fma_f32 v[132:133], v[128:129], v[132:133], v[128:129] neg_lo:[1,0,0] neg_hi:[1,0,0]
	v_and_b32_e32 v128, 0x7fffffff, v130
	v_cndmask_b32_e32 v138, v132, v138, vcc
	v_cmp_gt_f32_e32 vcc, 0, v129
	v_and_b32_e32 v129, 0x7fffffff, v131
	v_pk_fma_f32 v[128:129], v[128:129], s[64:65], 1.0 op_sel_hi:[1,0,0]
	v_cndmask_b32_e32 v139, v133, v139, vcc
	v_rcp_f32_e32 v128, v128
	v_rcp_f32_e32 v129, v129
	v_cmp_gt_f32_e32 vcc, 0, v130
	v_pk_fma_f32 v[132:133], v[128:129], s[74:75], v[136:137] op_sel_hi:[1,0,0]
	s_nop 0
	v_pk_fma_f32 v[132:133], v[128:129], v[132:133], s[86:87] op_sel_hi:[1,1,0]
	s_nop 0
	v_pk_fma_f32 v[132:133], v[128:129], v[132:133], s[0:1] op_sel_hi:[1,1,0]
	s_nop 0
	v_pk_fma_f32 v[132:133], v[128:129], v[132:133], s[4:5] op_sel_hi:[1,1,0]
	s_nop 0
	v_pk_mul_f32 v[128:129], v[128:129], v[132:133]
	v_pk_mul_f32 v[132:133], v[134:135], s[30:31] op_sel_hi:[1,0]
	s_nop 0
	v_exp_f32_e32 v132, v132
	v_exp_f32_e32 v133, v133
	s_nop 0
	v_pk_mul_f32 v[128:129], v[132:133], v[128:129]
	s_nop 0
	v_pk_mul_f32 v[132:133], v[130:131], v[128:129]
	v_pk_fma_f32 v[128:129], v[130:131], v[128:129], v[130:131] neg_lo:[1,0,0] neg_hi:[1,0,0]
	s_nop 0
	v_cndmask_b32_e32 v132, v128, v132, vcc
	v_mul_f32_e32 v128, v143, v143
	v_fmac_f32_e32 v128, v142, v142
	v_fmac_f32_e32 v128, v140, v140
	v_fmac_f32_e32 v128, v141, v141
	v_fmac_f32_e32 v128, v138, v138
	v_cmp_gt_f32_e32 vcc, 0, v131
	v_fmac_f32_e32 v128, v139, v139
	v_fmac_f32_e32 v128, v132, v132
	v_cndmask_b32_e32 v131, v129, v133, vcc
	v_fmac_f32_e32 v128, v131, v131
	v_add_f32_e32 v134, v176, v128
	v_cvt_pk_bf16_f32 v128, v142, v143
	v_cvt_pk_bf16_f32 v129, v140, v141
	v_cvt_pk_bf16_f32 v130, v138, v139
	v_cvt_pk_bf16_f32 v131, v132, v131
	global_store_dwordx4 v[166:167], v[128:131], off offset:256
	s_nop 1
	v_and_b32_e32 v129, 64, v190
	v_xor_b32_e32 v128, 16, v190
	v_add_u32_e32 v129, 64, v129
	v_cmp_lt_i32_e32 vcc, v128, v129
	v_xor_b32_e32 v130, 32, v190
	s_nop 0
	v_cndmask_b32_e32 v128, v190, v128, vcc
	v_lshlrev_b32_e32 v133, 2, v128
	ds_bpermute_b32 v128, v133, v134
	v_cmp_lt_i32_e32 vcc, v130, v129
	s_waitcnt lgkmcnt(0)
	v_add_f32_e32 v128, v134, v128
	v_cndmask_b32_e32 v129, v190, v130, vcc
	v_lshlrev_b32_e32 v134, 2, v129
	ds_bpermute_b32 v129, v134, v128
	s_and_saveexec_b64 s[30:31], s[28:29]
	s_cbranch_execz .LBB0_867
	s_waitcnt lgkmcnt(0)
	v_add_f32_e32 v128, v128, v129
	v_cvt_f64_f32_e32 v[128:129], v128
	v_ldexp_f64 v[128:129], v[128:129], 32
	v_trunc_f64_e32 v[128:129], v[128:129]
	v_ldexp_f64 v[136:137], v[128:129], s93
	v_floor_f64_e32 v[136:137], v[136:137]
	v_fmac_f64_e32 v[128:129], 0xc1f00000, v[136:137]
	v_lshl_add_u64 v[130:131], v[156:157], 3, s[18:19]
	v_cvt_u32_f64_e32 v128, v[128:129]
	v_cvt_u32_f64_e32 v129, v[136:137]
	global_atomic_add_x2 v[130:131], v[128:129], off

; template <class Epi>
; __device__ __forceinline__ void gemm_phase(const int TID, const int BID, LAS unsigned char* lds, const Gemm g, const StaticOrder& S, const Epi& E) {
;     ...
;     for (;;) {
;         const bool has_next = S.next(ui + 1, nxt);
;         const char* nA = has_next ? (const char*)g.A + (size_t)nxt.pm * tstepA : cA; const char* nB = has_next ? (const char*)g.Bt + (size_t)nxt.pn * tstepB : cB;
;     ...
; #pragma unroll
;         for (int a = 0; a < 2; ++a)
; #pragma unroll
;             for (int b = 0; b < 2; ++b)
; #pragma unroll
;                 for (int m = 0; m < 4; ++m)
; #pragma unroll
;                     for (int n = 0; n < 2; ++n) acc[a][b][m][n] = (f32x4){0.f, 0.f, 0.f, 0.f};
;         cur = nxt; cA = nA; cB = nB; ++ui;
.LBB0_924:
	s_ashr_i32 s19, s18, 31
	v_mov_b64_e32 v[0:1], 0x400
	s_lshl_b64 s[22:23], s[18:19], 20
	v_cmp_lt_i64_e32 vcc, s[26:27], v[0:1]
	s_add_u32 s26, s84, s22
	s_addc_u32 s27, s85, s23
	s_and_b64 s[22:23], vcc, exec
	s_cselect_b32 s1, s27, s35
	s_cselect_b32 s4, s26, s34
	s_ashr_i32 s17, s16, 31
	s_lshl_b64 s[22:23], s[16:17], 20
	s_add_u32 s28, s44, s22
	s_addc_u32 s29, s45, s23
	s_and_b64 s[22:23], vcc, exec
	s_cselect_b32 s17, s29, s37
	s_cselect_b32 s19, s28, s36
	s_add_u32 s34, s34, 0x80080
	s_addc_u32 s35, s35, 0
	s_add_u32 s22, s36, 0x100
	v_mov_b32_e32 v0, 0
	s_addc_u32 s23, s37, 0
	s_mov_b32 s64, -2
	v_mov_b32_e32 v1, v0
	v_mov_b32_e32 v2, v0
	v_mov_b32_e32 v3, v0
	v_mov_b32_e32 v4, v0
	v_mov_b32_e32 v5, v0
	v_mov_b32_e32 v6, v0
	v_mov_b32_e32 v7, v0
	v_mov_b32_e32 v16, v0
	v_mov_b32_e32 v17, v0
	v_mov_b32_e32 v18, v0
	v_mov_b32_e32 v19, v0
	v_mov_b32_e32 v20, v0
	v_mov_b32_e32 v21, v0
	v_mov_b32_e32 v22, v0
	v_mov_b32_e32 v23, v0
	v_mov_b32_e32 v32, v0
	v_mov_b32_e32 v33, v0
	v_mov_b32_e32 v34, v0
	v_mov_b32_e32 v35, v0
	v_mov_b32_e32 v36, v0
	v_mov_b32_e32 v37, v0
	v_mov_b32_e32 v38, v0
	v_mov_b32_e32 v39, v0
	v_mov_b32_e32 v48, v0
	v_mov_b32_e32 v49, v0
	v_mov_b32_e32 v50, v0
	v_mov_b32_e32 v51, v0
	v_mov_b32_e32 v52, v0
	v_mov_b32_e32 v53, v0
	v_mov_b32_e32 v54, v0
	v_mov_b32_e32 v55, v0
	v_mov_b32_e32 v8, v0
	v_mov_b32_e32 v9, v0
	v_mov_b32_e32 v10, v0
	v_mov_b32_e32 v11, v0
	v_mov_b32_e32 v12, v0
	v_mov_b32_e32 v13, v0
	v_mov_b32_e32 v14, v0
	v_mov_b32_e32 v15, v0
	v_mov_b32_e32 v24, v0
	v_mov_b32_e32 v25, v0
	v_mov_b32_e32 v26, v0
	v_mov_b32_e32 v27, v0
	v_mov_b32_e32 v28, v0
	v_mov_b32_e32 v29, v0
	v_mov_b32_e32 v30, v0
	v_mov_b32_e32 v31, v0
	v_mov_b32_e32 v40, v0
	v_mov_b32_e32 v41, v0
	v_mov_b32_e32 v42, v0
	v_mov_b32_e32 v43, v0
	v_mov_b32_e32 v44, v0
	v_mov_b32_e32 v45, v0
	v_mov_b32_e32 v46, v0
	v_mov_b32_e32 v47, v0
	v_mov_b32_e32 v56, v0
	v_mov_b32_e32 v57, v0
	v_mov_b32_e32 v58, v0
	v_mov_b32_e32 v59, v0
	v_mov_b32_e32 v60, v0
	v_mov_b32_e32 v61, v0
	v_mov_b32_e32 v62, v0
	v_mov_b32_e32 v63, v0
	v_mov_b32_e32 v64, v0
	v_mov_b32_e32 v65, v0
	v_mov_b32_e32 v66, v0
	v_mov_b32_e32 v67, v0
	v_mov_b32_e32 v68, v0
	v_mov_b32_e32 v69, v0
	v_mov_b32_e32 v70, v0
	v_mov_b32_e32 v71, v0
	v_mov_b32_e32 v80, v0
	v_mov_b32_e32 v81, v0
	v_mov_b32_e32 v82, v0
	v_mov_b32_e32 v83, v0
	v_mov_b32_e32 v84, v0
	v_mov_b32_e32 v85, v0
	v_mov_b32_e32 v86, v0
	v_mov_b32_e32 v87, v0
	v_mov_b32_e32 v96, v0
	v_mov_b32_e32 v97, v0
	v_mov_b32_e32 v98, v0
	v_mov_b32_e32 v99, v0
	v_mov_b32_e32 v100, v0
	v_mov_b32_e32 v101, v0
	v_mov_b32_e32 v102, v0
	v_mov_b32_e32 v103, v0
	v_mov_b32_e32 v112, v0
	v_mov_b32_e32 v113, v0
	v_mov_b32_e32 v114, v0
	v_mov_b32_e32 v115, v0
	v_mov_b32_e32 v116, v0
	v_mov_b32_e32 v117, v0
	v_mov_b32_e32 v118, v0
	v_mov_b32_e32 v119, v0
	v_mov_b32_e32 v72, v0
	v_mov_b32_e32 v73, v0
	v_mov_b32_e32 v74, v0
	v_mov_b32_e32 v75, v0
	v_mov_b32_e32 v76, v0
	v_mov_b32_e32 v77, v0
	v_mov_b32_e32 v78, v0
	v_mov_b32_e32 v79, v0
	v_mov_b32_e32 v88, v0
	v_mov_b32_e32 v89, v0
	v_mov_b32_e32 v90, v0
	v_mov_b32_e32 v91, v0
	v_mov_b32_e32 v92, v0
	v_mov_b32_e32 v93, v0
	v_mov_b32_e32 v94, v0
	v_mov_b32_e32 v95, v0
	v_mov_b32_e32 v104, v0
	v_mov_b32_e32 v105, v0
	v_mov_b32_e32 v106, v0
	v_mov_b32_e32 v107, v0
	v_mov_b32_e32 v108, v0
	v_mov_b32_e32 v109, v0
	v_mov_b32_e32 v110, v0
	v_mov_b32_e32 v111, v0
	v_mov_b32_e32 v120, v0
	v_mov_b32_e32 v121, v0
	v_mov_b32_e32 v122, v0
	v_mov_b32_e32 v123, v0
	v_mov_b32_e32 v124, v0
	v_mov_b32_e32 v125, v0
	v_mov_b32_e32 v126, v0
	v_mov_b32_e32 v127, v0
	s_branch .LBB0_925

; #define PG8_STAGE(bufoff, gbase, voff) do { _Pragma("unroll") for (int _i = 0; _i < 2; ++_i) \
;         __builtin_amdgcn_global_load_lds((const unsigned*)((const char*)(gbase) + (voff)[_i]), (LAS unsigned*)(lds + (bufoff) + ldsw + _i * 8192), 16, 0, 0); } while (0)
; #define PG8_LDA(dst, b, h) do { _Pragma("unroll") for (int m = 0; m < 4; ++m) _Pragma("unroll") for (int k = 0; k < 2; ++k) dst[m][k] = *(const LAS bf16x8*)(lds + PG8_SA(b, h) + aoff + m * 2048 + k * 1024); } while (0)
; #define PG8_LDB(dst, b, h) do { _Pragma("unroll") for (int n = 0; n < 2; ++n) _Pragma("unroll") for (int k = 0; k < 2; ++k) dst[n][k] = *(const LAS bf16x8*)(lds + PG8_SB(b, h) + boff + n * 2048 + k * 1024); } while (0)
; #define PG8_MMA(ai, bj, At, Bt) do { __builtin_amdgcn_s_setprio(1); _Pragma("unroll") for (int m = 0; m < 4; ++m) _Pragma("unroll") for (int n = 0; n < 2; ++n) _Pragma("unroll") for (int k = 0; k < 2; ++k) \
;         acc[ai][bj][m][n] = __builtin_amdgcn_mfma_f32_16x16x32_bf16(Bt[n][k], At[m][k], acc[ai][bj][m][n], 0, 0, 0); __builtin_amdgcn_s_setprio(0); } while (0)
; #define PG8_WAIT_L(n) asm volatile("s_waitcnt lgkmcnt(" #n ")" ::: "memory")
; #define PG8_BAR __builtin_amdgcn_s_barrier()
; #define PG8_SCHED __builtin_amdgcn_sched_barrier(0)
; template <class Epi>
; __device__ __forceinline__ void gemm_phase(const int TID, const int BID, LAS unsigned char* lds, const Gemm g, const StaticOrder& S, const Epi& E) {
;     ...
;             const bool last = (t == nt - 2);
;             const char* a1 = cA + (size_t)(t + 1) * kstep;
;             const char* a2 = last ? nA : cA + (size_t)(t + 2) * kstep; const char* b2 = last ? nB : cB + (size_t)(t + 2) * kstep;
;             const char* a3 = a2 + kstep; const char* b3 = b2 + kstep;
;             PG8_LDB(B0, 0, 0); PG8_SCHED; PG8_LDA(At, 0, 0); PG8_STAGE(PG8_SA(1, 1), a1 + hstepA, voffA);
;             PG8_WAIT_L(8); PG8_BAR; PG8_WAIT_L(0); PG8_MMA(0, 0, At, B0); PG8_BAR; PG8_SCHED;
;             PG8_LDB(B1, 0, 1); PG8_STAGE(PG8_SB(0, 0), b2, voffB);
;             PG8_BAR; PG8_WAIT_L(0); PG8_MMA(0, 1, At, B1); PG8_BAR;
;             PG8_LDA(At, 0, 1); PG8_STAGE(PG8_SA(0, 0), a2, voffA);
;             PG8_BAR; PG8_WAIT_L(0); PG8_MMA(1, 0, At, B0); PG8_BAR; PG8_SCHED;
.LBB0_925:
	v_add_u32_e32 v154, s31, v147
	ds_read_b128 v[138:141], v154
	ds_read_b128 v[142:145], v154 offset:1024
	ds_read_b128 v[150:153], v154 offset:2048
	ds_read_b128 v[154:157], v154 offset:3072
	s_add_u32 s36, s34, 0xfff80080
	s_addc_u32 s37, s35, -1
	s_cmp_eq_u32 s64, 28
	s_cselect_b32 s39, s1, s37
	s_cselect_b32 s38, s4, s36
	s_cselect_b32 s37, s17, s23
	s_cselect_b32 s36, s19, s22
	v_lshl_add_u64 v[158:159], s[34:35], 0, v[134:135]
	s_add_i32 m0, s48, 0xc000
	ds_read_b128 v[166:169], v149
	ds_read_b128 v[170:173], v149 offset:1024
	ds_read_b128 v[174:177], v149 offset:2048
	ds_read_b128 v[178:181], v149 offset:3072
	ds_read_b128 v[182:185], v149 offset:4096
	ds_read_b128 v[196:199], v149 offset:5120
	ds_read_b128 v[208:211], v149 offset:6144
	ds_read_b128 v[212:215], v149 offset:7168
	global_load_lds_dwordx4 v[158:159], off
	s_add_i32 m0, s48, 0xe000
	v_lshl_add_u64 v[158:159], s[34:35], 0, v[136:137]
	global_load_lds_dwordx4 v[158:159], off
	s_waitcnt lgkmcnt(8)
	s_barrier
	s_waitcnt lgkmcnt(0)
	s_setprio 1
	v_mfma_f32_16x16x32_bf16 v[124:127], v[138:141], v[166:169], v[124:127]
	v_mfma_f32_16x16x32_bf16 v[120:123], v[150:153], v[166:169], v[120:123]
	v_mfma_f32_16x16x32_bf16 v[108:111], v[138:141], v[174:177], v[108:111]
	v_mfma_f32_16x16x32_bf16 v[104:107], v[150:153], v[174:177], v[104:107]
	v_mfma_f32_16x16x32_bf16 v[92:95], v[138:141], v[182:185], v[92:95]
	v_mfma_f32_16x16x32_bf16 v[88:91], v[150:153], v[182:185], v[88:91]
	v_mfma_f32_16x16x32_bf16 v[76:79], v[138:141], v[208:211], v[76:79]
	v_mfma_f32_16x16x32_bf16 v[72:75], v[150:153], v[208:211], v[72:75]
	v_mfma_f32_16x16x32_bf16 v[124:127], v[142:145], v[170:173], v[124:127]
	v_mfma_f32_16x16x32_bf16 v[120:123], v[154:157], v[170:173], v[120:123]
	v_mfma_f32_16x16x32_bf16 v[108:111], v[142:145], v[178:181], v[108:111]
	v_mfma_f32_16x16x32_bf16 v[104:107], v[154:157], v[178:181], v[104:107]
	v_mfma_f32_16x16x32_bf16 v[92:95], v[142:145], v[196:199], v[92:95]
	v_mfma_f32_16x16x32_bf16 v[88:91], v[154:157], v[196:199], v[88:91]
	v_mfma_f32_16x16x32_bf16 v[76:79], v[142:145], v[212:215], v[76:79]
	v_mfma_f32_16x16x32_bf16 v[72:75], v[154:157], v[212:215], v[72:75]
	s_setprio 0
	s_barrier
	v_add_u32_e32 v158, s50, v147
	s_mov_b32 m0, s46
	ds_read_b128 v[216:219], v158
	ds_read_b128 v[220:223], v158 offset:1024
	ds_read_b128 v[224:227], v158 offset:2048
	ds_read_b128 v[228:231], v158 offset:3072
	v_lshl_add_u64 v[158:159], s[36:37], 0, v[160:161]
	global_load_lds_dwordx4 v[158:159], off
	s_mov_b32 m0, s47
	v_lshl_add_u64 v[200:201], s[36:37], 0, v[132:133]
	global_load_lds_dwordx4 v[200:201], off
	s_barrier
	s_waitcnt lgkmcnt(0)
	s_setprio 1
	v_mfma_f32_16x16x32_bf16 v[116:119], v[216:219], v[166:169], v[116:119]
	v_mfma_f32_16x16x32_bf16 v[112:115], v[224:227], v[166:169], v[112:115]
	v_mfma_f32_16x16x32_bf16 v[100:103], v[216:219], v[174:177], v[100:103]
	v_mfma_f32_16x16x32_bf16 v[96:99], v[224:227], v[174:177], v[96:99]
	v_mfma_f32_16x16x32_bf16 v[84:87], v[216:219], v[182:185], v[84:87]
	v_mfma_f32_16x16x32_bf16 v[80:83], v[224:227], v[182:185], v[80:83]
	v_mfma_f32_16x16x32_bf16 v[68:71], v[216:219], v[208:211], v[68:71]
	v_mfma_f32_16x16x32_bf16 v[64:67], v[224:227], v[208:211], v[64:67]
	v_mfma_f32_16x16x32_bf16 v[116:119], v[220:223], v[170:173], v[116:119]
	v_mfma_f32_16x16x32_bf16 v[112:115], v[228:231], v[170:173], v[112:115]
	v_mfma_f32_16x16x32_bf16 v[100:103], v[220:223], v[178:181], v[100:103]
	v_mfma_f32_16x16x32_bf16 v[96:99], v[228:231], v[178:181], v[96:99]
	v_mfma_f32_16x16x32_bf16 v[84:87], v[220:223], v[196:199], v[84:87]
	v_mfma_f32_16x16x32_bf16 v[80:83], v[228:231], v[196:199], v[80:83]
	v_mfma_f32_16x16x32_bf16 v[68:71], v[220:223], v[212:215], v[68:71]
	v_mfma_f32_16x16x32_bf16 v[64:67], v[228:231], v[212:215], v[64:67]
	s_setprio 0
	s_mov_b32 m0, s48
	v_lshl_add_u64 v[232:233], s[38:39], 0, v[128:129]
	s_barrier
	ds_read_b128 v[166:169], v149 offset:16384
	ds_read_b128 v[170:173], v149 offset:17408
	ds_read_b128 v[174:177], v149 offset:18432
	ds_read_b128 v[178:181], v149 offset:19456
	ds_read_b128 v[182:185], v149 offset:20480
	ds_read_b128 v[196:199], v149 offset:21504
	ds_read_b128 v[208:211], v149 offset:22528
	ds_read_b128 v[212:215], v149 offset:23552
	global_load_lds_dwordx4 v[232:233], off
	s_mov_b32 m0, s49
	v_lshl_add_u64 v[234:235], s[38:39], 0, v[130:131]
	global_load_lds_dwordx4 v[234:235], off
	s_barrier
	s_waitcnt lgkmcnt(0)
	s_setprio 1
	v_mfma_f32_16x16x32_bf16 v[60:63], v[138:141], v[166:169], v[60:63]
	v_mfma_f32_16x16x32_bf16 v[56:59], v[150:153], v[166:169], v[56:59]
	v_mfma_f32_16x16x32_bf16 v[44:47], v[138:141], v[174:177], v[44:47]
	v_mfma_f32_16x16x32_bf16 v[40:43], v[150:153], v[174:177], v[40:43]
	v_mfma_f32_16x16x32_bf16 v[28:31], v[138:141], v[182:185], v[28:31]
	v_mfma_f32_16x16x32_bf16 v[24:27], v[150:153], v[182:185], v[24:27]
	v_mfma_f32_16x16x32_bf16 v[12:15], v[138:141], v[208:211], v[12:15]
	v_mfma_f32_16x16x32_bf16 v[8:11], v[150:153], v[208:211], v[8:11]
	v_mfma_f32_16x16x32_bf16 v[60:63], v[142:145], v[170:173], v[60:63]
	v_mfma_f32_16x16x32_bf16 v[56:59], v[154:157], v[170:173], v[56:59]
	v_mfma_f32_16x16x32_bf16 v[44:47], v[142:145], v[178:181], v[44:47]
	v_mfma_f32_16x16x32_bf16 v[40:43], v[154:157], v[178:181], v[40:43]
	v_mfma_f32_16x16x32_bf16 v[28:31], v[142:145], v[196:199], v[28:31]
	v_mfma_f32_16x16x32_bf16 v[24:27], v[154:157], v[196:199], v[24:27]
	v_mfma_f32_16x16x32_bf16 v[12:15], v[142:145], v[212:215], v[12:15]
	v_mfma_f32_16x16x32_bf16 v[8:11], v[154:157], v[212:215], v[8:11]
	s_setprio 0
	s_barrier
; #define PG8_STAGE(bufoff, gbase, voff) do { _Pragma("unroll") for (int _i = 0; _i < 2; ++_i) \
;         __builtin_amdgcn_global_load_lds((const unsigned*)((const char*)(gbase) + (voff)[_i]), (LAS unsigned*)(lds + (bufoff) + ldsw + _i * 8192), 16, 0, 0); } while (0)
; #define PG8_LDA(dst, b, h) do { _Pragma("unroll") for (int m = 0; m < 4; ++m) _Pragma("unroll") for (int k = 0; k < 2; ++k) dst[m][k] = *(const LAS bf16x8*)(lds + PG8_SA(b, h) + aoff + m * 2048 + k * 1024); } while (0)
; #define PG8_LDB(dst, b, h) do { _Pragma("unroll") for (int n = 0; n < 2; ++n) _Pragma("unroll") for (int k = 0; k < 2; ++k) dst[n][k] = *(const LAS bf16x8*)(lds + PG8_SB(b, h) + boff + n * 2048 + k * 1024); } while (0)
; #define PG8_MMA(ai, bj, At, Bt) do { __builtin_amdgcn_s_setprio(1); _Pragma("unroll") for (int m = 0; m < 4; ++m) _Pragma("unroll") for (int n = 0; n < 2; ++n) _Pragma("unroll") for (int k = 0; k < 2; ++k) \
;         acc[ai][bj][m][n] = __builtin_amdgcn_mfma_f32_16x16x32_bf16(Bt[n][k], At[m][k], acc[ai][bj][m][n], 0, 0, 0); __builtin_amdgcn_s_setprio(0); } while (0)
; #define PG8_WAIT_V(n) asm volatile("s_waitcnt vmcnt(" #n ")" ::: "memory")
; #define PG8_WAIT_L(n) asm volatile("s_waitcnt lgkmcnt(" #n ")" ::: "memory")
; #define PG8_BAR __builtin_amdgcn_s_barrier()
; #define PG8_SCHED __builtin_amdgcn_sched_barrier(0)
; template <class Epi>
; __device__ __forceinline__ void gemm_phase(const int TID, const int BID, LAS unsigned char* lds, const Gemm g, const StaticOrder& S, const Epi& E) {
;     ...
;             PG8_STAGE(PG8_SB(0, 1), b2 + hstepB, voffB);
;             PG8_WAIT_V(6); PG8_BAR; PG8_MMA(1, 1, At, B1); PG8_BAR;
;             PG8_LDB(B0, 1, 0); PG8_SCHED; PG8_LDA(At, 1, 0); PG8_STAGE(PG8_SA(0, 1), a2 + hstepA, voffA);
;             PG8_WAIT_L(8); PG8_BAR; PG8_WAIT_L(0); PG8_MMA(0, 0, At, B0); PG8_BAR; PG8_SCHED;
;             PG8_LDB(B1, 1, 1); PG8_STAGE(PG8_SB(1, 0), b3, voffB);
;             PG8_BAR; PG8_WAIT_L(0); PG8_MMA(0, 1, At, B1); PG8_BAR;
;             PG8_LDA(At, 1, 1); PG8_STAGE(PG8_SA(1, 0), a3, voffA);
;             PG8_BAR; PG8_WAIT_L(0); PG8_MMA(1, 0, At, B0); PG8_BAR; PG8_SCHED;
	s_add_u32 s66, s36, 0x80000
	s_addc_u32 s67, s37, 0
	s_mov_b32 m0, s51
	v_lshl_add_u64 v[138:139], s[66:67], 0, v[160:161]
	global_load_lds_dwordx4 v[138:139], off
	s_mov_b32 m0, s52
	v_lshl_add_u64 v[138:139], s[66:67], 0, v[132:133]
	global_load_lds_dwordx4 v[138:139], off
	s_waitcnt vmcnt(6)
	s_barrier
	s_setprio 1
	v_mfma_f32_16x16x32_bf16 v[52:55], v[216:219], v[166:169], v[52:55]
	v_mfma_f32_16x16x32_bf16 v[48:51], v[224:227], v[166:169], v[48:51]
	v_mfma_f32_16x16x32_bf16 v[36:39], v[216:219], v[174:177], v[36:39]
	v_mfma_f32_16x16x32_bf16 v[32:35], v[224:227], v[174:177], v[32:35]
	v_mfma_f32_16x16x32_bf16 v[20:23], v[216:219], v[182:185], v[20:23]
	v_mfma_f32_16x16x32_bf16 v[16:19], v[224:227], v[182:185], v[16:19]
	v_mfma_f32_16x16x32_bf16 v[4:7], v[216:219], v[208:211], v[4:7]
	v_mfma_f32_16x16x32_bf16 v[0:3], v[224:227], v[208:211], v[0:3]
	v_mfma_f32_16x16x32_bf16 v[52:55], v[220:223], v[170:173], v[52:55]
	v_mfma_f32_16x16x32_bf16 v[48:51], v[228:231], v[170:173], v[48:51]
	v_mfma_f32_16x16x32_bf16 v[36:39], v[220:223], v[178:181], v[36:39]
	v_mfma_f32_16x16x32_bf16 v[32:35], v[228:231], v[178:181], v[32:35]
	v_mfma_f32_16x16x32_bf16 v[20:23], v[220:223], v[196:199], v[20:23]
	v_mfma_f32_16x16x32_bf16 v[16:19], v[228:231], v[196:199], v[16:19]
	v_mfma_f32_16x16x32_bf16 v[4:7], v[220:223], v[212:215], v[4:7]
	v_mfma_f32_16x16x32_bf16 v[0:3], v[228:231], v[212:215], v[0:3]
	s_setprio 0
	v_add_u32_e32 v154, s55, v147
	s_barrier
	ds_read_b128 v[138:141], v154
	ds_read_b128 v[142:145], v154 offset:1024
	ds_read_b128 v[150:153], v154 offset:2048
	ds_read_b128 v[154:157], v154 offset:3072
	s_add_u32 s38, s38, 0x80000
	s_addc_u32 s39, s39, 0
	s_mov_b32 m0, s53
	v_lshl_add_u64 v[216:217], s[38:39], 0, v[128:129]
	ds_read_b128 v[166:169], v149 offset:32768
	ds_read_b128 v[170:173], v149 offset:33792
	ds_read_b128 v[174:177], v149 offset:34816
	ds_read_b128 v[178:181], v149 offset:35840
	ds_read_b128 v[182:185], v149 offset:36864
	ds_read_b128 v[196:199], v149 offset:37888
	ds_read_b128 v[208:211], v149 offset:38912
	ds_read_b128 v[212:215], v149 offset:39936
	global_load_lds_dwordx4 v[216:217], off
	s_mov_b32 m0, s54
	v_lshl_add_u64 v[216:217], s[38:39], 0, v[130:131]
	global_load_lds_dwordx4 v[216:217], off
	s_waitcnt lgkmcnt(8)
	s_barrier
	s_waitcnt lgkmcnt(0)
	s_setprio 1
	v_mfma_f32_16x16x32_bf16 v[124:127], v[138:141], v[166:169], v[124:127]
	v_mfma_f32_16x16x32_bf16 v[120:123], v[150:153], v[166:169], v[120:123]
	v_mfma_f32_16x16x32_bf16 v[108:111], v[138:141], v[174:177], v[108:111]
	v_mfma_f32_16x16x32_bf16 v[104:107], v[150:153], v[174:177], v[104:107]
	v_mfma_f32_16x16x32_bf16 v[92:95], v[138:141], v[182:185], v[92:95]
	v_mfma_f32_16x16x32_bf16 v[88:91], v[150:153], v[182:185], v[88:91]
	v_mfma_f32_16x16x32_bf16 v[76:79], v[138:141], v[208:211], v[76:79]
	v_mfma_f32_16x16x32_bf16 v[72:75], v[150:153], v[208:211], v[72:75]
	v_mfma_f32_16x16x32_bf16 v[124:127], v[142:145], v[170:173], v[124:127]
	v_mfma_f32_16x16x32_bf16 v[120:123], v[154:157], v[170:173], v[120:123]
	v_mfma_f32_16x16x32_bf16 v[108:111], v[142:145], v[178:181], v[108:111]
	v_mfma_f32_16x16x32_bf16 v[104:107], v[154:157], v[178:181], v[104:107]
	v_mfma_f32_16x16x32_bf16 v[92:95], v[142:145], v[196:199], v[92:95]
	v_mfma_f32_16x16x32_bf16 v[88:91], v[154:157], v[196:199], v[88:91]
	v_mfma_f32_16x16x32_bf16 v[76:79], v[142:145], v[212:215], v[76:79]
	v_mfma_f32_16x16x32_bf16 v[72:75], v[154:157], v[212:215], v[72:75]
	s_setprio 0
	s_barrier
	s_mov_b32 m0, s56
	v_add_u32_e32 v228, s60, v147
	v_lshl_add_u64 v[158:159], v[158:159], 0, s[90:91]
	ds_read_b128 v[216:219], v228
	ds_read_b128 v[220:223], v228 offset:1024
	ds_read_b128 v[224:227], v228 offset:2048
	ds_read_b128 v[228:231], v228 offset:3072
	global_load_lds_dwordx4 v[158:159], off
	s_mov_b32 m0, s57
	v_lshl_add_u64 v[158:159], v[200:201], 0, s[90:91]
	global_load_lds_dwordx4 v[158:159], off
	s_barrier
	s_waitcnt lgkmcnt(0)
	s_setprio 1
	v_mfma_f32_16x16x32_bf16 v[116:119], v[216:219], v[166:169], v[116:119]
	v_mfma_f32_16x16x32_bf16 v[112:115], v[224:227], v[166:169], v[112:115]
	v_mfma_f32_16x16x32_bf16 v[100:103], v[216:219], v[174:177], v[100:103]
	v_mfma_f32_16x16x32_bf16 v[96:99], v[224:227], v[174:177], v[96:99]
	v_mfma_f32_16x16x32_bf16 v[84:87], v[216:219], v[182:185], v[84:87]
	v_mfma_f32_16x16x32_bf16 v[80:83], v[224:227], v[182:185], v[80:83]
	v_mfma_f32_16x16x32_bf16 v[68:71], v[216:219], v[208:211], v[68:71]
	v_mfma_f32_16x16x32_bf16 v[64:67], v[224:227], v[208:211], v[64:67]
	v_mfma_f32_16x16x32_bf16 v[116:119], v[220:223], v[170:173], v[116:119]
	v_mfma_f32_16x16x32_bf16 v[112:115], v[228:231], v[170:173], v[112:115]
	v_mfma_f32_16x16x32_bf16 v[100:103], v[220:223], v[178:181], v[100:103]
	v_mfma_f32_16x16x32_bf16 v[96:99], v[228:231], v[178:181], v[96:99]
	v_mfma_f32_16x16x32_bf16 v[84:87], v[220:223], v[196:199], v[84:87]
	v_mfma_f32_16x16x32_bf16 v[80:83], v[228:231], v[196:199], v[80:83]
	v_mfma_f32_16x16x32_bf16 v[68:71], v[220:223], v[212:215], v[68:71]
	v_mfma_f32_16x16x32_bf16 v[64:67], v[228:231], v[212:215], v[64:67]
	s_setprio 0
	s_mov_b32 m0, s58
	v_lshl_add_u64 v[158:159], v[232:233], 0, s[90:91]
	s_barrier
	ds_read_b128 v[166:169], v149 offset:49152
	ds_read_b128 v[170:173], v149 offset:50176
	ds_read_b128 v[174:177], v149 offset:51200
	ds_read_b128 v[178:181], v149 offset:52224
	ds_read_b128 v[182:185], v149 offset:53248
	ds_read_b128 v[196:199], v149 offset:54272
	ds_read_b128 v[208:211], v149 offset:55296
	ds_read_b128 v[212:215], v149 offset:56320
	global_load_lds_dwordx4 v[158:159], off
	s_mov_b32 m0, s59
	v_lshl_add_u64 v[158:159], v[234:235], 0, s[90:91]
	global_load_lds_dwordx4 v[158:159], off
	s_barrier
; __device__ __forceinline__ unsigned cvt_pk_bf16(float lo, float hi) { unsigned r; asm volatile("v_cvt_pk_bf16_f32 %0, %1, %2" : "=v"(r) : "v"(lo), "v"(hi)); return r; }
; __device__ __forceinline__ float rinv_st(stat_t s, float invn) { return rsqrtf((float)((double)s * (1.0 / 4294967296.0)) * invn + 1e-6f); }
; #define PG8_STAGE(bufoff, gbase, voff) do { _Pragma("unroll") for (int _i = 0; _i < 2; ++_i) \
;         __builtin_amdgcn_global_load_lds((const unsigned*)((const char*)(gbase) + (voff)[_i]), (LAS unsigned*)(lds + (bufoff) + ldsw + _i * 8192), 16, 0, 0); } while (0)
; #define PG8_WAIT_V(n) asm volatile("s_waitcnt vmcnt(" #n ")" ::: "memory")
; #define PG8_WAIT_L(n) asm volatile("s_waitcnt lgkmcnt(" #n ")" ::: "memory")
; #define PG8_BAR __builtin_amdgcn_s_barrier()
; #define PG8_SCHED __builtin_amdgcn_sched_barrier(0)
; template <class Epi>
; __device__ __forceinline__ void gemm_phase(const int TID, const int BID, LAS unsigned char* lds, const Gemm g, const StaticOrder& S, const Epi& E) {
;     ...
;             PG8_BAR; PG8_WAIT_L(0); PG8_MMA(1, 0, At, B0); PG8_BAR; PG8_SCHED;
;             PG8_STAGE(PG8_SB(1, 1), b3 + hstepB, voffB);
;             PG8_WAIT_V(6); PG8_BAR; PG8_MMA(1, 1, At, B1); PG8_BAR;
;     __device__ __forceinline__ void operator()(const f32x4 (&acc)[2][2][4][2], const Unit& u, int wr, int wc, int fr, int fq) const {
;         const int row0 = u.pm * BM + wr * 64 + fr, col0 = u.pn * BM + wc * 32 + 8 * fq;
; #pragma unroll
;         for (int ai = 0; ai < 2; ++ai)
; #pragma unroll
;             for (int m = 0; m < 4; ++m) {
;                 const int row = row0 + ai * HALF + m * 16; const float r = rinv_st(stats[row], 1.0f / 2048.0f);
;                 bf16_t* rowp = U + (size_t)row * FF + col0;
; #pragma unroll
;                 for (int bj = 0; bj < 2; ++bj) {
;                     f32x4 v0 = acc[ai][bj][m][0] * r, v1 = acc[ai][bj][m][1] * r;
; #pragma unroll
;                     for (int j = 0; j < 4; ++j) { const float a = fmaxf(v0[j], 0.f), b = fmaxf(v1[j], 0.f); v0[j] = a * a; v1[j] = b * b; }
;                     u32x4 w; w.x = cvt_pk_bf16(v0[0], v0[1]); w.y = cvt_pk_bf16(v0[2], v0[3]); w.z = cvt_pk_bf16(v1[0], v1[1]); w.w = cvt_pk_bf16(v1[2], v1[3]);
;                     *(u32x4*)(rowp + bj * HALF) = w;
;                 }
	s_waitcnt lgkmcnt(0)
	s_setprio 1
	v_mfma_f32_16x16x32_bf16 v[60:63], v[138:141], v[166:169], v[60:63]
	v_mfma_f32_16x16x32_bf16 v[56:59], v[150:153], v[166:169], v[56:59]
	v_mfma_f32_16x16x32_bf16 v[44:47], v[138:141], v[174:177], v[44:47]
	v_mfma_f32_16x16x32_bf16 v[40:43], v[150:153], v[174:177], v[40:43]
	v_mfma_f32_16x16x32_bf16 v[28:31], v[138:141], v[182:185], v[28:31]
	v_mfma_f32_16x16x32_bf16 v[24:27], v[150:153], v[182:185], v[24:27]
	v_mfma_f32_16x16x32_bf16 v[12:15], v[138:141], v[208:211], v[12:15]
	v_mfma_f32_16x16x32_bf16 v[8:11], v[150:153], v[208:211], v[8:11]
	v_mfma_f32_16x16x32_bf16 v[60:63], v[142:145], v[170:173], v[60:63]
	v_mfma_f32_16x16x32_bf16 v[56:59], v[154:157], v[170:173], v[56:59]
	v_mfma_f32_16x16x32_bf16 v[44:47], v[142:145], v[178:181], v[44:47]
	v_mfma_f32_16x16x32_bf16 v[40:43], v[154:157], v[178:181], v[40:43]
	v_mfma_f32_16x16x32_bf16 v[28:31], v[142:145], v[196:199], v[28:31]
	v_mfma_f32_16x16x32_bf16 v[24:27], v[154:157], v[196:199], v[24:27]
	v_mfma_f32_16x16x32_bf16 v[12:15], v[142:145], v[212:215], v[12:15]
	v_mfma_f32_16x16x32_bf16 v[8:11], v[154:157], v[212:215], v[8:11]
	s_setprio 0
	s_barrier
	s_add_u32 s36, s36, 0x80080
	s_addc_u32 s37, s37, 0
	s_mov_b32 m0, s61
	v_lshl_add_u64 v[138:139], s[36:37], 0, v[160:161]
	global_load_lds_dwordx4 v[138:139], off
	s_mov_b32 m0, s62
	v_lshl_add_u64 v[138:139], s[36:37], 0, v[132:133]
	global_load_lds_dwordx4 v[138:139], off
	s_waitcnt vmcnt(6)
	s_barrier
	s_setprio 1
	v_mfma_f32_16x16x32_bf16 v[52:55], v[216:219], v[166:169], v[52:55]
	v_mfma_f32_16x16x32_bf16 v[48:51], v[224:227], v[166:169], v[48:51]
	v_mfma_f32_16x16x32_bf16 v[36:39], v[216:219], v[174:177], v[36:39]
	v_mfma_f32_16x16x32_bf16 v[32:35], v[224:227], v[174:177], v[32:35]
	v_mfma_f32_16x16x32_bf16 v[20:23], v[216:219], v[182:185], v[20:23]
	v_mfma_f32_16x16x32_bf16 v[16:19], v[224:227], v[182:185], v[16:19]
	v_mfma_f32_16x16x32_bf16 v[4:7], v[216:219], v[208:211], v[4:7]
	v_mfma_f32_16x16x32_bf16 v[0:3], v[224:227], v[208:211], v[0:3]
	v_mfma_f32_16x16x32_bf16 v[52:55], v[220:223], v[170:173], v[52:55]
	v_mfma_f32_16x16x32_bf16 v[48:51], v[228:231], v[170:173], v[48:51]
	v_mfma_f32_16x16x32_bf16 v[36:39], v[220:223], v[178:181], v[36:39]
	v_mfma_f32_16x16x32_bf16 v[32:35], v[228:231], v[178:181], v[32:35]
	v_mfma_f32_16x16x32_bf16 v[20:23], v[220:223], v[196:199], v[20:23]
	v_mfma_f32_16x16x32_bf16 v[16:19], v[228:231], v[196:199], v[16:19]
	v_mfma_f32_16x16x32_bf16 v[4:7], v[220:223], v[212:215], v[4:7]
	v_mfma_f32_16x16x32_bf16 v[0:3], v[228:231], v[212:215], v[0:3]
	s_setprio 0
	s_add_i32 s64, s64, 2
	s_add_u32 s34, s34, 0x100
	s_addc_u32 s35, s35, 0
	s_add_u32 s22, s22, 0x100
	s_addc_u32 s23, s23, 0
	s_cmp_gt_u32 s64, 29
	s_cbranch_scc0 .Lrot_925
	s_barrier
	v_lshl_add_u32 v142, s30, 8, v146
	v_ashrrev_i32_e32 v143, 31, v142
	v_lshl_add_u64 v[138:139], v[142:143], 3, s[10:11]
	v_lshl_or_b32 v140, s0, 8, v148
	v_ashrrev_i32_e32 v141, 31, v140
	s_mov_b64 s[0:1], 0x200000
	s_mov_b32 s30, s18
	s_mov_b64 s[36:37], s[28:29]
	s_mov_b64 s[34:35], s[26:27]
	v_mov_b64_e32 v[144:145], v[236:237]
	v_cvt_f64_u32_e32 v[150:151], v145
	v_ldexp_f64 v[150:151], v[150:151], 32
	v_cvt_f64_u32_e32 v[144:145], v144
	v_add_f64 v[144:145], v[150:151], v[144:145]
	v_ldexp_f64 v[144:145], v[144:145], s93
	v_cvt_f32_f64_e32 v144, v[144:145]
	v_fmamk_f32 v144, v144, 0x3a000000, v189
	v_cmp_gt_f32_e32 vcc, s78, v144
	v_mul_f32_e32 v145, 0x4b800000, v144
	s_nop 0
	v_cndmask_b32_e32 v144, v144, v145, vcc
	v_rsq_f32_e32 v144, v144
	s_nop 0
	v_mul_f32_e32 v145, 0x45800000, v144
	v_cndmask_b32_e32 v150, v144, v145, vcc
	v_pk_mul_f32 v[120:121], v[120:121], v[150:151] op_sel_hi:[1,0]
	v_pk_mul_f32 v[124:125], v[124:125], v[150:151] op_sel_hi:[1,0]
	v_pk_mul_f32 v[122:123], v[122:123], v[150:151] op_sel_hi:[1,0]
	v_max_f32_e32 v120, 0, v120
	v_lshlrev_b64 v[144:145], 14, v[142:143]
	v_pk_mul_f32 v[126:127], v[126:127], v[150:151] op_sel_hi:[1,0]
	v_mul_f32_e32 v143, v120, v120
	v_max_f32_e32 v120, 0, v125
	v_max_f32_e32 v121, 0, v121
	v_max_f32_e32 v122, 0, v122
	v_lshl_add_u64 v[152:153], s[14:15], 0, v[144:145]
	v_lshlrev_b64 v[144:145], 1, v[140:141]
	v_max_f32_e32 v124, 0, v124
	v_mul_f32_e32 v120, v120, v120
	v_mul_f32_e32 v125, v121, v121
	v_max_f32_e32 v121, 0, v126
	v_mul_f32_e32 v126, v122, v122
	v_max_f32_e32 v122, 0, v127
	v_max_f32_e32 v123, 0, v123
	v_pk_mul_f32 v[114:115], v[114:115], v[150:151] op_sel_hi:[1,0]
	v_pk_mul_f32 v[112:113], v[112:113], v[150:151] op_sel_hi:[1,0]
	v_lshl_add_u64 v[140:141], v[152:153], 0, v[144:145]
	v_mul_f32_e32 v124, v124, v124
	v_mul_f32_e32 v121, v121, v121
	v_mul_f32_e32 v122, v122, v122
	v_mul_f32_e32 v123, v123, v123
	v_cvt_pk_bf16_f32 v120, v124, v120
	v_pk_mul_f32 v[118:119], v[118:119], v[150:151] op_sel_hi:[1,0]
	v_pk_mul_f32 v[116:117], v[116:117], v[150:151] op_sel_hi:[1,0]
	v_max_f32_e32 v112, 0, v112
	v_max_f32_e32 v113, 0, v113
	v_max_f32_e32 v114, 0, v114
	v_cvt_pk_bf16_f32 v121, v121, v122
	v_cvt_pk_bf16_f32 v122, v143, v125
	v_cvt_pk_bf16_f32 v123, v126, v123
	global_store_dwordx4 v[140:141], v[120:123], off
	v_max_f32_e32 v115, 0, v115
	v_max_f32_e32 v116, 0, v116
	v_mul_f32_e32 v120, v112, v112
	v_max_f32_e32 v112, 0, v117
	v_mul_f32_e32 v117, v113, v113
	v_max_f32_e32 v113, 0, v118
	v_mul_f32_e32 v118, v114, v114
	v_max_f32_e32 v114, 0, v119
	v_mul_f32_e32 v112, v112, v112
	v_mul_f32_e32 v113, v113, v113
	v_mul_f32_e32 v114, v114, v114
	v_mul_f32_e32 v115, v115, v115
	v_mul_f32_e32 v116, v116, v116
	v_cvt_pk_bf16_f32 v112, v116, v112
	v_cvt_pk_bf16_f32 v113, v113, v114
	v_cvt_pk_bf16_f32 v114, v120, v117
	v_cvt_pk_bf16_f32 v115, v118, v115
; __device__ __forceinline__ unsigned cvt_pk_bf16(float lo, float hi) { unsigned r; asm volatile("v_cvt_pk_bf16_f32 %0, %1, %2" : "=v"(r) : "v"(lo), "v"(hi)); return r; }
; __device__ __forceinline__ float rinv_st(stat_t s, float invn) { return rsqrtf((float)((double)s * (1.0 / 4294967296.0)) * invn + 1e-6f); }
;     __device__ __forceinline__ void operator()(const f32x4 (&acc)[2][2][4][2], const Unit& u, int wr, int wc, int fr, int fq) const {
;         const int row0 = u.pm * BM + wr * 64 + fr, col0 = u.pn * BM + wc * 32 + 8 * fq;
; #pragma unroll
;         for (int ai = 0; ai < 2; ++ai)
; #pragma unroll
;             for (int m = 0; m < 4; ++m) {
;                 const int row = row0 + ai * HALF + m * 16; const float r = rinv_st(stats[row], 1.0f / 2048.0f);
;                 bf16_t* rowp = U + (size_t)row * FF + col0;
; #pragma unroll
;                 for (int bj = 0; bj < 2; ++bj) {
;                     f32x4 v0 = acc[ai][bj][m][0] * r, v1 = acc[ai][bj][m][1] * r;
; #pragma unroll
;                     for (int j = 0; j < 4; ++j) { const float a = fmaxf(v0[j], 0.f), b = fmaxf(v1[j], 0.f); v0[j] = a * a; v1[j] = b * b; }
;                     u32x4 w; w.x = cvt_pk_bf16(v0[0], v0[1]); w.y = cvt_pk_bf16(v0[2], v0[3]); w.z = cvt_pk_bf16(v1[0], v1[1]); w.w = cvt_pk_bf16(v1[2], v1[3]);
;                     *(u32x4*)(rowp + bj * HALF) = w;
;                 }
	global_store_dwordx4 v[140:141], v[112:115], off offset:256
	s_nop 1
	v_mov_b64_e32 v[114:115], v[238:239]
	v_cvt_f64_u32_e32 v[116:117], v115
	v_ldexp_f64 v[116:117], v[116:117], 32
	v_cvt_f64_u32_e32 v[114:115], v114
	v_add_f64 v[114:115], v[116:117], v[114:115]
	v_ldexp_f64 v[114:115], v[114:115], s93
	v_cvt_f32_f64_e32 v114, v[114:115]
	v_fmamk_f32 v114, v114, 0x3a000000, v189
	v_cmp_gt_f32_e32 vcc, s78, v114
	v_mul_f32_e32 v115, 0x4b800000, v114
	v_or_b32_e32 v112, 16, v142
	v_cndmask_b32_e32 v114, v114, v115, vcc
	v_rsq_f32_e32 v114, v114
	v_ashrrev_i32_e32 v113, 31, v112
	v_lshlrev_b64 v[112:113], 14, v[112:113]
	v_lshl_add_u64 v[112:113], s[14:15], 0, v[112:113]
	v_mul_f32_e32 v115, 0x45800000, v114
	v_cndmask_b32_e32 v114, v114, v115, vcc
	v_pk_mul_f32 v[104:105], v[104:105], v[114:115] op_sel_hi:[1,0]
	v_pk_mul_f32 v[108:109], v[108:109], v[114:115] op_sel_hi:[1,0]
	v_pk_mul_f32 v[106:107], v[106:107], v[114:115] op_sel_hi:[1,0]
	v_max_f32_e32 v104, 0, v104
	v_pk_mul_f32 v[110:111], v[110:111], v[114:115] op_sel_hi:[1,0]
	v_mul_f32_e32 v115, v104, v104
	v_max_f32_e32 v104, 0, v109
	v_max_f32_e32 v105, 0, v105
	v_max_f32_e32 v106, 0, v106
	v_max_f32_e32 v108, 0, v108
	v_mul_f32_e32 v104, v104, v104
	v_mul_f32_e32 v109, v105, v105
	v_max_f32_e32 v105, 0, v110
	v_mul_f32_e32 v110, v106, v106
	v_max_f32_e32 v106, 0, v111
	v_max_f32_e32 v107, 0, v107
	v_pk_mul_f32 v[98:99], v[98:99], v[114:115] op_sel_hi:[1,0]
	v_pk_mul_f32 v[96:97], v[96:97], v[114:115] op_sel_hi:[1,0]
	v_lshl_add_u64 v[112:113], v[112:113], 0, v[144:145]
	v_mul_f32_e32 v108, v108, v108
	v_mul_f32_e32 v105, v105, v105
	v_mul_f32_e32 v106, v106, v106
	v_mul_f32_e32 v107, v107, v107
	v_cvt_pk_bf16_f32 v104, v108, v104
	v_pk_mul_f32 v[102:103], v[102:103], v[114:115] op_sel_hi:[1,0]
	v_pk_mul_f32 v[100:101], v[100:101], v[114:115] op_sel_hi:[1,0]
	v_max_f32_e32 v96, 0, v96
	v_max_f32_e32 v97, 0, v97
	v_max_f32_e32 v98, 0, v98
	v_cvt_pk_bf16_f32 v105, v105, v106
	v_cvt_pk_bf16_f32 v106, v115, v109
	v_cvt_pk_bf16_f32 v107, v110, v107
	global_store_dwordx4 v[112:113], v[104:107], off
	v_max_f32_e32 v99, 0, v99
	v_max_f32_e32 v100, 0, v100
	v_mul_f32_e32 v104, v96, v96
	v_max_f32_e32 v96, 0, v101
	v_mul_f32_e32 v101, v97, v97
	v_max_f32_e32 v97, 0, v102
	v_mul_f32_e32 v102, v98, v98
	v_max_f32_e32 v98, 0, v103
	v_mul_f32_e32 v96, v96, v96
	v_mul_f32_e32 v97, v97, v97
	v_mul_f32_e32 v98, v98, v98
	v_mul_f32_e32 v99, v99, v99
	v_mul_f32_e32 v100, v100, v100
	v_cvt_pk_bf16_f32 v96, v100, v96
	v_cvt_pk_bf16_f32 v97, v97, v98
	v_cvt_pk_bf16_f32 v98, v104, v101
	v_cvt_pk_bf16_f32 v99, v102, v99
	global_store_dwordx4 v[112:113], v[96:99], off offset:256
	s_nop 1
	v_mov_b64_e32 v[98:99], v[240:241]
	v_cvt_f64_u32_e32 v[100:101], v99
	v_ldexp_f64 v[100:101], v[100:101], 32
	v_cvt_f64_u32_e32 v[98:99], v98
	v_add_f64 v[98:99], v[100:101], v[98:99]
	v_ldexp_f64 v[98:99], v[98:99], s93
	v_cvt_f32_f64_e32 v98, v[98:99]
	v_fmamk_f32 v98, v98, 0x3a000000, v189
	v_cmp_gt_f32_e32 vcc, s78, v98
	v_mul_f32_e32 v99, 0x4b800000, v98
	v_or_b32_e32 v96, 32, v142
	v_cndmask_b32_e32 v98, v98, v99, vcc
	v_rsq_f32_e32 v98, v98
	v_ashrrev_i32_e32 v97, 31, v96
	v_lshlrev_b64 v[96:97], 14, v[96:97]
	v_lshl_add_u64 v[96:97], s[14:15], 0, v[96:97]
	v_mul_f32_e32 v99, 0x45800000, v98
	v_cndmask_b32_e32 v98, v98, v99, vcc
	v_pk_mul_f32 v[88:89], v[88:89], v[98:99] op_sel_hi:[1,0]
	v_pk_mul_f32 v[92:93], v[92:93], v[98:99] op_sel_hi:[1,0]
	v_pk_mul_f32 v[90:91], v[90:91], v[98:99] op_sel_hi:[1,0]
	v_max_f32_e32 v88, 0, v88
	v_pk_mul_f32 v[94:95], v[94:95], v[98:99] op_sel_hi:[1,0]
	v_mul_f32_e32 v99, v88, v88
	v_max_f32_e32 v88, 0, v93
	v_max_f32_e32 v89, 0, v89
	v_max_f32_e32 v90, 0, v90
	v_max_f32_e32 v92, 0, v92
	v_mul_f32_e32 v88, v88, v88
	v_mul_f32_e32 v93, v89, v89
	v_max_f32_e32 v89, 0, v94
	v_mul_f32_e32 v94, v90, v90
	v_max_f32_e32 v90, 0, v95
	v_max_f32_e32 v91, 0, v91
	v_pk_mul_f32 v[82:83], v[82:83], v[98:99] op_sel_hi:[1,0]
	v_pk_mul_f32 v[80:81], v[80:81], v[98:99] op_sel_hi:[1,0]
	v_lshl_add_u64 v[96:97], v[96:97], 0, v[144:145]
	v_mul_f32_e32 v92, v92, v92
	v_mul_f32_e32 v89, v89, v89
	v_mul_f32_e32 v90, v90, v90
	v_mul_f32_e32 v91, v91, v91
	v_cvt_pk_bf16_f32 v88, v92, v88
	v_pk_mul_f32 v[86:87], v[86:87], v[98:99] op_sel_hi:[1,0]
	v_pk_mul_f32 v[84:85], v[84:85], v[98:99] op_sel_hi:[1,0]
	v_max_f32_e32 v80, 0, v80
	v_max_f32_e32 v81, 0, v81
	v_max_f32_e32 v82, 0, v82
	v_cvt_pk_bf16_f32 v89, v89, v90
	v_cvt_pk_bf16_f32 v90, v99, v93
	v_cvt_pk_bf16_f32 v91, v94, v91
	global_store_dwordx4 v[96:97], v[88:91], off
	v_max_f32_e32 v83, 0, v83
	v_max_f32_e32 v84, 0, v84
	v_mul_f32_e32 v88, v80, v80
	v_max_f32_e32 v80, 0, v85
	v_mul_f32_e32 v85, v81, v81
	v_max_f32_e32 v81, 0, v86
	v_mul_f32_e32 v86, v82, v82
	v_max_f32_e32 v82, 0, v87
	v_mul_f32_e32 v80, v80, v80
	v_mul_f32_e32 v81, v81, v81
	v_mul_f32_e32 v82, v82, v82
	v_mul_f32_e32 v83, v83, v83
	v_mul_f32_e32 v84, v84, v84
	v_cvt_pk_bf16_f32 v80, v84, v80
	v_cvt_pk_bf16_f32 v81, v81, v82
	v_cvt_pk_bf16_f32 v82, v88, v85
	v_cvt_pk_bf16_f32 v83, v86, v83
	global_store_dwordx4 v[96:97], v[80:83], off offset:256
	s_nop 1
	v_mov_b64_e32 v[82:83], v[242:243]
	v_cvt_f64_u32_e32 v[84:85], v83
	v_ldexp_f64 v[84:85], v[84:85], 32
	v_cvt_f64_u32_e32 v[82:83], v82
	v_add_f64 v[82:83], v[84:85], v[82:83]
	v_ldexp_f64 v[82:83], v[82:83], s93
	v_cvt_f32_f64_e32 v82, v[82:83]
	v_fmamk_f32 v82, v82, 0x3a000000, v189
	v_cmp_gt_f32_e32 vcc, s78, v82
	v_mul_f32_e32 v83, 0x4b800000, v82
	v_or_b32_e32 v80, 48, v142
	v_cndmask_b32_e32 v82, v82, v83, vcc
	v_rsq_f32_e32 v82, v82
	v_ashrrev_i32_e32 v81, 31, v80
	v_lshlrev_b64 v[80:81], 14, v[80:81]
; __device__ __forceinline__ unsigned cvt_pk_bf16(float lo, float hi) { unsigned r; asm volatile("v_cvt_pk_bf16_f32 %0, %1, %2" : "=v"(r) : "v"(lo), "v"(hi)); return r; }
; __device__ __forceinline__ float rinv_st(stat_t s, float invn) { return rsqrtf((float)((double)s * (1.0 / 4294967296.0)) * invn + 1e-6f); }
;     __device__ __forceinline__ void operator()(const f32x4 (&acc)[2][2][4][2], const Unit& u, int wr, int wc, int fr, int fq) const {
;         const int row0 = u.pm * BM + wr * 64 + fr, col0 = u.pn * BM + wc * 32 + 8 * fq;
; #pragma unroll
;         for (int ai = 0; ai < 2; ++ai)
; #pragma unroll
;             for (int m = 0; m < 4; ++m) {
;                 const int row = row0 + ai * HALF + m * 16; const float r = rinv_st(stats[row], 1.0f / 2048.0f);
;                 bf16_t* rowp = U + (size_t)row * FF + col0;
; #pragma unroll
;                 for (int bj = 0; bj < 2; ++bj) {
;                     f32x4 v0 = acc[ai][bj][m][0] * r, v1 = acc[ai][bj][m][1] * r;
; #pragma unroll
;                     for (int j = 0; j < 4; ++j) { const float a = fmaxf(v0[j], 0.f), b = fmaxf(v1[j], 0.f); v0[j] = a * a; v1[j] = b * b; }
;                     u32x4 w; w.x = cvt_pk_bf16(v0[0], v0[1]); w.y = cvt_pk_bf16(v0[2], v0[3]); w.z = cvt_pk_bf16(v1[0], v1[1]); w.w = cvt_pk_bf16(v1[2], v1[3]);
;                     *(u32x4*)(rowp + bj * HALF) = w;
;                 }
	v_lshl_add_u64 v[80:81], s[14:15], 0, v[80:81]
	v_mul_f32_e32 v83, 0x45800000, v82
	v_cndmask_b32_e32 v82, v82, v83, vcc
	v_pk_mul_f32 v[72:73], v[72:73], v[82:83] op_sel_hi:[1,0]
	v_pk_mul_f32 v[76:77], v[76:77], v[82:83] op_sel_hi:[1,0]
	v_pk_mul_f32 v[74:75], v[74:75], v[82:83] op_sel_hi:[1,0]
	v_max_f32_e32 v72, 0, v72
	v_pk_mul_f32 v[78:79], v[78:79], v[82:83] op_sel_hi:[1,0]
	v_mul_f32_e32 v83, v72, v72
	v_max_f32_e32 v72, 0, v77
	v_max_f32_e32 v73, 0, v73
	v_max_f32_e32 v74, 0, v74
	v_max_f32_e32 v76, 0, v76
	v_mul_f32_e32 v72, v72, v72
	v_mul_f32_e32 v77, v73, v73
	v_max_f32_e32 v73, 0, v78
	v_mul_f32_e32 v78, v74, v74
	v_max_f32_e32 v74, 0, v79
	v_max_f32_e32 v75, 0, v75
	v_pk_mul_f32 v[66:67], v[66:67], v[82:83] op_sel_hi:[1,0]
	v_pk_mul_f32 v[64:65], v[64:65], v[82:83] op_sel_hi:[1,0]
	v_lshl_add_u64 v[80:81], v[80:81], 0, v[144:145]
	v_mul_f32_e32 v76, v76, v76
	v_mul_f32_e32 v73, v73, v73
	v_mul_f32_e32 v74, v74, v74
	v_mul_f32_e32 v75, v75, v75
	v_cvt_pk_bf16_f32 v72, v76, v72
	v_pk_mul_f32 v[70:71], v[70:71], v[82:83] op_sel_hi:[1,0]
	v_pk_mul_f32 v[68:69], v[68:69], v[82:83] op_sel_hi:[1,0]
	v_max_f32_e32 v64, 0, v64
	v_max_f32_e32 v65, 0, v65
	v_max_f32_e32 v66, 0, v66
	v_cvt_pk_bf16_f32 v73, v73, v74
	v_cvt_pk_bf16_f32 v74, v83, v77
	v_cvt_pk_bf16_f32 v75, v78, v75
	global_store_dwordx4 v[80:81], v[72:75], off
	v_max_f32_e32 v67, 0, v67
	v_max_f32_e32 v68, 0, v68
	v_mul_f32_e32 v72, v64, v64
	v_max_f32_e32 v64, 0, v69
	v_mul_f32_e32 v69, v65, v65
	v_max_f32_e32 v65, 0, v70
	v_mul_f32_e32 v70, v66, v66
	v_max_f32_e32 v66, 0, v71
	v_mul_f32_e32 v64, v64, v64
	v_mul_f32_e32 v65, v65, v65
	v_mul_f32_e32 v66, v66, v66
	v_mul_f32_e32 v67, v67, v67
	v_mul_f32_e32 v68, v68, v68
	v_cvt_pk_bf16_f32 v64, v68, v64
	v_cvt_pk_bf16_f32 v65, v65, v66
	v_cvt_pk_bf16_f32 v66, v72, v69
	v_cvt_pk_bf16_f32 v67, v70, v67
	global_store_dwordx4 v[80:81], v[64:67], off offset:256
	s_nop 1
	v_mov_b64_e32 v[64:65], v[244:245]
	v_cvt_f64_u32_e32 v[66:67], v65
	v_ldexp_f64 v[66:67], v[66:67], 32
	v_cvt_f64_u32_e32 v[64:65], v64
	v_add_f64 v[64:65], v[66:67], v[64:65]
	v_ldexp_f64 v[64:65], v[64:65], s93
	v_cvt_f32_f64_e32 v64, v[64:65]
	v_fmamk_f32 v64, v64, 0x3a000000, v189
	v_cmp_gt_f32_e32 vcc, s78, v64
	v_mul_f32_e32 v65, 0x4b800000, v64
	s_nop 0
	v_cndmask_b32_e32 v64, v64, v65, vcc
	v_rsq_f32_e32 v64, v64
	s_nop 0
	v_mul_f32_e32 v65, 0x45800000, v64
	v_cndmask_b32_e32 v66, v64, v65, vcc
	v_pk_mul_f32 v[56:57], v[56:57], v[66:67] op_sel_hi:[1,0]
	v_pk_mul_f32 v[60:61], v[60:61], v[66:67] op_sel_hi:[1,0]
	v_pk_mul_f32 v[58:59], v[58:59], v[66:67] op_sel_hi:[1,0]
	v_max_f32_e32 v56, 0, v56
	v_pk_mul_f32 v[62:63], v[62:63], v[66:67] op_sel_hi:[1,0]
	v_max_f32_e32 v60, 0, v60
	v_mul_f32_e32 v67, v56, v56
	v_max_f32_e32 v56, 0, v61
	v_max_f32_e32 v57, 0, v57
	v_max_f32_e32 v58, 0, v58
	v_lshl_add_u64 v[64:65], v[140:141], 0, s[0:1]
	v_mul_f32_e32 v60, v60, v60
	v_mul_f32_e32 v56, v56, v56
	v_mul_f32_e32 v61, v57, v57
	v_max_f32_e32 v57, 0, v62
	v_mul_f32_e32 v62, v58, v58
	v_max_f32_e32 v58, 0, v63
	s_mov_b32 s0, 0x200000
	v_mul_f32_e32 v57, v57, v57
	v_max_f32_e32 v59, 0, v59
	v_mul_f32_e32 v58, v58, v58
	v_cvt_pk_bf16_f32 v56, v60, v56
	v_add_co_u32_e32 v60, vcc, s0, v140
	v_pk_mul_f32 v[50:51], v[50:51], v[66:67] op_sel_hi:[1,0]
	v_pk_mul_f32 v[48:49], v[48:49], v[66:67] op_sel_hi:[1,0]
	v_mul_f32_e32 v59, v59, v59
	v_cvt_pk_bf16_f32 v57, v57, v58
	v_cvt_pk_bf16_f32 v58, v67, v61
	v_addc_co_u32_e32 v61, vcc, 0, v141, vcc
	v_pk_mul_f32 v[54:55], v[54:55], v[66:67] op_sel_hi:[1,0]
	v_pk_mul_f32 v[52:53], v[52:53], v[66:67] op_sel_hi:[1,0]
	v_max_f32_e32 v48, 0, v48
	v_max_f32_e32 v49, 0, v49
	v_max_f32_e32 v50, 0, v50
	v_cvt_pk_bf16_f32 v59, v62, v59
	global_store_dwordx4 v[60:61], v[56:59], off
	v_max_f32_e32 v51, 0, v51
	v_max_f32_e32 v52, 0, v52
	v_mul_f32_e32 v56, v48, v48
	v_max_f32_e32 v48, 0, v53
	v_mul_f32_e32 v53, v49, v49
	v_max_f32_e32 v49, 0, v54
	v_mul_f32_e32 v54, v50, v50
	v_max_f32_e32 v50, 0, v55
	v_mul_f32_e32 v48, v48, v48
	v_mul_f32_e32 v49, v49, v49
	v_mul_f32_e32 v50, v50, v50
	v_mul_f32_e32 v51, v51, v51
	v_mul_f32_e32 v52, v52, v52
	v_cvt_pk_bf16_f32 v48, v52, v48
	v_cvt_pk_bf16_f32 v49, v49, v50
	v_cvt_pk_bf16_f32 v50, v56, v53
	v_cvt_pk_bf16_f32 v51, v54, v51
	global_store_dwordx4 v[64:65], v[48:51], off offset:256
	s_nop 1
	v_mov_b64_e32 v[48:49], v[246:247]
	s_mov_b64 s[0:1], 0x240000
	v_cvt_f64_u32_e32 v[50:51], v49
	v_ldexp_f64 v[50:51], v[50:51], 32
	v_cvt_f64_u32_e32 v[48:49], v48
	v_add_f64 v[48:49], v[50:51], v[48:49]
	v_ldexp_f64 v[48:49], v[48:49], s93
	v_cvt_f32_f64_e32 v48, v[48:49]
	v_fmamk_f32 v48, v48, 0x3a000000, v189
	v_cmp_gt_f32_e32 vcc, s78, v48
	v_mul_f32_e32 v49, 0x4b800000, v48
	s_nop 0
	v_cndmask_b32_e32 v48, v48, v49, vcc
	v_rsq_f32_e32 v48, v48
	s_nop 0
	v_mul_f32_e32 v49, 0x45800000, v48
	v_cndmask_b32_e32 v50, v48, v49, vcc
	v_pk_mul_f32 v[40:41], v[40:41], v[50:51] op_sel_hi:[1,0]
	v_pk_mul_f32 v[44:45], v[44:45], v[50:51] op_sel_hi:[1,0]
	v_pk_mul_f32 v[42:43], v[42:43], v[50:51] op_sel_hi:[1,0]
	v_max_f32_e32 v40, 0, v40
	v_pk_mul_f32 v[46:47], v[46:47], v[50:51] op_sel_hi:[1,0]
	v_max_f32_e32 v44, 0, v44
	v_mul_f32_e32 v51, v40, v40
	v_max_f32_e32 v40, 0, v45
	v_max_f32_e32 v41, 0, v41
	v_max_f32_e32 v42, 0, v42
	v_lshl_add_u64 v[48:49], v[140:141], 0, s[0:1]
	v_mul_f32_e32 v44, v44, v44
	v_mul_f32_e32 v40, v40, v40
	v_mul_f32_e32 v45, v41, v41
	v_max_f32_e32 v41, 0, v46
	v_mul_f32_e32 v46, v42, v42
	v_max_f32_e32 v42, 0, v47
	s_mov_b32 s0, 0x240000
	v_mul_f32_e32 v41, v41, v41
	v_max_f32_e32 v43, 0, v43
	v_mul_f32_e32 v42, v42, v42
	v_cvt_pk_bf16_f32 v40, v44, v40
	v_add_co_u32_e32 v44, vcc, s0, v140
; __device__ __forceinline__ unsigned cvt_pk_bf16(float lo, float hi) { unsigned r; asm volatile("v_cvt_pk_bf16_f32 %0, %1, %2" : "=v"(r) : "v"(lo), "v"(hi)); return r; }
; __device__ __forceinline__ float rinv_st(stat_t s, float invn) { return rsqrtf((float)((double)s * (1.0 / 4294967296.0)) * invn + 1e-6f); }
; #define PG8_WAIT_V(n) asm volatile("s_waitcnt vmcnt(" #n ")" ::: "memory")
; #define PG8_BAR __builtin_amdgcn_s_barrier()
; template <class Epi>
; __device__ __forceinline__ void gemm_phase(const int TID, const int BID, LAS unsigned char* lds, const Gemm g, const StaticOrder& S, const Epi& E) {
;     ...
;         if (!has_next) break;
; #pragma unroll
;         for (int a = 0; a < 2; ++a)
; #pragma unroll
;             for (int b = 0; b < 2; ++b)
; #pragma unroll
;                 for (int m = 0; m < 4; ++m)
; #pragma unroll
;                     for (int n = 0; n < 2; ++n) acc[a][b][m][n] = (f32x4){0.f, 0.f, 0.f, 0.f};
;         cur = nxt; cA = nA; cB = nB; ++ui;
;     }
;     PG8_WAIT_V(0);
;     if (wr == 0) PG8_BAR;
;     PG8_BAR;
;     __device__ __forceinline__ void operator()(const f32x4 (&acc)[2][2][4][2], const Unit& u, int wr, int wc, int fr, int fq) const {
;         const int row0 = u.pm * BM + wr * 64 + fr, col0 = u.pn * BM + wc * 32 + 8 * fq;
; #pragma unroll
;         for (int ai = 0; ai < 2; ++ai)
; #pragma unroll
;             for (int m = 0; m < 4; ++m) {
;                 const int row = row0 + ai * HALF + m * 16; const float r = rinv_st(stats[row], 1.0f / 2048.0f);
;                 bf16_t* rowp = U + (size_t)row * FF + col0;
; #pragma unroll
;                 for (int bj = 0; bj < 2; ++bj) {
;                     f32x4 v0 = acc[ai][bj][m][0] * r, v1 = acc[ai][bj][m][1] * r;
; #pragma unroll
;                     for (int j = 0; j < 4; ++j) { const float a = fmaxf(v0[j], 0.f), b = fmaxf(v1[j], 0.f); v0[j] = a * a; v1[j] = b * b; }
;                     u32x4 w; w.x = cvt_pk_bf16(v0[0], v0[1]); w.y = cvt_pk_bf16(v0[2], v0[3]); w.z = cvt_pk_bf16(v1[0], v1[1]); w.w = cvt_pk_bf16(v1[2], v1[3]);
;                     *(u32x4*)(rowp + bj * HALF) = w;
;                 }
;             }
;     }
	v_pk_mul_f32 v[34:35], v[34:35], v[50:51] op_sel_hi:[1,0]
	v_pk_mul_f32 v[32:33], v[32:33], v[50:51] op_sel_hi:[1,0]
	v_mul_f32_e32 v43, v43, v43
	v_cvt_pk_bf16_f32 v41, v41, v42
	v_cvt_pk_bf16_f32 v42, v51, v45
	v_addc_co_u32_e32 v45, vcc, 0, v141, vcc
	v_pk_mul_f32 v[38:39], v[38:39], v[50:51] op_sel_hi:[1,0]
	v_pk_mul_f32 v[36:37], v[36:37], v[50:51] op_sel_hi:[1,0]
	v_max_f32_e32 v32, 0, v32
	v_max_f32_e32 v33, 0, v33
	v_max_f32_e32 v34, 0, v34
	v_cvt_pk_bf16_f32 v43, v46, v43
	global_store_dwordx4 v[44:45], v[40:43], off
	v_max_f32_e32 v35, 0, v35
	v_max_f32_e32 v36, 0, v36
	v_mul_f32_e32 v40, v32, v32
	v_max_f32_e32 v32, 0, v37
	v_mul_f32_e32 v37, v33, v33
	v_max_f32_e32 v33, 0, v38
	v_mul_f32_e32 v38, v34, v34
	v_max_f32_e32 v34, 0, v39
	v_mul_f32_e32 v32, v32, v32
	v_mul_f32_e32 v33, v33, v33
	v_mul_f32_e32 v34, v34, v34
	v_mul_f32_e32 v35, v35, v35
	v_mul_f32_e32 v36, v36, v36
	v_cvt_pk_bf16_f32 v32, v36, v32
	v_cvt_pk_bf16_f32 v33, v33, v34
	v_cvt_pk_bf16_f32 v34, v40, v37
	v_cvt_pk_bf16_f32 v35, v38, v35
	global_store_dwordx4 v[48:49], v[32:35], off offset:256
	s_nop 1
	v_mov_b64_e32 v[32:33], v[248:249]
	s_mov_b64 s[0:1], 0x280000
	v_cvt_f64_u32_e32 v[34:35], v33
	v_ldexp_f64 v[34:35], v[34:35], 32
	v_cvt_f64_u32_e32 v[32:33], v32
	v_add_f64 v[32:33], v[34:35], v[32:33]
	v_ldexp_f64 v[32:33], v[32:33], s93
	v_cvt_f32_f64_e32 v32, v[32:33]
	v_fmamk_f32 v32, v32, 0x3a000000, v189
	v_cmp_gt_f32_e32 vcc, s78, v32
	v_mul_f32_e32 v33, 0x4b800000, v32
	s_nop 0
	v_cndmask_b32_e32 v32, v32, v33, vcc
	v_rsq_f32_e32 v32, v32
	s_nop 0
	v_mul_f32_e32 v33, 0x45800000, v32
	v_cndmask_b32_e32 v34, v32, v33, vcc
	v_pk_mul_f32 v[24:25], v[24:25], v[34:35] op_sel_hi:[1,0]
	v_pk_mul_f32 v[28:29], v[28:29], v[34:35] op_sel_hi:[1,0]
	v_pk_mul_f32 v[26:27], v[26:27], v[34:35] op_sel_hi:[1,0]
	v_max_f32_e32 v24, 0, v24
	v_pk_mul_f32 v[30:31], v[30:31], v[34:35] op_sel_hi:[1,0]
	v_max_f32_e32 v28, 0, v28
	v_mul_f32_e32 v35, v24, v24
	v_max_f32_e32 v24, 0, v29
	v_max_f32_e32 v25, 0, v25
	v_max_f32_e32 v26, 0, v26
	v_lshl_add_u64 v[32:33], v[140:141], 0, s[0:1]
	v_mul_f32_e32 v28, v28, v28
	v_mul_f32_e32 v24, v24, v24
	v_mul_f32_e32 v29, v25, v25
	v_max_f32_e32 v25, 0, v30
	v_mul_f32_e32 v30, v26, v26
	v_max_f32_e32 v26, 0, v31
	s_mov_b32 s0, 0x280000
	v_mul_f32_e32 v25, v25, v25
	v_max_f32_e32 v27, 0, v27
	v_mul_f32_e32 v26, v26, v26
	v_cvt_pk_bf16_f32 v24, v28, v24
	v_add_co_u32_e32 v28, vcc, s0, v140
	v_pk_mul_f32 v[18:19], v[18:19], v[34:35] op_sel_hi:[1,0]
	v_pk_mul_f32 v[16:17], v[16:17], v[34:35] op_sel_hi:[1,0]
	v_mul_f32_e32 v27, v27, v27
	v_cvt_pk_bf16_f32 v25, v25, v26
	v_cvt_pk_bf16_f32 v26, v35, v29
	v_addc_co_u32_e32 v29, vcc, 0, v141, vcc
	v_pk_mul_f32 v[22:23], v[22:23], v[34:35] op_sel_hi:[1,0]
	v_pk_mul_f32 v[20:21], v[20:21], v[34:35] op_sel_hi:[1,0]
	v_max_f32_e32 v16, 0, v16
	v_max_f32_e32 v17, 0, v17
	v_max_f32_e32 v18, 0, v18
	v_cvt_pk_bf16_f32 v27, v30, v27
	global_store_dwordx4 v[28:29], v[24:27], off
	v_max_f32_e32 v19, 0, v19
	v_max_f32_e32 v20, 0, v20
	v_mul_f32_e32 v24, v16, v16
	v_max_f32_e32 v16, 0, v21
	v_mul_f32_e32 v21, v17, v17
	v_max_f32_e32 v17, 0, v22
	v_mul_f32_e32 v22, v18, v18
	v_max_f32_e32 v18, 0, v23
	v_mul_f32_e32 v16, v16, v16
	v_mul_f32_e32 v17, v17, v17
	v_mul_f32_e32 v18, v18, v18
	v_mul_f32_e32 v19, v19, v19
	v_mul_f32_e32 v20, v20, v20
	v_cvt_pk_bf16_f32 v16, v20, v16
	v_cvt_pk_bf16_f32 v17, v17, v18
	v_cvt_pk_bf16_f32 v18, v24, v21
	v_cvt_pk_bf16_f32 v19, v22, v19
	global_store_dwordx4 v[32:33], v[16:19], off offset:256
	s_nop 1
	v_mov_b64_e32 v[16:17], v[250:251]
	s_mov_b64 s[0:1], 0x2c0000
	v_cvt_f64_u32_e32 v[18:19], v17
	v_ldexp_f64 v[18:19], v[18:19], 32
	v_cvt_f64_u32_e32 v[16:17], v16
	v_add_f64 v[16:17], v[18:19], v[16:17]
	v_ldexp_f64 v[16:17], v[16:17], s93
	v_cvt_f32_f64_e32 v16, v[16:17]
	v_fmamk_f32 v16, v16, 0x3a000000, v189
	v_cmp_gt_f32_e32 vcc, s78, v16
	v_mul_f32_e32 v17, 0x4b800000, v16
	v_lshl_add_u64 v[18:19], v[140:141], 0, s[0:1]
	v_cndmask_b32_e32 v16, v16, v17, vcc
	v_rsq_f32_e32 v16, v16
	s_mov_b32 s0, 0x2c0000
	v_mul_f32_e32 v17, 0x45800000, v16
	v_cndmask_b32_e32 v16, v16, v17, vcc
	v_pk_mul_f32 v[8:9], v[8:9], v[16:17] op_sel_hi:[1,0]
	v_pk_mul_f32 v[12:13], v[12:13], v[16:17] op_sel_hi:[1,0]
	v_pk_mul_f32 v[10:11], v[10:11], v[16:17] op_sel_hi:[1,0]
	v_max_f32_e32 v8, 0, v8
	v_pk_mul_f32 v[14:15], v[14:15], v[16:17] op_sel_hi:[1,0]
	v_max_f32_e32 v12, 0, v12
	v_mul_f32_e32 v17, v8, v8
	v_max_f32_e32 v8, 0, v13
	v_max_f32_e32 v9, 0, v9
	v_max_f32_e32 v10, 0, v10
	v_mul_f32_e32 v12, v12, v12
	v_mul_f32_e32 v8, v8, v8
	v_mul_f32_e32 v13, v9, v9
	v_max_f32_e32 v9, 0, v14
	v_mul_f32_e32 v14, v10, v10
	v_max_f32_e32 v10, 0, v15
	v_mul_f32_e32 v9, v9, v9
	v_max_f32_e32 v11, 0, v11
	v_mul_f32_e32 v10, v10, v10
	v_cvt_pk_bf16_f32 v8, v12, v8
	v_add_co_u32_e32 v12, vcc, s0, v140
	v_pk_mul_f32 v[2:3], v[2:3], v[16:17] op_sel_hi:[1,0]
	v_pk_mul_f32 v[0:1], v[0:1], v[16:17] op_sel_hi:[1,0]
	v_mul_f32_e32 v11, v11, v11
	v_cvt_pk_bf16_f32 v9, v9, v10
	v_cvt_pk_bf16_f32 v10, v17, v13
	v_addc_co_u32_e32 v13, vcc, 0, v141, vcc
	v_pk_mul_f32 v[6:7], v[6:7], v[16:17] op_sel_hi:[1,0]
	v_pk_mul_f32 v[4:5], v[4:5], v[16:17] op_sel_hi:[1,0]
	v_max_f32_e32 v0, 0, v0
	v_max_f32_e32 v1, 0, v1
	v_max_f32_e32 v2, 0, v2
	v_cvt_pk_bf16_f32 v11, v14, v11
	global_store_dwordx4 v[12:13], v[8:11], off
	v_max_f32_e32 v3, 0, v3
	v_max_f32_e32 v4, 0, v4
	v_mul_f32_e32 v8, v0, v0
	v_max_f32_e32 v0, 0, v5
	v_mul_f32_e32 v5, v1, v1
	v_max_f32_e32 v1, 0, v6
	v_mul_f32_e32 v6, v2, v2
	v_max_f32_e32 v2, 0, v7
	v_mul_f32_e32 v0, v0, v0
	v_mul_f32_e32 v1, v1, v1
	v_mul_f32_e32 v2, v2, v2
	v_mul_f32_e32 v3, v3, v3
	s_and_b64 vcc, exec, s[8:9]
	s_mov_b32 s0, s16
	v_mul_f32_e32 v4, v4, v4
	v_cvt_pk_bf16_f32 v0, v4, v0
	v_cvt_pk_bf16_f32 v1, v1, v2
	v_cvt_pk_bf16_f32 v2, v8, v5
	v_cvt_pk_bf16_f32 v3, v6, v3
	global_store_dwordx4 v[18:19], v[0:3], off offset:256
	s_cbranch_vccz .LBB0_918
	s_waitcnt vmcnt(0)
	s_cmpk_gt_u32 s42, 0xff
	s_cbranch_scc1 .LBB0_929
	s_barrier

; template <class Epi>
; __device__ __forceinline__ void gemm_phase(const int TID, const int BID, LAS unsigned char* lds, const Gemm g, const StaticOrder& S, const Epi& E) {
;     ...
; #pragma unroll
;         for (int a = 0; a < 2; ++a)
; #pragma unroll
;             for (int b = 0; b < 2; ++b)
; #pragma unroll
;                 for (int m = 0; m < 4; ++m)
; #pragma unroll
;                     for (int n = 0; n < 2; ++n) acc[a][b][m][n] = (f32x4){0.f, 0.f, 0.f, 0.f};
;         cur = nxt; cA = nA; cB = nB; ++ui;
.LBB0_954:
	s_add_u32 s12, s18, 0x80
	s_addc_u32 s13, s19, 0
	s_add_u32 s18, s16, 0x100
	v_mov_b32_e32 v0, 0
	s_addc_u32 s19, s17, 0
	s_mov_b32 s14, 0
	v_mov_b32_e32 v1, v0
	v_mov_b32_e32 v2, v0
	v_mov_b32_e32 v3, v0
	v_mov_b32_e32 v4, v0
	v_mov_b32_e32 v5, v0
	v_mov_b32_e32 v6, v0
	v_mov_b32_e32 v7, v0
	v_mov_b32_e32 v16, v0
	v_mov_b32_e32 v17, v0
	v_mov_b32_e32 v18, v0
	v_mov_b32_e32 v19, v0
	v_mov_b32_e32 v20, v0
	v_mov_b32_e32 v21, v0
	v_mov_b32_e32 v22, v0
	v_mov_b32_e32 v23, v0
	v_mov_b32_e32 v32, v0
	v_mov_b32_e32 v33, v0
	v_mov_b32_e32 v34, v0
	v_mov_b32_e32 v35, v0
	v_mov_b32_e32 v36, v0
	v_mov_b32_e32 v37, v0
	v_mov_b32_e32 v38, v0
	v_mov_b32_e32 v39, v0
	v_mov_b32_e32 v56, v0
	v_mov_b32_e32 v57, v0
	v_mov_b32_e32 v58, v0
	v_mov_b32_e32 v59, v0
	v_mov_b32_e32 v64, v0
	v_mov_b32_e32 v65, v0
	v_mov_b32_e32 v66, v0
	v_mov_b32_e32 v67, v0
	v_mov_b32_e32 v8, v0
	v_mov_b32_e32 v9, v0
	v_mov_b32_e32 v10, v0
	v_mov_b32_e32 v11, v0
	v_mov_b32_e32 v12, v0
	v_mov_b32_e32 v13, v0
	v_mov_b32_e32 v14, v0
	v_mov_b32_e32 v15, v0
	v_mov_b32_e32 v24, v0
	v_mov_b32_e32 v25, v0
	v_mov_b32_e32 v26, v0
	v_mov_b32_e32 v27, v0
	v_mov_b32_e32 v28, v0
	v_mov_b32_e32 v29, v0
	v_mov_b32_e32 v30, v0
	v_mov_b32_e32 v31, v0
	v_mov_b32_e32 v40, v0
	v_mov_b32_e32 v41, v0
	v_mov_b32_e32 v42, v0
	v_mov_b32_e32 v43, v0
	v_mov_b32_e32 v44, v0
	v_mov_b32_e32 v45, v0
	v_mov_b32_e32 v46, v0
	v_mov_b32_e32 v47, v0
	v_mov_b32_e32 v72, v0
	v_mov_b32_e32 v73, v0
	v_mov_b32_e32 v74, v0
	v_mov_b32_e32 v75, v0
	v_mov_b32_e32 v76, v0
	v_mov_b32_e32 v77, v0
	v_mov_b32_e32 v78, v0
	v_mov_b32_e32 v79, v0
	v_mov_b32_e32 v80, v0
	v_mov_b32_e32 v81, v0
	v_mov_b32_e32 v82, v0
	v_mov_b32_e32 v83, v0
	v_mov_b32_e32 v84, v0
	v_mov_b32_e32 v85, v0
	v_mov_b32_e32 v86, v0
	v_mov_b32_e32 v87, v0
	v_mov_b32_e32 v96, v0
	v_mov_b32_e32 v97, v0
	v_mov_b32_e32 v98, v0
	v_mov_b32_e32 v99, v0
	v_mov_b32_e32 v100, v0
	v_mov_b32_e32 v101, v0
	v_mov_b32_e32 v102, v0
	v_mov_b32_e32 v103, v0
	v_mov_b32_e32 v112, v0
	v_mov_b32_e32 v113, v0
	v_mov_b32_e32 v114, v0
	v_mov_b32_e32 v115, v0
	v_mov_b32_e32 v116, v0
	v_mov_b32_e32 v117, v0
	v_mov_b32_e32 v118, v0
	v_mov_b32_e32 v119, v0
	v_mov_b32_e32 v128, v0
	v_mov_b32_e32 v129, v0
	v_mov_b32_e32 v130, v0
	v_mov_b32_e32 v131, v0
	v_mov_b32_e32 v132, v0
	v_mov_b32_e32 v133, v0
	v_mov_b32_e32 v134, v0
	v_mov_b32_e32 v135, v0
	v_mov_b32_e32 v88, v0
	v_mov_b32_e32 v89, v0
	v_mov_b32_e32 v90, v0
	v_mov_b32_e32 v91, v0
	v_mov_b32_e32 v92, v0
	v_mov_b32_e32 v93, v0
	v_mov_b32_e32 v94, v0
	v_mov_b32_e32 v95, v0
	v_mov_b32_e32 v104, v0
	v_mov_b32_e32 v105, v0
	v_mov_b32_e32 v106, v0
	v_mov_b32_e32 v107, v0
	v_mov_b32_e32 v108, v0
	v_mov_b32_e32 v109, v0
	v_mov_b32_e32 v110, v0
	v_mov_b32_e32 v111, v0
	v_mov_b32_e32 v120, v0
	v_mov_b32_e32 v121, v0
	v_mov_b32_e32 v122, v0
	v_mov_b32_e32 v123, v0
	v_mov_b32_e32 v124, v0
	v_mov_b32_e32 v125, v0
	v_mov_b32_e32 v126, v0
	v_mov_b32_e32 v127, v0
	v_mov_b32_e32 v136, v0
	v_mov_b32_e32 v137, v0
	v_mov_b32_e32 v138, v0
	v_mov_b32_e32 v139, v0
	v_mov_b32_e32 v140, v0
	v_mov_b32_e32 v141, v0
	v_mov_b32_e32 v142, v0
	v_mov_b32_e32 v143, v0
	s_branch .LBB0_955

; #define PG8_STAGE(bufoff, gbase, voff) do { _Pragma("unroll") for (int _i = 0; _i < 2; ++_i) \
;         __builtin_amdgcn_global_load_lds((const unsigned*)((const char*)(gbase) + (voff)[_i]), (LAS unsigned*)(lds + (bufoff) + ldsw + _i * 8192), 16, 0, 0); } while (0)
; #define PG8_LDA(dst, b, h) do { _Pragma("unroll") for (int m = 0; m < 4; ++m) _Pragma("unroll") for (int k = 0; k < 2; ++k) dst[m][k] = *(const LAS bf16x8*)(lds + PG8_SA(b, h) + aoff + m * 2048 + k * 1024); } while (0)
; #define PG8_LDB(dst, b, h) do { _Pragma("unroll") for (int n = 0; n < 2; ++n) _Pragma("unroll") for (int k = 0; k < 2; ++k) dst[n][k] = *(const LAS bf16x8*)(lds + PG8_SB(b, h) + boff + n * 2048 + k * 1024); } while (0)
; #define PG8_MMA(ai, bj, At, Bt) do { __builtin_amdgcn_s_setprio(1); _Pragma("unroll") for (int m = 0; m < 4; ++m) _Pragma("unroll") for (int n = 0; n < 2; ++n) _Pragma("unroll") for (int k = 0; k < 2; ++k) \
;         acc[ai][bj][m][n] = __builtin_amdgcn_mfma_f32_16x16x32_bf16(Bt[n][k], At[m][k], acc[ai][bj][m][n], 0, 0, 0); __builtin_amdgcn_s_setprio(0); } while (0)
; #define PG8_WAIT_L(n) asm volatile("s_waitcnt lgkmcnt(" #n ")" ::: "memory")
; #define PG8_BAR __builtin_amdgcn_s_barrier()
; #define PG8_SCHED __builtin_amdgcn_sched_barrier(0)
; template <class Epi>
; __device__ __forceinline__ void gemm_phase(const int TID, const int BID, LAS unsigned char* lds, const Gemm g, const StaticOrder& S, const Epi& E) {
;     ...
;             const bool last = (t == nt - 2);
;             const char* a1 = cA + (size_t)(t + 1) * kstep;
;             const char* a2 = last ? nA : cA + (size_t)(t + 2) * kstep; const char* b2 = last ? nB : cB + (size_t)(t + 2) * kstep;
;             const char* a3 = a2 + kstep; const char* b3 = b2 + kstep;
;             PG8_LDB(B0, 0, 0); PG8_SCHED; PG8_LDA(At, 0, 0); PG8_STAGE(PG8_SA(1, 1), a1 + hstepA, voffA);
;             PG8_WAIT_L(8); PG8_BAR; PG8_WAIT_L(0); PG8_MMA(0, 0, At, B0); PG8_BAR; PG8_SCHED;
;             PG8_LDB(B1, 0, 1); PG8_STAGE(PG8_SB(0, 0), b2, voffB);
;             PG8_BAR; PG8_WAIT_L(0); PG8_MMA(0, 1, At, B1); PG8_BAR;
;             PG8_LDA(At, 0, 1); PG8_STAGE(PG8_SA(0, 0), a2, voffA);
;             PG8_BAR; PG8_WAIT_L(0); PG8_MMA(1, 0, At, B0); PG8_BAR; PG8_SCHED;
.LBB0_955:
	v_add_u32_e32 v68, s63, v198
	ds_read_b128 v[48:51], v68
	ds_read_b128 v[52:55], v68 offset:1024
	ds_read_b128 v[60:63], v68 offset:2048
	ds_read_b128 v[68:71], v68 offset:3072
	s_add_i32 vcc_lo, s14, 2
	s_add_u32 s16, s12, 0x80
	s_addc_u32 s15, s13, 0
	s_cmp_eq_u32 s88, s14
	s_cselect_b32 s14, s50, s16
	s_cselect_b32 s15, s51, s15
	s_cselect_b32 s17, s53, s19
	s_cselect_b32 s16, s52, s18
	v_lshl_add_u64 v[182:183], s[12:13], 0, v[166:167]
	s_add_i32 m0, s76, 0xc000
	ds_read_b128 v[144:147], v200
	ds_read_b128 v[148:151], v200 offset:1024
	ds_read_b128 v[170:173], v200 offset:2048
	ds_read_b128 v[174:177], v200 offset:3072
	ds_read_b128 v[178:181], v200 offset:4096
	ds_read_b128 v[208:211], v200 offset:5120
	ds_read_b128 v[212:215], v200 offset:6144
	ds_read_b128 v[216:219], v200 offset:7168
	global_load_lds_dwordx4 v[182:183], off
	s_add_i32 m0, s76, 0xe000
	v_lshl_add_u64 v[182:183], s[12:13], 0, v[168:169]
	global_load_lds_dwordx4 v[182:183], off
	s_waitcnt lgkmcnt(8)
	s_barrier
	s_waitcnt lgkmcnt(0)
	s_setprio 1
	v_mfma_f32_16x16x32_bf16 v[140:143], v[48:51], v[144:147], v[140:143]
	v_mfma_f32_16x16x32_bf16 v[136:139], v[60:63], v[144:147], v[136:139]
	v_mfma_f32_16x16x32_bf16 v[124:127], v[48:51], v[170:173], v[124:127]
	v_mfma_f32_16x16x32_bf16 v[120:123], v[60:63], v[170:173], v[120:123]
	v_mfma_f32_16x16x32_bf16 v[108:111], v[48:51], v[178:181], v[108:111]
	v_mfma_f32_16x16x32_bf16 v[104:107], v[60:63], v[178:181], v[104:107]
	v_mfma_f32_16x16x32_bf16 v[92:95], v[48:51], v[212:215], v[92:95]
	v_mfma_f32_16x16x32_bf16 v[88:91], v[60:63], v[212:215], v[88:91]
	v_mfma_f32_16x16x32_bf16 v[140:143], v[52:55], v[148:151], v[140:143]
	v_mfma_f32_16x16x32_bf16 v[136:139], v[68:71], v[148:151], v[136:139]
	v_mfma_f32_16x16x32_bf16 v[124:127], v[52:55], v[174:177], v[124:127]
	v_mfma_f32_16x16x32_bf16 v[120:123], v[68:71], v[174:177], v[120:123]
	v_mfma_f32_16x16x32_bf16 v[108:111], v[52:55], v[208:211], v[108:111]
	v_mfma_f32_16x16x32_bf16 v[104:107], v[68:71], v[208:211], v[104:107]
	v_mfma_f32_16x16x32_bf16 v[92:95], v[52:55], v[216:219], v[92:95]
	v_mfma_f32_16x16x32_bf16 v[88:91], v[68:71], v[216:219], v[88:91]
	s_setprio 0
	s_barrier
	v_add_u32_e32 v182, s80, v198
	s_mov_b32 m0, s0
	ds_read_b128 v[220:223], v182
	ds_read_b128 v[224:227], v182 offset:1024
	ds_read_b128 v[228:231], v182 offset:2048
	ds_read_b128 v[232:235], v182 offset:3072
	v_lshl_add_u64 v[182:183], s[16:17], 0, v[160:161]
	global_load_lds_dwordx4 v[182:183], off
	s_mov_b32 m0, s1
	v_lshl_add_u64 v[236:237], s[16:17], 0, v[158:159]
	global_load_lds_dwordx4 v[236:237], off
	s_barrier
	s_waitcnt lgkmcnt(0)
	s_setprio 1
	v_mfma_f32_16x16x32_bf16 v[132:135], v[220:223], v[144:147], v[132:135]
	v_mfma_f32_16x16x32_bf16 v[128:131], v[228:231], v[144:147], v[128:131]
	v_mfma_f32_16x16x32_bf16 v[116:119], v[220:223], v[170:173], v[116:119]
	v_mfma_f32_16x16x32_bf16 v[112:115], v[228:231], v[170:173], v[112:115]
	v_mfma_f32_16x16x32_bf16 v[100:103], v[220:223], v[178:181], v[100:103]
	v_mfma_f32_16x16x32_bf16 v[96:99], v[228:231], v[178:181], v[96:99]
	v_mfma_f32_16x16x32_bf16 v[84:87], v[220:223], v[212:215], v[84:87]
	v_mfma_f32_16x16x32_bf16 v[80:83], v[228:231], v[212:215], v[80:83]
	v_mfma_f32_16x16x32_bf16 v[132:135], v[224:227], v[148:151], v[132:135]
	v_mfma_f32_16x16x32_bf16 v[128:131], v[232:235], v[148:151], v[128:131]
	v_mfma_f32_16x16x32_bf16 v[116:119], v[224:227], v[174:177], v[116:119]
	v_mfma_f32_16x16x32_bf16 v[112:115], v[232:235], v[174:177], v[112:115]
	v_mfma_f32_16x16x32_bf16 v[100:103], v[224:227], v[208:211], v[100:103]
	v_mfma_f32_16x16x32_bf16 v[96:99], v[232:235], v[208:211], v[96:99]
	v_mfma_f32_16x16x32_bf16 v[84:87], v[224:227], v[216:219], v[84:87]
	v_mfma_f32_16x16x32_bf16 v[80:83], v[232:235], v[216:219], v[80:83]
	s_setprio 0
	s_mov_b32 m0, s76
	v_lshl_add_u64 v[238:239], s[14:15], 0, v[154:155]
	s_barrier
	ds_read_b128 v[144:147], v200 offset:16384
	ds_read_b128 v[148:151], v200 offset:17408
	ds_read_b128 v[170:173], v200 offset:18432
	ds_read_b128 v[174:177], v200 offset:19456
	ds_read_b128 v[178:181], v200 offset:20480
	ds_read_b128 v[208:211], v200 offset:21504
	ds_read_b128 v[212:215], v200 offset:22528
	ds_read_b128 v[216:219], v200 offset:23552
	global_load_lds_dwordx4 v[238:239], off
	s_mov_b32 m0, s22
	v_lshl_add_u64 v[240:241], s[14:15], 0, v[156:157]
	global_load_lds_dwordx4 v[240:241], off
	s_barrier
	s_waitcnt lgkmcnt(0)
	s_setprio 1
	v_mfma_f32_16x16x32_bf16 v[76:79], v[48:51], v[144:147], v[76:79]
	v_mfma_f32_16x16x32_bf16 v[72:75], v[60:63], v[144:147], v[72:75]
	v_mfma_f32_16x16x32_bf16 v[44:47], v[48:51], v[170:173], v[44:47]
	v_mfma_f32_16x16x32_bf16 v[40:43], v[60:63], v[170:173], v[40:43]
	v_mfma_f32_16x16x32_bf16 v[28:31], v[48:51], v[178:181], v[28:31]
	v_mfma_f32_16x16x32_bf16 v[24:27], v[60:63], v[178:181], v[24:27]
	v_mfma_f32_16x16x32_bf16 v[12:15], v[48:51], v[212:215], v[12:15]
	v_mfma_f32_16x16x32_bf16 v[8:11], v[60:63], v[212:215], v[8:11]
	v_mfma_f32_16x16x32_bf16 v[76:79], v[52:55], v[148:151], v[76:79]
	v_mfma_f32_16x16x32_bf16 v[72:75], v[68:71], v[148:151], v[72:75]
	v_mfma_f32_16x16x32_bf16 v[44:47], v[52:55], v[174:177], v[44:47]
	v_mfma_f32_16x16x32_bf16 v[40:43], v[68:71], v[174:177], v[40:43]
	v_mfma_f32_16x16x32_bf16 v[28:31], v[52:55], v[208:211], v[28:31]
	v_mfma_f32_16x16x32_bf16 v[24:27], v[68:71], v[208:211], v[24:27]
	v_mfma_f32_16x16x32_bf16 v[12:15], v[52:55], v[216:219], v[12:15]
	v_mfma_f32_16x16x32_bf16 v[8:11], v[68:71], v[216:219], v[8:11]
	s_setprio 0
	s_barrier
; #define PG8_STAGE(bufoff, gbase, voff) do { _Pragma("unroll") for (int _i = 0; _i < 2; ++_i) \
;         __builtin_amdgcn_global_load_lds((const unsigned*)((const char*)(gbase) + (voff)[_i]), (LAS unsigned*)(lds + (bufoff) + ldsw + _i * 8192), 16, 0, 0); } while (0)
; #define PG8_LDA(dst, b, h) do { _Pragma("unroll") for (int m = 0; m < 4; ++m) _Pragma("unroll") for (int k = 0; k < 2; ++k) dst[m][k] = *(const LAS bf16x8*)(lds + PG8_SA(b, h) + aoff + m * 2048 + k * 1024); } while (0)
; #define PG8_LDB(dst, b, h) do { _Pragma("unroll") for (int n = 0; n < 2; ++n) _Pragma("unroll") for (int k = 0; k < 2; ++k) dst[n][k] = *(const LAS bf16x8*)(lds + PG8_SB(b, h) + boff + n * 2048 + k * 1024); } while (0)
; #define PG8_MMA(ai, bj, At, Bt) do { __builtin_amdgcn_s_setprio(1); _Pragma("unroll") for (int m = 0; m < 4; ++m) _Pragma("unroll") for (int n = 0; n < 2; ++n) _Pragma("unroll") for (int k = 0; k < 2; ++k) \
;         acc[ai][bj][m][n] = __builtin_amdgcn_mfma_f32_16x16x32_bf16(Bt[n][k], At[m][k], acc[ai][bj][m][n], 0, 0, 0); __builtin_amdgcn_s_setprio(0); } while (0)
; #define PG8_WAIT_V(n) asm volatile("s_waitcnt vmcnt(" #n ")" ::: "memory")
; #define PG8_WAIT_L(n) asm volatile("s_waitcnt lgkmcnt(" #n ")" ::: "memory")
; #define PG8_BAR __builtin_amdgcn_s_barrier()
; #define PG8_SCHED __builtin_amdgcn_sched_barrier(0)
; template <class Epi>
; __device__ __forceinline__ void gemm_phase(const int TID, const int BID, LAS unsigned char* lds, const Gemm g, const StaticOrder& S, const Epi& E) {
;     ...
;             PG8_STAGE(PG8_SB(0, 1), b2 + hstepB, voffB);
;             PG8_WAIT_V(6); PG8_BAR; PG8_MMA(1, 1, At, B1); PG8_BAR;
;             PG8_LDB(B0, 1, 0); PG8_SCHED; PG8_LDA(At, 1, 0); PG8_STAGE(PG8_SA(0, 1), a2 + hstepA, voffA);
;             PG8_WAIT_L(8); PG8_BAR; PG8_WAIT_L(0); PG8_MMA(0, 0, At, B0); PG8_BAR; PG8_SCHED;
;             PG8_LDB(B1, 1, 1); PG8_STAGE(PG8_SB(1, 0), b3, voffB);
;             PG8_BAR; PG8_WAIT_L(0); PG8_MMA(0, 1, At, B1); PG8_BAR;
	s_add_u32 s16, s16, s58
	s_addc_u32 s17, s17, 0
	s_mov_b32 m0, s71
	v_lshl_add_u64 v[242:243], s[16:17], 0, v[160:161]
	global_load_lds_dwordx4 v[242:243], off
	s_mov_b32 m0, s23
	v_lshl_add_u64 v[244:245], s[16:17], 0, v[158:159]
	global_load_lds_dwordx4 v[244:245], off
	s_waitcnt vmcnt(6)
	s_barrier
	s_setprio 1
	v_mfma_f32_16x16x32_bf16 v[36:39], v[220:223], v[170:173], v[36:39]
	v_mfma_f32_16x16x32_bf16 v[32:35], v[228:231], v[170:173], v[32:35]
	v_mfma_f32_16x16x32_bf16 v[20:23], v[220:223], v[178:181], v[20:23]
	v_mfma_f32_16x16x32_bf16 v[16:19], v[228:231], v[178:181], v[16:19]
	v_mfma_f32_16x16x32_bf16 v[4:7], v[220:223], v[212:215], v[4:7]
	v_mfma_f32_16x16x32_bf16 v[0:3], v[228:231], v[212:215], v[0:3]
	v_mfma_f32_16x16x32_bf16 v[48:51], v[220:223], v[144:147], v[64:67]
	v_mfma_f32_16x16x32_bf16 v[52:55], v[228:231], v[144:147], v[56:59]
	v_mfma_f32_16x16x32_bf16 v[36:39], v[224:227], v[174:177], v[36:39]
	v_mfma_f32_16x16x32_bf16 v[32:35], v[232:235], v[174:177], v[32:35]
	v_mfma_f32_16x16x32_bf16 v[20:23], v[224:227], v[208:211], v[20:23]
	v_mfma_f32_16x16x32_bf16 v[16:19], v[232:235], v[208:211], v[16:19]
	v_mfma_f32_16x16x32_bf16 v[4:7], v[224:227], v[216:219], v[4:7]
	v_mfma_f32_16x16x32_bf16 v[0:3], v[232:235], v[216:219], v[0:3]
	v_mfma_f32_16x16x32_bf16 v[48:51], v[224:227], v[148:151], v[48:51]
	v_mfma_f32_16x16x32_bf16 v[52:55], v[232:235], v[148:151], v[52:55]
	s_setprio 0
	v_add_u32_e32 v68, s81, v198
	s_barrier
	ds_read_b128 v[56:59], v68
	ds_read_b128 v[60:63], v68 offset:1024
	ds_read_b128 v[64:67], v68 offset:2048
	ds_read_b128 v[68:71], v68 offset:3072
	s_add_u32 s14, s14, s36
	s_addc_u32 s15, s15, 0
	s_mov_b32 m0, s96
	v_lshl_add_u64 v[220:221], s[14:15], 0, v[154:155]
	ds_read_b128 v[144:147], v200 offset:32768
	ds_read_b128 v[148:151], v200 offset:33792
	ds_read_b128 v[170:173], v200 offset:34816
	ds_read_b128 v[174:177], v200 offset:35840
	ds_read_b128 v[178:181], v200 offset:36864
	ds_read_b128 v[208:211], v200 offset:37888
	ds_read_b128 v[212:215], v200 offset:38912
	ds_read_b128 v[216:219], v200 offset:39936
	global_load_lds_dwordx4 v[220:221], off
	s_mov_b32 m0, s97
	v_lshl_add_u64 v[220:221], s[14:15], 0, v[156:157]
	global_load_lds_dwordx4 v[220:221], off
	s_waitcnt lgkmcnt(8)
	s_barrier
	s_waitcnt lgkmcnt(0)
	s_setprio 1
	v_mfma_f32_16x16x32_bf16 v[140:143], v[56:59], v[144:147], v[140:143]
	v_mfma_f32_16x16x32_bf16 v[136:139], v[64:67], v[144:147], v[136:139]
	v_mfma_f32_16x16x32_bf16 v[124:127], v[56:59], v[170:173], v[124:127]
	v_mfma_f32_16x16x32_bf16 v[120:123], v[64:67], v[170:173], v[120:123]
	v_mfma_f32_16x16x32_bf16 v[108:111], v[56:59], v[178:181], v[108:111]
	v_mfma_f32_16x16x32_bf16 v[104:107], v[64:67], v[178:181], v[104:107]
	v_mfma_f32_16x16x32_bf16 v[92:95], v[56:59], v[212:215], v[92:95]
	v_mfma_f32_16x16x32_bf16 v[88:91], v[64:67], v[212:215], v[88:91]
	v_mfma_f32_16x16x32_bf16 v[140:143], v[60:63], v[148:151], v[140:143]
	v_mfma_f32_16x16x32_bf16 v[136:139], v[68:71], v[148:151], v[136:139]
	v_mfma_f32_16x16x32_bf16 v[124:127], v[60:63], v[174:177], v[124:127]
	v_mfma_f32_16x16x32_bf16 v[120:123], v[68:71], v[174:177], v[120:123]
	v_mfma_f32_16x16x32_bf16 v[108:111], v[60:63], v[208:211], v[108:111]
	v_mfma_f32_16x16x32_bf16 v[104:107], v[68:71], v[208:211], v[104:107]
	v_mfma_f32_16x16x32_bf16 v[92:95], v[60:63], v[216:219], v[92:95]
	v_mfma_f32_16x16x32_bf16 v[88:91], v[68:71], v[216:219], v[88:91]
	s_setprio 0
	s_barrier
	s_mov_b32 m0, s66
	v_add_u32_e32 v201, s87, v198
	v_lshl_add_u64 v[182:183], v[182:183], 0, s[90:91]
	ds_read_b128 v[220:223], v201
	ds_read_b128 v[224:227], v201 offset:1024
	ds_read_b128 v[228:231], v201 offset:2048
	ds_read_b128 v[232:235], v201 offset:3072
	global_load_lds_dwordx4 v[182:183], off
	s_mov_b32 m0, s92
	v_lshl_add_u64 v[182:183], v[236:237], 0, s[90:91]
	global_load_lds_dwordx4 v[182:183], off
	s_barrier
; #define PG8_STAGE(bufoff, gbase, voff) do { _Pragma("unroll") for (int _i = 0; _i < 2; ++_i) \
;         __builtin_amdgcn_global_load_lds((const unsigned*)((const char*)(gbase) + (voff)[_i]), (LAS unsigned*)(lds + (bufoff) + ldsw + _i * 8192), 16, 0, 0); } while (0)
; #define PG8_LDA(dst, b, h) do { _Pragma("unroll") for (int m = 0; m < 4; ++m) _Pragma("unroll") for (int k = 0; k < 2; ++k) dst[m][k] = *(const LAS bf16x8*)(lds + PG8_SA(b, h) + aoff + m * 2048 + k * 1024); } while (0)
; #define PG8_MMA(ai, bj, At, Bt) do { __builtin_amdgcn_s_setprio(1); _Pragma("unroll") for (int m = 0; m < 4; ++m) _Pragma("unroll") for (int n = 0; n < 2; ++n) _Pragma("unroll") for (int k = 0; k < 2; ++k) \
;         acc[ai][bj][m][n] = __builtin_amdgcn_mfma_f32_16x16x32_bf16(Bt[n][k], At[m][k], acc[ai][bj][m][n], 0, 0, 0); __builtin_amdgcn_s_setprio(0); } while (0)
; #define PG8_WAIT_V(n) asm volatile("s_waitcnt vmcnt(" #n ")" ::: "memory")
; #define PG8_WAIT_L(n) asm volatile("s_waitcnt lgkmcnt(" #n ")" ::: "memory")
; #define PG8_BAR __builtin_amdgcn_s_barrier()
; #define PG8_SCHED __builtin_amdgcn_sched_barrier(0)
; template <class Epi>
; __device__ __forceinline__ void gemm_phase(const int TID, const int BID, LAS unsigned char* lds, const Gemm g, const StaticOrder& S, const Epi& E) {
;     ...
;             PG8_BAR; PG8_WAIT_L(0); PG8_MMA(0, 1, At, B1); PG8_BAR;
;             PG8_LDA(At, 1, 1); PG8_STAGE(PG8_SA(1, 0), a3, voffA);
;             PG8_BAR; PG8_WAIT_L(0); PG8_MMA(1, 0, At, B0); PG8_BAR; PG8_SCHED;
;             PG8_STAGE(PG8_SB(1, 1), b3 + hstepB, voffB);
;             PG8_WAIT_V(6); PG8_BAR; PG8_MMA(1, 1, At, B1); PG8_BAR;
;     __device__ __forceinline__ void operator()(const f32x4 (&acc)[2][2][4][2], const Unit& u, int wr, int wc, int fr, int fq) const {
;         const int row0 = u.pm * BM + wr * 64 + fr, col0 = col_off + u.pn * BM + wc * 32 + 8 * fq;
;         f32x4 cs[2][2];
; #pragma unroll
;         for (int bj = 0; bj < 2; ++bj)
; #pragma unroll
;             for (int n = 0; n < 2; ++n) cs[bj][n] = colscale ? *(const f32x4*)(colscale + col0 + bj * HALF + 4 * n) : (f32x4){1.f, 1.f, 1.f, 1.f};
	s_waitcnt lgkmcnt(0)
	s_setprio 1
	v_mfma_f32_16x16x32_bf16 v[132:135], v[220:223], v[144:147], v[132:135]
	v_mfma_f32_16x16x32_bf16 v[128:131], v[228:231], v[144:147], v[128:131]
	v_mfma_f32_16x16x32_bf16 v[116:119], v[220:223], v[170:173], v[116:119]
	v_mfma_f32_16x16x32_bf16 v[112:115], v[228:231], v[170:173], v[112:115]
	v_mfma_f32_16x16x32_bf16 v[100:103], v[220:223], v[178:181], v[100:103]
	v_mfma_f32_16x16x32_bf16 v[96:99], v[228:231], v[178:181], v[96:99]
	v_mfma_f32_16x16x32_bf16 v[84:87], v[220:223], v[212:215], v[84:87]
	v_mfma_f32_16x16x32_bf16 v[80:83], v[228:231], v[212:215], v[80:83]
	v_mfma_f32_16x16x32_bf16 v[132:135], v[224:227], v[148:151], v[132:135]
	v_mfma_f32_16x16x32_bf16 v[128:131], v[232:235], v[148:151], v[128:131]
	v_mfma_f32_16x16x32_bf16 v[116:119], v[224:227], v[174:177], v[116:119]
	v_mfma_f32_16x16x32_bf16 v[112:115], v[232:235], v[174:177], v[112:115]
	v_mfma_f32_16x16x32_bf16 v[100:103], v[224:227], v[208:211], v[100:103]
	v_mfma_f32_16x16x32_bf16 v[96:99], v[232:235], v[208:211], v[96:99]
	v_mfma_f32_16x16x32_bf16 v[84:87], v[224:227], v[216:219], v[84:87]
	v_mfma_f32_16x16x32_bf16 v[80:83], v[232:235], v[216:219], v[80:83]
	s_setprio 0
	s_mov_b32 m0, s4
	v_lshl_add_u64 v[182:183], v[238:239], 0, s[90:91]
	s_barrier
	ds_read_b128 v[144:147], v200 offset:49152
	ds_read_b128 v[148:151], v200 offset:50176
	ds_read_b128 v[170:173], v200 offset:51200
	ds_read_b128 v[174:177], v200 offset:52224
	ds_read_b128 v[178:181], v200 offset:53248
	ds_read_b128 v[208:211], v200 offset:54272
	ds_read_b128 v[212:215], v200 offset:55296
	ds_read_b128 v[216:219], v200 offset:56320
	global_load_lds_dwordx4 v[182:183], off
	s_mov_b32 m0, s64
	v_lshl_add_u64 v[182:183], v[240:241], 0, s[90:91]
	global_load_lds_dwordx4 v[182:183], off
	s_barrier
	s_waitcnt lgkmcnt(0)
	s_setprio 1
	v_mfma_f32_16x16x32_bf16 v[76:79], v[56:59], v[144:147], v[76:79]
	v_mfma_f32_16x16x32_bf16 v[72:75], v[64:67], v[144:147], v[72:75]
	v_mfma_f32_16x16x32_bf16 v[44:47], v[56:59], v[170:173], v[44:47]
	v_mfma_f32_16x16x32_bf16 v[40:43], v[64:67], v[170:173], v[40:43]
	v_mfma_f32_16x16x32_bf16 v[28:31], v[56:59], v[178:181], v[28:31]
	v_mfma_f32_16x16x32_bf16 v[24:27], v[64:67], v[178:181], v[24:27]
	v_mfma_f32_16x16x32_bf16 v[12:15], v[56:59], v[212:215], v[12:15]
	v_mfma_f32_16x16x32_bf16 v[8:11], v[64:67], v[212:215], v[8:11]
	v_mfma_f32_16x16x32_bf16 v[76:79], v[60:63], v[148:151], v[76:79]
	v_mfma_f32_16x16x32_bf16 v[72:75], v[68:71], v[148:151], v[72:75]
	v_mfma_f32_16x16x32_bf16 v[44:47], v[60:63], v[174:177], v[44:47]
	v_mfma_f32_16x16x32_bf16 v[40:43], v[68:71], v[174:177], v[40:43]
	v_mfma_f32_16x16x32_bf16 v[28:31], v[60:63], v[208:211], v[28:31]
	v_mfma_f32_16x16x32_bf16 v[24:27], v[68:71], v[208:211], v[24:27]
	v_mfma_f32_16x16x32_bf16 v[12:15], v[60:63], v[216:219], v[12:15]
	v_mfma_f32_16x16x32_bf16 v[8:11], v[68:71], v[216:219], v[8:11]
	s_setprio 0
	s_barrier
	s_mov_b32 m0, s74
	v_lshl_add_u64 v[56:57], v[242:243], 0, s[90:91]
	global_load_lds_dwordx4 v[56:57], off
	s_mov_b32 m0, s95
	v_lshl_add_u64 v[56:57], v[244:245], 0, s[90:91]
	global_load_lds_dwordx4 v[56:57], off
	s_waitcnt vmcnt(6)
	s_barrier
	s_setprio 1
	v_mfma_f32_16x16x32_bf16 v[48:51], v[220:223], v[144:147], v[48:51]
	v_mfma_f32_16x16x32_bf16 v[64:67], v[224:227], v[148:151], v[48:51]
	v_mfma_f32_16x16x32_bf16 v[48:51], v[228:231], v[144:147], v[52:55]
	v_mfma_f32_16x16x32_bf16 v[36:39], v[220:223], v[170:173], v[36:39]
	v_mfma_f32_16x16x32_bf16 v[32:35], v[228:231], v[170:173], v[32:35]
	v_mfma_f32_16x16x32_bf16 v[20:23], v[220:223], v[178:181], v[20:23]
	v_mfma_f32_16x16x32_bf16 v[16:19], v[228:231], v[178:181], v[16:19]
	v_mfma_f32_16x16x32_bf16 v[4:7], v[220:223], v[212:215], v[4:7]
	v_mfma_f32_16x16x32_bf16 v[0:3], v[228:231], v[212:215], v[0:3]
	v_mfma_f32_16x16x32_bf16 v[56:59], v[232:235], v[148:151], v[48:51]
	v_mfma_f32_16x16x32_bf16 v[36:39], v[224:227], v[174:177], v[36:39]
	v_mfma_f32_16x16x32_bf16 v[32:35], v[232:235], v[174:177], v[32:35]
	v_mfma_f32_16x16x32_bf16 v[20:23], v[224:227], v[208:211], v[20:23]
	v_mfma_f32_16x16x32_bf16 v[16:19], v[232:235], v[208:211], v[16:19]
	v_mfma_f32_16x16x32_bf16 v[4:7], v[224:227], v[216:219], v[4:7]
	v_mfma_f32_16x16x32_bf16 v[0:3], v[232:235], v[216:219], v[0:3]
	s_setprio 0
	s_add_u32 s12, s12, 0x100
	s_addc_u32 s13, s13, 0
	s_add_u32 s18, s18, 0x100
	s_addc_u32 s19, s19, 0
	s_cmp_ge_u32 vcc_lo, s57
	s_mov_b32 s14, vcc_lo
	s_cbranch_scc0 .Lrot_955
	s_barrier
	v_lshl_add_u32 v174, s55, 8, v199
	v_ashrrev_i32_e32 v175, 31, v174
	v_mov_b32_e32 v60, 1.0
	v_cndmask_b32_e64 v48, 0, 1, s[40:41]
	v_lshl_add_u64 v[144:145], v[174:175], 2, s[26:27]
	v_cmp_ne_u32_e64 s[12:13], 1, v48
	s_andn2_b64 vcc, exec, s[40:41]
	v_mov_b32_e32 v68, 1.0
	v_mov_b32_e32 v69, v60
	v_mov_b32_e32 v70, 1.0
	v_mov_b32_e32 v71, 1.0
	s_cbranch_vccnz .LBB0_958
	global_load_dwordx4 v[68:71], v[144:145], off
